# P3: f32 residual x streamed into accumulators inside fully unrolled K-loop (no exposed x loads in epilogue)
# speedup vs baseline: 1.0109x; 1.0004x over previous
;     __device__ __forceinline__ const char* aptr(const Unit& u) const { return (u.kind == 1 ? A1 : A0) + (size_t)u.pm * tstep; }
;     __device__ __forceinline__ const char* bptr(const Unit& u) const { return (u.kind == 1 ? B1 : B0) + (size_t)u.pn * tstep; }
; #define PG8_STAGE(bufoff, gbase, voff) do { _Pragma("unroll") for (int _i = 0; _i < 2; ++_i) \
;         __builtin_amdgcn_global_load_lds((const unsigned*)((const char*)(gbase) + (voff)[_i]), (LAS unsigned*)(lds + (bufoff) + ldsw + _i * 8192), 16, 0, 0); } while (0)
; #define PG8_WAIT_V(n) asm volatile("s_waitcnt vmcnt(" #n ")" ::: "memory")
; #define PG8_WAIT_L(n) asm volatile("s_waitcnt lgkmcnt(" #n ")" ::: "memory")
; #define PG8_BAR __builtin_amdgcn_s_barrier()
; template <class Epi, bool ALIGN_EPI, bool SP2>
; __device__ __forceinline__ void gemm_phase(LAS unsigned char* lds, const int K, const Sched& S, const Epi& E) {
;     ...
;         const bool has_next = S.next(ui + 1, nxt);
;         const char* nA = has_next ? S.aptr(nxt) : cA; const char* nB = has_next ? S.bptr(nxt) : cB;
;         for (int t = 0; t < nt; t += 2) {
;             const bool last = (t == nt - 2);
;             const char* a1 = cA + (size_t)(t + 1) * kstep;
;             const char* a2 = last ? nA : cA + (size_t)(t + 2) * kstep; const char* b2 = last ? nB : cB + (size_t)(t + 2) * kstep;
;             const char* a3 = a2 + kstep; const char* b3 = b2 + kstep;
;             if constexpr (SP2) {
;             PG8_LDB(B0, 0, 0); PG8_LDB(B1, 0, 1); PG8_SCHED; PG8_LDA(At, 0, 0); PG8_STAGE(PG8_SA(1, 1), a1 + hstep, voffA);
;             PG8_WAIT_V(8); PG8_WAIT_L(0); PG8_BAR; PG8_MMA(0, 0, At, B0); PG8_MMA(0, 1, At, B1); PG8_BAR; PG8_SCHED;
;     __device__ __forceinline__ void operator()(Acc& acc, const Unit& u, int wr, int wc, int fr, int fq) const {
;     ...
;                     for (int bj = 0; bj < 2; ++bj) { const float* p = basef + (size_t)(row0 + ai * HALF + m * 16) * D + col0 + bj * HALF; rx[m][bj][0] = *(const f32x4*)p; rx[m][bj][1] = *(const f32x4*)(p + 4); }
;                 __builtin_amdgcn_sched_barrier(0);
; #pragma unroll
;                 for (int m = 0; m < 4; ++m) { const int row = row0 + ai * HALF + m * 16; const size_t o = (size_t)row * D + col0; float ss = 0.f;
; #pragma unroll
;                     for (int bj = 0; bj < 2; ++bj) { const f32x4 h0 = rx[m][bj][0] + acc[ai][bj][m][0], h1 = rx[m][bj][1] + acc[ai][bj][m][1];
.LBB0_694:
	s_ashr_i32 s19, s18, 31
	s_lshl_b64 s[22:23], s[18:19], 19
	s_add_u32 s22, s38, s22
	s_addc_u32 s23, s39, s23
	s_and_b64 s[26:27], s[24:25], exec
	s_cselect_b32 s7, s23, s31
	s_cselect_b32 s19, s22, s30
	s_ashr_i32 s21, s20, 31
	s_lshl_b64 s[26:27], s[20:21], 19
	s_add_u32 s26, s40, s26
	s_addc_u32 s27, s41, s27
	s_and_b64 s[36:37], s[24:25], exec
	s_cselect_b32 s21, s27, s35
	s_cselect_b32 s56, s26, s34
	s_add_u32 s30, s30, 0x40080
	s_addc_u32 s31, s31, 0
	s_add_u32 s57, s34, 0x100
	v_mov_b64_e32 v[0:1], 0
	v_mov_b64_e32 v[2:3], 0
	v_mov_b64_e32 v[4:5], 0
	v_mov_b64_e32 v[6:7], 0
	v_mov_b64_e32 v[8:9], 0
	v_mov_b64_e32 v[10:11], 0
	v_mov_b64_e32 v[12:13], 0
	v_mov_b64_e32 v[14:15], 0
	v_mov_b64_e32 v[16:17], 0
	v_mov_b64_e32 v[18:19], 0
	v_mov_b64_e32 v[20:21], 0
	v_mov_b64_e32 v[22:23], 0
	v_mov_b64_e32 v[24:25], 0
	v_mov_b64_e32 v[26:27], 0
	v_mov_b64_e32 v[28:29], 0
	v_mov_b64_e32 v[30:31], 0
	v_mov_b64_e32 v[32:33], 0
	v_mov_b64_e32 v[34:35], 0
	v_mov_b64_e32 v[36:37], 0
	v_mov_b64_e32 v[38:39], 0
	v_mov_b64_e32 v[40:41], 0
	v_mov_b64_e32 v[42:43], 0
	v_mov_b64_e32 v[44:45], 0
	v_mov_b64_e32 v[46:47], 0
	v_mov_b64_e32 v[48:49], 0
	v_mov_b64_e32 v[50:51], 0
	v_mov_b64_e32 v[52:53], 0
	v_mov_b64_e32 v[54:55], 0
	v_mov_b64_e32 v[56:57], 0
	v_mov_b64_e32 v[58:59], 0
	v_mov_b64_e32 v[60:61], 0
	v_mov_b64_e32 v[62:63], 0
	v_mov_b64_e32 v[64:65], 0
	v_mov_b64_e32 v[66:67], 0
	v_mov_b64_e32 v[68:69], 0
	v_mov_b64_e32 v[70:71], 0
	v_mov_b64_e32 v[72:73], 0
	v_mov_b64_e32 v[74:75], 0
	v_mov_b64_e32 v[76:77], 0
	v_mov_b64_e32 v[78:79], 0
	v_mov_b64_e32 v[80:81], 0
	v_mov_b64_e32 v[82:83], 0
	v_mov_b64_e32 v[84:85], 0
	v_mov_b64_e32 v[86:87], 0
	v_mov_b64_e32 v[88:89], 0
	v_mov_b64_e32 v[90:91], 0
	v_mov_b64_e32 v[92:93], 0
	v_mov_b64_e32 v[94:95], 0
	v_mov_b64_e32 v[96:97], 0
	v_mov_b64_e32 v[98:99], 0
	v_mov_b64_e32 v[100:101], 0
	v_mov_b64_e32 v[102:103], 0
	v_mov_b64_e32 v[104:105], 0
	v_mov_b64_e32 v[106:107], 0
	v_mov_b64_e32 v[108:109], 0
	v_mov_b64_e32 v[110:111], 0
	v_mov_b64_e32 v[112:113], 0
	v_mov_b64_e32 v[114:115], 0
	v_mov_b64_e32 v[116:117], 0
	v_mov_b64_e32 v[118:119], 0
	v_mov_b64_e32 v[120:121], 0
	v_mov_b64_e32 v[122:123], 0
	v_mov_b64_e32 v[124:125], 0
	v_mov_b64_e32 v[126:127], 0
	s_addc_u32 s58, s35, 0
	s_mov_b32 s59, -2
	s_waitcnt lgkmcnt(0)
	s_lshl_b32 s70, s28, 20
	s_lshl_b32 s71, s6, 10
	s_add_i32 s70, s70, s71
	s_add_u32 s70, s64, s70
	s_addc_u32 s71, s65, 0
	v_and_b32_e32 v229, 15, v228
	v_lshlrev_b32_e32 v229, 12, v229
	v_bfe_u32 v230, v228, 4, 2
	v_lshl_or_b32 v229, v230, 5, v229
	v_bfe_u32 v230, v228, 6, 2
	v_lshl_or_b32 v229, v230, 7, v229
	v_bfe_u32 v230, v228, 8, 1
	v_lshl_or_b32 v229, v230, 18, v229
.Lp3_kloop:
	ds_read_b128 v[128:131], v203
	ds_read_b128 v[132:135], v203 offset:1024
	ds_read_b128 v[136:139], v203 offset:2048
	ds_read_b128 v[140:143], v203 offset:3072
	ds_read_b128 v[144:147], v204
	ds_read_b128 v[148:151], v204 offset:1024
	ds_read_b128 v[152:155], v204 offset:2048
	ds_read_b128 v[156:159], v204 offset:3072
	s_add_u32 s34, s30, 0xfffc0080
	s_addc_u32 s35, s31, -1
	s_cmp_eq_u32 s59, 12
	s_cselect_b32 s37, s7, s35
	s_cselect_b32 s36, s19, s34
	s_cselect_b32 s35, s21, s58
	s_cselect_b32 s34, s56, s57
	s_mov_b32 m0, s53
	v_lshl_add_u64 v[214:215], s[30:31], 0, v[184:185]
	ds_read_b128 v[160:163], v205
	ds_read_b128 v[164:167], v205 offset:1024
	ds_read_b128 v[168:171], v205 offset:2048
	ds_read_b128 v[172:175], v205 offset:3072
	ds_read_b128 v[188:191], v205 offset:4096
	ds_read_b128 v[192:195], v205 offset:5120
	ds_read_b128 v[196:199], v205 offset:6144
	ds_read_b128 v[210:213], v205 offset:7168
	global_load_lds_dwordx4 v[214:215], off
	v_lshl_add_u64 v[214:215], s[30:31], 0, v[186:187]
	s_mov_b32 m0, s54
	s_nop 0
	global_load_lds_dwordx4 v[214:215], off
	s_waitcnt vmcnt(8)
	s_waitcnt lgkmcnt(0)
	s_mov_b64 s[68:69], s[70:71]
	global_load_dwordx4 v[232:235], v229, s[68:69]
	s_setprio 1
	s_waitcnt lgkmcnt(0)
	v_mfma_f32_16x16x32_bf16 v[124:127], v[128:131], v[160:163], v[124:127]
	v_mfma_f32_16x16x32_bf16 v[120:123], v[136:139], v[160:163], v[120:123]
	v_mfma_f32_16x16x32_bf16 v[108:111], v[128:131], v[168:171], v[108:111]
	v_mfma_f32_16x16x32_bf16 v[104:107], v[136:139], v[168:171], v[104:107]
	s_barrier
	v_mfma_f32_16x16x32_bf16 v[92:95], v[128:131], v[188:191], v[92:95]
	v_mfma_f32_16x16x32_bf16 v[88:91], v[136:139], v[188:191], v[88:91]
	v_mfma_f32_16x16x32_bf16 v[76:79], v[128:131], v[196:199], v[76:79]
	v_mfma_f32_16x16x32_bf16 v[72:75], v[136:139], v[196:199], v[72:75]
	v_mfma_f32_16x16x32_bf16 v[124:127], v[132:135], v[164:167], v[124:127]
	v_mfma_f32_16x16x32_bf16 v[120:123], v[140:143], v[164:167], v[120:123]
	v_mfma_f32_16x16x32_bf16 v[108:111], v[132:135], v[172:175], v[108:111]
	v_mfma_f32_16x16x32_bf16 v[104:107], v[140:143], v[172:175], v[104:107]
	v_mfma_f32_16x16x32_bf16 v[92:95], v[132:135], v[192:195], v[92:95]
	v_mfma_f32_16x16x32_bf16 v[88:91], v[140:143], v[192:195], v[88:91]
	v_mfma_f32_16x16x32_bf16 v[76:79], v[132:135], v[210:213], v[76:79]
	v_mfma_f32_16x16x32_bf16 v[72:75], v[140:143], v[210:213], v[72:75]
	s_setprio 0
	s_setprio 1
	v_mfma_f32_16x16x32_bf16 v[116:119], v[144:147], v[160:163], v[116:119]
	v_mfma_f32_16x16x32_bf16 v[112:115], v[152:155], v[160:163], v[112:115]
	v_mfma_f32_16x16x32_bf16 v[100:103], v[144:147], v[168:171], v[100:103]
	v_mfma_f32_16x16x32_bf16 v[96:99], v[152:155], v[168:171], v[96:99]
	v_mfma_f32_16x16x32_bf16 v[84:87], v[144:147], v[188:191], v[84:87]
	v_mfma_f32_16x16x32_bf16 v[80:83], v[152:155], v[188:191], v[80:83]
	v_mfma_f32_16x16x32_bf16 v[68:71], v[144:147], v[196:199], v[68:71]
	v_mfma_f32_16x16x32_bf16 v[64:67], v[152:155], v[196:199], v[64:67]
	v_mfma_f32_16x16x32_bf16 v[116:119], v[148:151], v[164:167], v[116:119]
	v_mfma_f32_16x16x32_bf16 v[112:115], v[156:159], v[164:167], v[112:115]
	v_mfma_f32_16x16x32_bf16 v[100:103], v[148:151], v[172:175], v[100:103]
	v_mfma_f32_16x16x32_bf16 v[96:99], v[156:159], v[172:175], v[96:99]
	v_mfma_f32_16x16x32_bf16 v[84:87], v[148:151], v[192:195], v[84:87]
	v_mfma_f32_16x16x32_bf16 v[80:83], v[156:159], v[192:195], v[80:83]
	v_mfma_f32_16x16x32_bf16 v[68:71], v[148:151], v[210:213], v[68:71]
	v_mfma_f32_16x16x32_bf16 v[64:67], v[156:159], v[210:213], v[64:67]
	s_setprio 0
	s_barrier
; #define PG8_STAGE(bufoff, gbase, voff) do { _Pragma("unroll") for (int _i = 0; _i < 2; ++_i) \
;         __builtin_amdgcn_global_load_lds((const unsigned*)((const char*)(gbase) + (voff)[_i]), (LAS unsigned*)(lds + (bufoff) + ldsw + _i * 8192), 16, 0, 0); } while (0)
; #define PG8_LDA(dst, b, h) do { _Pragma("unroll") for (int m = 0; m < 4; ++m) _Pragma("unroll") for (int k = 0; k < 2; ++k) dst[m][k] = *(const LAS bf16x8*)(lds + PG8_SA(b, h) + aoff + m * 2048 + k * 1024); } while (0)
; #define PG8_LDB(dst, b, h) do { _Pragma("unroll") for (int n = 0; n < 2; ++n) _Pragma("unroll") for (int k = 0; k < 2; ++k) dst[n][k] = *(const LAS bf16x8*)(lds + PG8_SB(b, h) + boff + n * 2048 + k * 1024); } while (0)
; #define PG8_WAIT_V(n) asm volatile("s_waitcnt vmcnt(" #n ")" ::: "memory")
; #define PG8_WAIT_L(n) asm volatile("s_waitcnt lgkmcnt(" #n ")" ::: "memory")
; #define PG8_BAR __builtin_amdgcn_s_barrier()
; #define PG8_SCHED __builtin_amdgcn_sched_barrier(0)
; template <class Epi, bool ALIGN_EPI, bool SP2>
; __device__ __forceinline__ void gemm_phase(LAS unsigned char* lds, const int K, const Sched& S, const Epi& E) {
;     ...
;             PG8_LDA(At, 0, 1); PG8_STAGE(PG8_SB(0, 0), b2, voffB); PG8_STAGE(PG8_SB(0, 1), b2 + hstep, voffB); PG8_STAGE(PG8_SA(0, 0), a2, voffA);
;             PG8_WAIT_V(8); PG8_WAIT_L(0); PG8_BAR; PG8_MMA(1, 0, At, B0); PG8_MMA(1, 1, At, B1); PG8_BAR; PG8_SCHED;
;             PG8_LDB(B0, 1, 0); PG8_LDB(B1, 1, 1); PG8_SCHED; PG8_LDA(At, 1, 0); PG8_STAGE(PG8_SA(0, 1), a2 + hstep, voffA);
;             PG8_WAIT_V(8); PG8_WAIT_L(0); PG8_BAR; PG8_MMA(0, 0, At, B0); PG8_MMA(0, 1, At, B1); PG8_BAR; PG8_SCHED;
;     __device__ __forceinline__ void operator()(Acc& acc, const Unit& u, int wr, int wc, int fr, int fq) const {
;     ...
;                     for (int bj = 0; bj < 2; ++bj) { const float* p = basef + (size_t)(row0 + ai * HALF + m * 16) * D + col0 + bj * HALF; rx[m][bj][0] = *(const f32x4*)p; rx[m][bj][1] = *(const f32x4*)(p + 4); }
;                 __builtin_amdgcn_sched_barrier(0);
; #pragma unroll
;                 for (int m = 0; m < 4; ++m) { const int row = row0 + ai * HALF + m * 16; const size_t o = (size_t)row * D + col0; float ss = 0.f;
; #pragma unroll
;                     for (int bj = 0; bj < 2; ++bj) { const f32x4 h0 = rx[m][bj][0] + acc[ai][bj][m][0], h1 = rx[m][bj][1] + acc[ai][bj][m][1];
	s_mov_b32 m0, s55
	v_lshl_add_u64 v[214:215], s[34:35], 0, v[178:179]
	ds_read_b128 v[160:163], v205 offset:16384
	ds_read_b128 v[164:167], v205 offset:17408
	ds_read_b128 v[168:171], v205 offset:18432
	ds_read_b128 v[172:175], v205 offset:19456
	ds_read_b128 v[188:191], v205 offset:20480
	ds_read_b128 v[192:195], v205 offset:21504
	ds_read_b128 v[196:199], v205 offset:22528
	ds_read_b128 v[210:213], v205 offset:23552
	global_load_lds_dwordx4 v[214:215], off
	s_add_i32 m0, s55, 0x2000
	s_add_u32 s60, s34, 0x40000
	v_lshl_add_u64 v[216:217], s[34:35], 0, v[182:183]
	s_addc_u32 s61, s35, 0
	s_add_i32 s62, s51, s42
	global_load_lds_dwordx4 v[216:217], off
	v_lshl_add_u64 v[218:219], s[60:61], 0, v[178:179]
	s_mov_b32 m0, s62
	v_lshl_add_u64 v[220:221], s[36:37], 0, v[180:181]
	global_load_lds_dwordx4 v[218:219], off
	v_lshl_add_u64 v[218:219], s[60:61], 0, v[182:183]
	s_add_i32 m0, s62, 0x2000
	s_nop 0
	global_load_lds_dwordx4 v[218:219], off
	v_lshl_add_u64 v[218:219], s[36:37], 0, v[176:177]
	s_mov_b32 m0, s29
	s_nop 0
	global_load_lds_dwordx4 v[218:219], off
	s_mov_b32 m0, s43
	s_nop 0
	global_load_lds_dwordx4 v[220:221], off
	s_waitcnt vmcnt(9)
	s_waitcnt lgkmcnt(0)
	global_load_dwordx4 v[236:239], v229, s[68:69] offset:16
	s_setprio 1
	s_waitcnt lgkmcnt(0)
	v_mfma_f32_16x16x32_bf16 v[60:63], v[128:131], v[160:163], v[60:63]
	v_mfma_f32_16x16x32_bf16 v[56:59], v[136:139], v[160:163], v[56:59]
	v_mfma_f32_16x16x32_bf16 v[44:47], v[128:131], v[168:171], v[44:47]
	v_mfma_f32_16x16x32_bf16 v[40:43], v[136:139], v[168:171], v[40:43]
	s_barrier
	v_mfma_f32_16x16x32_bf16 v[28:31], v[128:131], v[188:191], v[28:31]
	v_mfma_f32_16x16x32_bf16 v[24:27], v[136:139], v[188:191], v[24:27]
	v_mfma_f32_16x16x32_bf16 v[12:15], v[128:131], v[196:199], v[12:15]
	v_mfma_f32_16x16x32_bf16 v[8:11], v[136:139], v[196:199], v[8:11]
	v_mfma_f32_16x16x32_bf16 v[60:63], v[132:135], v[164:167], v[60:63]
	v_mfma_f32_16x16x32_bf16 v[56:59], v[140:143], v[164:167], v[56:59]
	v_mfma_f32_16x16x32_bf16 v[44:47], v[132:135], v[172:175], v[44:47]
	v_mfma_f32_16x16x32_bf16 v[40:43], v[140:143], v[172:175], v[40:43]
	v_mfma_f32_16x16x32_bf16 v[28:31], v[132:135], v[192:195], v[28:31]
	v_mfma_f32_16x16x32_bf16 v[24:27], v[140:143], v[192:195], v[24:27]
	v_mfma_f32_16x16x32_bf16 v[12:15], v[132:135], v[210:213], v[12:15]
	v_mfma_f32_16x16x32_bf16 v[8:11], v[140:143], v[210:213], v[8:11]
	s_setprio 0
	s_setprio 1
	v_mfma_f32_16x16x32_bf16 v[52:55], v[144:147], v[160:163], v[52:55]
	v_mfma_f32_16x16x32_bf16 v[48:51], v[152:155], v[160:163], v[48:51]
	v_mfma_f32_16x16x32_bf16 v[36:39], v[144:147], v[168:171], v[36:39]
	v_mfma_f32_16x16x32_bf16 v[32:35], v[152:155], v[168:171], v[32:35]
	v_mfma_f32_16x16x32_bf16 v[20:23], v[144:147], v[188:191], v[20:23]
	v_mfma_f32_16x16x32_bf16 v[16:19], v[152:155], v[188:191], v[16:19]
	v_mfma_f32_16x16x32_bf16 v[4:7], v[144:147], v[196:199], v[4:7]
	v_mfma_f32_16x16x32_bf16 v[0:3], v[152:155], v[196:199], v[0:3]
	v_mfma_f32_16x16x32_bf16 v[52:55], v[148:151], v[164:167], v[52:55]
	v_mfma_f32_16x16x32_bf16 v[48:51], v[156:159], v[164:167], v[48:51]
	v_mfma_f32_16x16x32_bf16 v[36:39], v[148:151], v[172:175], v[36:39]
	v_mfma_f32_16x16x32_bf16 v[32:35], v[156:159], v[172:175], v[32:35]
	v_mfma_f32_16x16x32_bf16 v[20:23], v[148:151], v[192:195], v[20:23]
	v_mfma_f32_16x16x32_bf16 v[16:19], v[156:159], v[192:195], v[16:19]
	v_mfma_f32_16x16x32_bf16 v[4:7], v[148:151], v[210:213], v[4:7]
	v_mfma_f32_16x16x32_bf16 v[0:3], v[156:159], v[210:213], v[0:3]
	s_setprio 0
	s_barrier
	s_add_i32 s60, 0, 0x18000
	s_add_i32 s61, 0, 0x1c000
	v_add_u32_e32 v140, s60, v202
	v_add_u32_e32 v156, s61, v202
	ds_read_b128 v[128:131], v140
	ds_read_b128 v[132:135], v140 offset:1024
	ds_read_b128 v[136:139], v140 offset:2048
	ds_read_b128 v[140:143], v140 offset:3072
	ds_read_b128 v[144:147], v156
	ds_read_b128 v[148:151], v156 offset:1024
	ds_read_b128 v[152:155], v156 offset:2048
	ds_read_b128 v[156:159], v156 offset:3072
	s_add_u32 s36, s36, 0x40000
	s_addc_u32 s37, s37, 0
	s_mov_b32 m0, s44
	v_lshl_add_u64 v[222:223], s[36:37], 0, v[176:177]
	ds_read_b128 v[160:163], v205 offset:32768
	ds_read_b128 v[164:167], v205 offset:33792
	ds_read_b128 v[168:171], v205 offset:34816
	ds_read_b128 v[172:175], v205 offset:35840
	ds_read_b128 v[188:191], v205 offset:36864
	ds_read_b128 v[192:195], v205 offset:37888
	ds_read_b128 v[196:199], v205 offset:38912
	ds_read_b128 v[210:213], v205 offset:39936
	global_load_lds_dwordx4 v[222:223], off
	v_lshl_add_u64 v[222:223], s[36:37], 0, v[180:181]
	s_mov_b32 m0, s45
	s_nop 0
	global_load_lds_dwordx4 v[222:223], off
	s_waitcnt vmcnt(10)
	s_waitcnt lgkmcnt(0)
	global_load_dwordx4 v[240:243], v229, s[68:69] offset:512
	s_setprio 1
	s_waitcnt lgkmcnt(0)
	v_mfma_f32_16x16x32_bf16 v[124:127], v[128:131], v[160:163], v[124:127]
	v_mfma_f32_16x16x32_bf16 v[120:123], v[136:139], v[160:163], v[120:123]
	v_mfma_f32_16x16x32_bf16 v[108:111], v[128:131], v[168:171], v[108:111]
	v_mfma_f32_16x16x32_bf16 v[104:107], v[136:139], v[168:171], v[104:107]
	s_barrier
; #define PG8_STAGE(bufoff, gbase, voff) do { _Pragma("unroll") for (int _i = 0; _i < 2; ++_i) \
;         __builtin_amdgcn_global_load_lds((const unsigned*)((const char*)(gbase) + (voff)[_i]), (LAS unsigned*)(lds + (bufoff) + ldsw + _i * 8192), 16, 0, 0); } while (0)
; #define PG8_LDA(dst, b, h) do { _Pragma("unroll") for (int m = 0; m < 4; ++m) _Pragma("unroll") for (int k = 0; k < 2; ++k) dst[m][k] = *(const LAS bf16x8*)(lds + PG8_SA(b, h) + aoff + m * 2048 + k * 1024); } while (0)
; #define PG8_MMA(ai, bj, At, Bt) do { __builtin_amdgcn_s_setprio(1); _Pragma("unroll") for (int m = 0; m < 4; ++m) _Pragma("unroll") for (int n = 0; n < 2; ++n) _Pragma("unroll") for (int k = 0; k < 2; ++k) \
;         acc[ai][bj][m][n] = __builtin_amdgcn_mfma_f32_16x16x32_bf16(Bt[n][k], At[m][k], acc[ai][bj][m][n], 0, 0, 0); __builtin_amdgcn_s_setprio(0); } while (0)
; #define PG8_WAIT_V(n) asm volatile("s_waitcnt vmcnt(" #n ")" ::: "memory")
; #define PG8_WAIT_L(n) asm volatile("s_waitcnt lgkmcnt(" #n ")" ::: "memory")
; #define PG8_BAR __builtin_amdgcn_s_barrier()
; #define PG8_SCHED __builtin_amdgcn_sched_barrier(0)
; template <class Epi, bool ALIGN_EPI, bool SP2>
; __device__ __forceinline__ void gemm_phase(LAS unsigned char* lds, const int K, const Sched& S, const Epi& E) {
;     ...
;             PG8_WAIT_V(8); PG8_WAIT_L(0); PG8_BAR; PG8_MMA(0, 0, At, B0); PG8_MMA(0, 1, At, B1); PG8_BAR; PG8_SCHED;
;             PG8_LDA(At, 1, 1); PG8_STAGE(PG8_SB(1, 0), b3, voffB); PG8_STAGE(PG8_SB(1, 1), b3 + hstep, voffB); PG8_STAGE(PG8_SA(1, 0), a3, voffA);
;             PG8_WAIT_V(8); PG8_WAIT_L(0); PG8_BAR; PG8_MMA(1, 0, At, B0); PG8_MMA(1, 1, At, B1); PG8_BAR; PG8_SCHED;
;     __device__ __forceinline__ void operator()(Acc& acc, const Unit& u, int wr, int wc, int fr, int fq) const {
;     ...
;                     for (int bj = 0; bj < 2; ++bj) { const float* p = basef + (size_t)(row0 + ai * HALF + m * 16) * D + col0 + bj * HALF; rx[m][bj][0] = *(const f32x4*)p; rx[m][bj][1] = *(const f32x4*)(p + 4); }
;                 __builtin_amdgcn_sched_barrier(0);
; #pragma unroll
;                 for (int m = 0; m < 4; ++m) { const int row = row0 + ai * HALF + m * 16; const size_t o = (size_t)row * D + col0; float ss = 0.f;
; #pragma unroll
;                     for (int bj = 0; bj < 2; ++bj) { const f32x4 h0 = rx[m][bj][0] + acc[ai][bj][m][0], h1 = rx[m][bj][1] + acc[ai][bj][m][1];
	v_mfma_f32_16x16x32_bf16 v[92:95], v[128:131], v[188:191], v[92:95]
	v_mfma_f32_16x16x32_bf16 v[88:91], v[136:139], v[188:191], v[88:91]
	v_mfma_f32_16x16x32_bf16 v[76:79], v[128:131], v[196:199], v[76:79]
	v_mfma_f32_16x16x32_bf16 v[72:75], v[136:139], v[196:199], v[72:75]
	v_mfma_f32_16x16x32_bf16 v[124:127], v[132:135], v[164:167], v[124:127]
	v_mfma_f32_16x16x32_bf16 v[120:123], v[140:143], v[164:167], v[120:123]
	v_mfma_f32_16x16x32_bf16 v[108:111], v[132:135], v[172:175], v[108:111]
	v_mfma_f32_16x16x32_bf16 v[104:107], v[140:143], v[172:175], v[104:107]
	v_mfma_f32_16x16x32_bf16 v[92:95], v[132:135], v[192:195], v[92:95]
	v_mfma_f32_16x16x32_bf16 v[88:91], v[140:143], v[192:195], v[88:91]
	v_mfma_f32_16x16x32_bf16 v[76:79], v[132:135], v[210:213], v[76:79]
	v_mfma_f32_16x16x32_bf16 v[72:75], v[140:143], v[210:213], v[72:75]
	s_setprio 0
	s_setprio 1
	v_mfma_f32_16x16x32_bf16 v[116:119], v[144:147], v[160:163], v[116:119]
	v_mfma_f32_16x16x32_bf16 v[112:115], v[152:155], v[160:163], v[112:115]
	v_mfma_f32_16x16x32_bf16 v[100:103], v[144:147], v[168:171], v[100:103]
	v_mfma_f32_16x16x32_bf16 v[96:99], v[152:155], v[168:171], v[96:99]
	v_mfma_f32_16x16x32_bf16 v[84:87], v[144:147], v[188:191], v[84:87]
	v_mfma_f32_16x16x32_bf16 v[80:83], v[152:155], v[188:191], v[80:83]
	v_mfma_f32_16x16x32_bf16 v[68:71], v[144:147], v[196:199], v[68:71]
	v_mfma_f32_16x16x32_bf16 v[64:67], v[152:155], v[196:199], v[64:67]
	v_mfma_f32_16x16x32_bf16 v[116:119], v[148:151], v[164:167], v[116:119]
	v_mfma_f32_16x16x32_bf16 v[112:115], v[156:159], v[164:167], v[112:115]
	v_mfma_f32_16x16x32_bf16 v[100:103], v[148:151], v[172:175], v[100:103]
	v_mfma_f32_16x16x32_bf16 v[96:99], v[156:159], v[172:175], v[96:99]
	v_mfma_f32_16x16x32_bf16 v[84:87], v[148:151], v[192:195], v[84:87]
	v_mfma_f32_16x16x32_bf16 v[80:83], v[156:159], v[192:195], v[80:83]
	v_mfma_f32_16x16x32_bf16 v[68:71], v[148:151], v[210:213], v[68:71]
	v_mfma_f32_16x16x32_bf16 v[64:67], v[156:159], v[210:213], v[64:67]
	s_setprio 0
	s_barrier
	s_add_i32 s36, s60, s42
	v_lshl_add_u64 v[214:215], v[214:215], 0, s[14:15]
	s_mov_b32 m0, s36
	ds_read_b128 v[160:163], v205 offset:49152
	ds_read_b128 v[164:167], v205 offset:50176
	ds_read_b128 v[168:171], v205 offset:51200
	ds_read_b128 v[172:175], v205 offset:52224
	ds_read_b128 v[188:191], v205 offset:53248
	ds_read_b128 v[192:195], v205 offset:54272
	ds_read_b128 v[196:199], v205 offset:55296
	ds_read_b128 v[210:213], v205 offset:56320
	global_load_lds_dwordx4 v[214:215], off
	s_add_i32 m0, s36, 0x2000
	s_add_u32 s34, s34, 0x40080
	v_lshl_add_u64 v[214:215], v[216:217], 0, s[14:15]
	s_addc_u32 s35, s35, 0
	s_add_i32 s36, s61, s42
	global_load_lds_dwordx4 v[214:215], off
	v_lshl_add_u64 v[214:215], s[34:35], 0, v[178:179]
	s_mov_b32 m0, s36
	s_nop 0
	global_load_lds_dwordx4 v[214:215], off
	v_lshl_add_u64 v[214:215], s[34:35], 0, v[182:183]
	s_add_i32 m0, s36, 0x2000
	s_nop 0
	global_load_lds_dwordx4 v[214:215], off
	v_lshl_add_u64 v[214:215], v[218:219], 0, s[14:15]
	s_mov_b32 m0, s49
	s_nop 0
	global_load_lds_dwordx4 v[214:215], off
	v_lshl_add_u64 v[214:215], v[220:221], 0, s[14:15]
	s_mov_b32 m0, s50
	s_nop 0
	global_load_lds_dwordx4 v[214:215], off
	s_waitcnt vmcnt(10)
	s_waitcnt lgkmcnt(0)
	v_add_f32_e32 v124, v124, v232
	v_add_f32_e32 v125, v125, v233
	v_add_f32_e32 v126, v126, v234
	v_add_f32_e32 v127, v127, v235
	global_load_dwordx4 v[232:235], v229, s[68:69] offset:528
	s_setprio 1
	s_waitcnt lgkmcnt(0)
	v_mfma_f32_16x16x32_bf16 v[60:63], v[128:131], v[160:163], v[60:63]
	v_mfma_f32_16x16x32_bf16 v[56:59], v[136:139], v[160:163], v[56:59]
	v_mfma_f32_16x16x32_bf16 v[44:47], v[128:131], v[168:171], v[44:47]
	v_mfma_f32_16x16x32_bf16 v[40:43], v[136:139], v[168:171], v[40:43]
	s_barrier
	v_mfma_f32_16x16x32_bf16 v[28:31], v[128:131], v[188:191], v[28:31]
	v_mfma_f32_16x16x32_bf16 v[24:27], v[136:139], v[188:191], v[24:27]
	v_mfma_f32_16x16x32_bf16 v[12:15], v[128:131], v[196:199], v[12:15]
	v_mfma_f32_16x16x32_bf16 v[8:11], v[136:139], v[196:199], v[8:11]
	v_mfma_f32_16x16x32_bf16 v[60:63], v[132:135], v[164:167], v[60:63]
	v_mfma_f32_16x16x32_bf16 v[56:59], v[140:143], v[164:167], v[56:59]
	v_mfma_f32_16x16x32_bf16 v[44:47], v[132:135], v[172:175], v[44:47]
	v_mfma_f32_16x16x32_bf16 v[40:43], v[140:143], v[172:175], v[40:43]
	v_mfma_f32_16x16x32_bf16 v[28:31], v[132:135], v[192:195], v[28:31]
	v_mfma_f32_16x16x32_bf16 v[24:27], v[140:143], v[192:195], v[24:27]
	v_mfma_f32_16x16x32_bf16 v[12:15], v[132:135], v[210:213], v[12:15]
	v_mfma_f32_16x16x32_bf16 v[8:11], v[140:143], v[210:213], v[8:11]
	s_setprio 0
	s_setprio 1
	v_mfma_f32_16x16x32_bf16 v[52:55], v[144:147], v[160:163], v[52:55]
	v_mfma_f32_16x16x32_bf16 v[48:51], v[152:155], v[160:163], v[48:51]
	v_mfma_f32_16x16x32_bf16 v[36:39], v[144:147], v[168:171], v[36:39]
	v_mfma_f32_16x16x32_bf16 v[32:35], v[152:155], v[168:171], v[32:35]
	v_mfma_f32_16x16x32_bf16 v[20:23], v[144:147], v[188:191], v[20:23]
	v_mfma_f32_16x16x32_bf16 v[16:19], v[152:155], v[188:191], v[16:19]
	v_mfma_f32_16x16x32_bf16 v[4:7], v[144:147], v[196:199], v[4:7]
	v_mfma_f32_16x16x32_bf16 v[0:3], v[152:155], v[196:199], v[0:3]
	v_mfma_f32_16x16x32_bf16 v[52:55], v[148:151], v[164:167], v[52:55]
	v_mfma_f32_16x16x32_bf16 v[48:51], v[156:159], v[164:167], v[48:51]
	v_mfma_f32_16x16x32_bf16 v[36:39], v[148:151], v[172:175], v[36:39]
	v_mfma_f32_16x16x32_bf16 v[32:35], v[156:159], v[172:175], v[32:35]
	v_mfma_f32_16x16x32_bf16 v[20:23], v[148:151], v[192:195], v[20:23]
	v_mfma_f32_16x16x32_bf16 v[16:19], v[156:159], v[192:195], v[16:19]
	v_mfma_f32_16x16x32_bf16 v[4:7], v[148:151], v[210:213], v[4:7]
	v_mfma_f32_16x16x32_bf16 v[0:3], v[156:159], v[210:213], v[0:3]
	s_setprio 0
	s_barrier
; #define PG8_WAIT_V(n) asm volatile("s_waitcnt vmcnt(" #n ")" ::: "memory")
; template <class Epi, bool ALIGN_EPI, bool SP2>
; __device__ __forceinline__ void gemm_phase(LAS unsigned char* lds, const int K, const Sched& S, const Epi& E) {
;     ...
;         for (int t = 0; t < nt; t += 2) {
;             const bool last = (t == nt - 2);
;             const char* a1 = cA + (size_t)(t + 1) * kstep;
;             const char* a2 = last ? nA : cA + (size_t)(t + 2) * kstep; const char* b2 = last ? nB : cB + (size_t)(t + 2) * kstep;
;             const char* a3 = a2 + kstep; const char* b3 = b2 + kstep;
;             if constexpr (SP2) {
;             PG8_LDB(B0, 0, 0); PG8_LDB(B1, 0, 1); PG8_SCHED; PG8_LDA(At, 0, 0); PG8_STAGE(PG8_SA(1, 1), a1 + hstep, voffA);
;             PG8_WAIT_V(8); PG8_WAIT_L(0); PG8_BAR; PG8_MMA(0, 0, At, B0); PG8_MMA(0, 1, At, B1); PG8_BAR; PG8_SCHED;
;             PG8_LDA(At, 0, 1); PG8_STAGE(PG8_SB(0, 0), b2, voffB); PG8_STAGE(PG8_SB(0, 1), b2 + hstep, voffB); PG8_STAGE(PG8_SA(0, 0), a2, voffA);
;             PG8_WAIT_V(8); PG8_WAIT_L(0); PG8_BAR; PG8_MMA(1, 0, At, B0); PG8_MMA(1, 1, At, B1); PG8_BAR; PG8_SCHED;
;             PG8_LDB(B0, 1, 0); PG8_LDB(B1, 1, 1); PG8_SCHED; PG8_LDA(At, 1, 0); PG8_STAGE(PG8_SA(0, 1), a2 + hstep, voffA);
;             PG8_WAIT_V(8); PG8_WAIT_L(0); PG8_BAR; PG8_MMA(0, 0, At, B0); PG8_MMA(0, 1, At, B1); PG8_BAR; PG8_SCHED;
;             PG8_LDA(At, 1, 1); PG8_STAGE(PG8_SB(1, 0), b3, voffB); PG8_STAGE(PG8_SB(1, 1), b3 + hstep, voffB); PG8_STAGE(PG8_SA(1, 0), a3, voffA);
;             PG8_WAIT_V(8); PG8_WAIT_L(0); PG8_BAR; PG8_MMA(1, 0, At, B0); PG8_MMA(1, 1, At, B1); PG8_BAR; PG8_SCHED;
;     __device__ __forceinline__ void operator()(Acc& acc, const Unit& u, int wr, int wc, int fr, int fq) const {
;     ...
;                     for (int bj = 0; bj < 2; ++bj) { const float* p = basef + (size_t)(row0 + ai * HALF + m * 16) * D + col0 + bj * HALF; rx[m][bj][0] = *(const f32x4*)p; rx[m][bj][1] = *(const f32x4*)(p + 4); }
;                 __builtin_amdgcn_sched_barrier(0);
; #pragma unroll
;                 for (int m = 0; m < 4; ++m) { const int row = row0 + ai * HALF + m * 16; const size_t o = (size_t)row * D + col0; float ss = 0.f;
; #pragma unroll
;                     for (int bj = 0; bj < 2; ++bj) { const f32x4 h0 = rx[m][bj][0] + acc[ai][bj][m][0], h1 = rx[m][bj][1] + acc[ai][bj][m][1];
	s_add_i32 s59, s59, 2
	s_add_u32 s30, s30, 0x100
	s_addc_u32 s31, s31, 0
	s_add_u32 s57, s57, 0x100
	s_addc_u32 s58, s58, 0
	ds_read_b128 v[128:131], v203
	ds_read_b128 v[132:135], v203 offset:1024
	ds_read_b128 v[136:139], v203 offset:2048
	ds_read_b128 v[140:143], v203 offset:3072
	ds_read_b128 v[144:147], v204
	ds_read_b128 v[148:151], v204 offset:1024
	ds_read_b128 v[152:155], v204 offset:2048
	ds_read_b128 v[156:159], v204 offset:3072
	s_add_u32 s34, s30, 0xfffc0080
	s_addc_u32 s35, s31, -1
	s_cmp_eq_u32 s59, 12
	s_cselect_b32 s37, s7, s35
	s_cselect_b32 s36, s19, s34
	s_cselect_b32 s35, s21, s58
	s_cselect_b32 s34, s56, s57
	s_mov_b32 m0, s53
	v_lshl_add_u64 v[214:215], s[30:31], 0, v[184:185]
	ds_read_b128 v[160:163], v205
	ds_read_b128 v[164:167], v205 offset:1024
	ds_read_b128 v[168:171], v205 offset:2048
	ds_read_b128 v[172:175], v205 offset:3072
	ds_read_b128 v[188:191], v205 offset:4096
	ds_read_b128 v[192:195], v205 offset:5120
	ds_read_b128 v[196:199], v205 offset:6144
	ds_read_b128 v[210:213], v205 offset:7168
	global_load_lds_dwordx4 v[214:215], off
	v_lshl_add_u64 v[214:215], s[30:31], 0, v[186:187]
	s_mov_b32 m0, s54
	s_nop 0
	global_load_lds_dwordx4 v[214:215], off
	s_waitcnt vmcnt(10)
	s_waitcnt lgkmcnt(0)
	v_add_f32_e32 v120, v120, v236
	v_add_f32_e32 v121, v121, v237
	v_add_f32_e32 v122, v122, v238
	v_add_f32_e32 v123, v123, v239
	s_add_u32 s68, s70, 0x10000
	s_addc_u32 s69, s71, 0
	global_load_dwordx4 v[236:239], v229, s[68:69]
	s_setprio 1
	s_waitcnt lgkmcnt(0)
	v_mfma_f32_16x16x32_bf16 v[124:127], v[128:131], v[160:163], v[124:127]
	v_mfma_f32_16x16x32_bf16 v[120:123], v[136:139], v[160:163], v[120:123]
	v_mfma_f32_16x16x32_bf16 v[108:111], v[128:131], v[168:171], v[108:111]
	v_mfma_f32_16x16x32_bf16 v[104:107], v[136:139], v[168:171], v[104:107]
	s_barrier
	v_mfma_f32_16x16x32_bf16 v[92:95], v[128:131], v[188:191], v[92:95]
	v_mfma_f32_16x16x32_bf16 v[88:91], v[136:139], v[188:191], v[88:91]
	v_mfma_f32_16x16x32_bf16 v[76:79], v[128:131], v[196:199], v[76:79]
	v_mfma_f32_16x16x32_bf16 v[72:75], v[136:139], v[196:199], v[72:75]
	v_mfma_f32_16x16x32_bf16 v[124:127], v[132:135], v[164:167], v[124:127]
	v_mfma_f32_16x16x32_bf16 v[120:123], v[140:143], v[164:167], v[120:123]
	v_mfma_f32_16x16x32_bf16 v[108:111], v[132:135], v[172:175], v[108:111]
	v_mfma_f32_16x16x32_bf16 v[104:107], v[140:143], v[172:175], v[104:107]
	v_mfma_f32_16x16x32_bf16 v[92:95], v[132:135], v[192:195], v[92:95]
	v_mfma_f32_16x16x32_bf16 v[88:91], v[140:143], v[192:195], v[88:91]
	v_mfma_f32_16x16x32_bf16 v[76:79], v[132:135], v[210:213], v[76:79]
	v_mfma_f32_16x16x32_bf16 v[72:75], v[140:143], v[210:213], v[72:75]
	s_setprio 0
	s_setprio 1
	v_mfma_f32_16x16x32_bf16 v[116:119], v[144:147], v[160:163], v[116:119]
	v_mfma_f32_16x16x32_bf16 v[112:115], v[152:155], v[160:163], v[112:115]
	v_mfma_f32_16x16x32_bf16 v[100:103], v[144:147], v[168:171], v[100:103]
	v_mfma_f32_16x16x32_bf16 v[96:99], v[152:155], v[168:171], v[96:99]
	v_mfma_f32_16x16x32_bf16 v[84:87], v[144:147], v[188:191], v[84:87]
	v_mfma_f32_16x16x32_bf16 v[80:83], v[152:155], v[188:191], v[80:83]
	v_mfma_f32_16x16x32_bf16 v[68:71], v[144:147], v[196:199], v[68:71]
	v_mfma_f32_16x16x32_bf16 v[64:67], v[152:155], v[196:199], v[64:67]
	v_mfma_f32_16x16x32_bf16 v[116:119], v[148:151], v[164:167], v[116:119]
	v_mfma_f32_16x16x32_bf16 v[112:115], v[156:159], v[164:167], v[112:115]
	v_mfma_f32_16x16x32_bf16 v[100:103], v[148:151], v[172:175], v[100:103]
	v_mfma_f32_16x16x32_bf16 v[96:99], v[156:159], v[172:175], v[96:99]
	v_mfma_f32_16x16x32_bf16 v[84:87], v[148:151], v[192:195], v[84:87]
	v_mfma_f32_16x16x32_bf16 v[80:83], v[156:159], v[192:195], v[80:83]
	v_mfma_f32_16x16x32_bf16 v[68:71], v[148:151], v[210:213], v[68:71]
	v_mfma_f32_16x16x32_bf16 v[64:67], v[156:159], v[210:213], v[64:67]
	s_setprio 0
	s_barrier
	s_mov_b32 m0, s55
	v_lshl_add_u64 v[214:215], s[34:35], 0, v[178:179]
	ds_read_b128 v[160:163], v205 offset:16384
	ds_read_b128 v[164:167], v205 offset:17408
	ds_read_b128 v[168:171], v205 offset:18432
	ds_read_b128 v[172:175], v205 offset:19456
	ds_read_b128 v[188:191], v205 offset:20480
	ds_read_b128 v[192:195], v205 offset:21504
	ds_read_b128 v[196:199], v205 offset:22528
	ds_read_b128 v[210:213], v205 offset:23552
	global_load_lds_dwordx4 v[214:215], off
	s_add_i32 m0, s55, 0x2000
	s_add_u32 s60, s34, 0x40000
	v_lshl_add_u64 v[216:217], s[34:35], 0, v[182:183]
	s_addc_u32 s61, s35, 0
	s_add_i32 s62, s51, s42
	global_load_lds_dwordx4 v[216:217], off
	v_lshl_add_u64 v[218:219], s[60:61], 0, v[178:179]
	s_mov_b32 m0, s62
	v_lshl_add_u64 v[220:221], s[36:37], 0, v[180:181]
	global_load_lds_dwordx4 v[218:219], off
	v_lshl_add_u64 v[218:219], s[60:61], 0, v[182:183]
	s_add_i32 m0, s62, 0x2000
	s_nop 0
	global_load_lds_dwordx4 v[218:219], off
	v_lshl_add_u64 v[218:219], s[36:37], 0, v[176:177]
	s_mov_b32 m0, s29
	s_nop 0
	global_load_lds_dwordx4 v[218:219], off
	s_mov_b32 m0, s43
	s_nop 0
	global_load_lds_dwordx4 v[220:221], off
	s_waitcnt vmcnt(10)
	s_waitcnt lgkmcnt(0)
	v_add_f32_e32 v116, v116, v240
	v_add_f32_e32 v117, v117, v241
	v_add_f32_e32 v118, v118, v242
	v_add_f32_e32 v119, v119, v243
	global_load_dwordx4 v[240:243], v229, s[68:69] offset:16
	s_setprio 1
	s_waitcnt lgkmcnt(0)
	v_mfma_f32_16x16x32_bf16 v[60:63], v[128:131], v[160:163], v[60:63]
	v_mfma_f32_16x16x32_bf16 v[56:59], v[136:139], v[160:163], v[56:59]
	v_mfma_f32_16x16x32_bf16 v[44:47], v[128:131], v[168:171], v[44:47]
	v_mfma_f32_16x16x32_bf16 v[40:43], v[136:139], v[168:171], v[40:43]
	s_barrier
; #define PG8_STAGE(bufoff, gbase, voff) do { _Pragma("unroll") for (int _i = 0; _i < 2; ++_i) \
;         __builtin_amdgcn_global_load_lds((const unsigned*)((const char*)(gbase) + (voff)[_i]), (LAS unsigned*)(lds + (bufoff) + ldsw + _i * 8192), 16, 0, 0); } while (0)
; #define PG8_LDA(dst, b, h) do { _Pragma("unroll") for (int m = 0; m < 4; ++m) _Pragma("unroll") for (int k = 0; k < 2; ++k) dst[m][k] = *(const LAS bf16x8*)(lds + PG8_SA(b, h) + aoff + m * 2048 + k * 1024); } while (0)
; #define PG8_LDB(dst, b, h) do { _Pragma("unroll") for (int n = 0; n < 2; ++n) _Pragma("unroll") for (int k = 0; k < 2; ++k) dst[n][k] = *(const LAS bf16x8*)(lds + PG8_SB(b, h) + boff + n * 2048 + k * 1024); } while (0)
; template <class Epi, bool ALIGN_EPI, bool SP2>
; __device__ __forceinline__ void gemm_phase(LAS unsigned char* lds, const int K, const Sched& S, const Epi& E) {
;     ...
;             PG8_LDA(At, 0, 1); PG8_STAGE(PG8_SB(0, 0), b2, voffB); PG8_STAGE(PG8_SB(0, 1), b2 + hstep, voffB); PG8_STAGE(PG8_SA(0, 0), a2, voffA);
;             PG8_WAIT_V(8); PG8_WAIT_L(0); PG8_BAR; PG8_MMA(1, 0, At, B0); PG8_MMA(1, 1, At, B1); PG8_BAR; PG8_SCHED;
;             PG8_LDB(B0, 1, 0); PG8_LDB(B1, 1, 1); PG8_SCHED; PG8_LDA(At, 1, 0); PG8_STAGE(PG8_SA(0, 1), a2 + hstep, voffA);
;             PG8_WAIT_V(8); PG8_WAIT_L(0); PG8_BAR; PG8_MMA(0, 0, At, B0); PG8_MMA(0, 1, At, B1); PG8_BAR; PG8_SCHED;
;             PG8_LDA(At, 1, 1); PG8_STAGE(PG8_SB(1, 0), b3, voffB); PG8_STAGE(PG8_SB(1, 1), b3 + hstep, voffB); PG8_STAGE(PG8_SA(1, 0), a3, voffA);
;             PG8_WAIT_V(8); PG8_WAIT_L(0); PG8_BAR; PG8_MMA(1, 0, At, B0); PG8_MMA(1, 1, At, B1); PG8_BAR; PG8_SCHED;
;     __device__ __forceinline__ void operator()(Acc& acc, const Unit& u, int wr, int wc, int fr, int fq) const {
;     ...
;                     for (int bj = 0; bj < 2; ++bj) { const float* p = basef + (size_t)(row0 + ai * HALF + m * 16) * D + col0 + bj * HALF; rx[m][bj][0] = *(const f32x4*)p; rx[m][bj][1] = *(const f32x4*)(p + 4); }
;                 __builtin_amdgcn_sched_barrier(0);
; #pragma unroll
;                 for (int m = 0; m < 4; ++m) { const int row = row0 + ai * HALF + m * 16; const size_t o = (size_t)row * D + col0; float ss = 0.f;
; #pragma unroll
;                     for (int bj = 0; bj < 2; ++bj) { const f32x4 h0 = rx[m][bj][0] + acc[ai][bj][m][0], h1 = rx[m][bj][1] + acc[ai][bj][m][1];
	v_mfma_f32_16x16x32_bf16 v[28:31], v[128:131], v[188:191], v[28:31]
	v_mfma_f32_16x16x32_bf16 v[24:27], v[136:139], v[188:191], v[24:27]
	v_mfma_f32_16x16x32_bf16 v[12:15], v[128:131], v[196:199], v[12:15]
	v_mfma_f32_16x16x32_bf16 v[8:11], v[136:139], v[196:199], v[8:11]
	v_mfma_f32_16x16x32_bf16 v[60:63], v[132:135], v[164:167], v[60:63]
	v_mfma_f32_16x16x32_bf16 v[56:59], v[140:143], v[164:167], v[56:59]
	v_mfma_f32_16x16x32_bf16 v[44:47], v[132:135], v[172:175], v[44:47]
	v_mfma_f32_16x16x32_bf16 v[40:43], v[140:143], v[172:175], v[40:43]
	v_mfma_f32_16x16x32_bf16 v[28:31], v[132:135], v[192:195], v[28:31]
	v_mfma_f32_16x16x32_bf16 v[24:27], v[140:143], v[192:195], v[24:27]
	v_mfma_f32_16x16x32_bf16 v[12:15], v[132:135], v[210:213], v[12:15]
	v_mfma_f32_16x16x32_bf16 v[8:11], v[140:143], v[210:213], v[8:11]
	s_setprio 0
	s_setprio 1
	v_mfma_f32_16x16x32_bf16 v[52:55], v[144:147], v[160:163], v[52:55]
	v_mfma_f32_16x16x32_bf16 v[48:51], v[152:155], v[160:163], v[48:51]
	v_mfma_f32_16x16x32_bf16 v[36:39], v[144:147], v[168:171], v[36:39]
	v_mfma_f32_16x16x32_bf16 v[32:35], v[152:155], v[168:171], v[32:35]
	v_mfma_f32_16x16x32_bf16 v[20:23], v[144:147], v[188:191], v[20:23]
	v_mfma_f32_16x16x32_bf16 v[16:19], v[152:155], v[188:191], v[16:19]
	v_mfma_f32_16x16x32_bf16 v[4:7], v[144:147], v[196:199], v[4:7]
	v_mfma_f32_16x16x32_bf16 v[0:3], v[152:155], v[196:199], v[0:3]
	v_mfma_f32_16x16x32_bf16 v[52:55], v[148:151], v[164:167], v[52:55]
	v_mfma_f32_16x16x32_bf16 v[48:51], v[156:159], v[164:167], v[48:51]
	v_mfma_f32_16x16x32_bf16 v[36:39], v[148:151], v[172:175], v[36:39]
	v_mfma_f32_16x16x32_bf16 v[32:35], v[156:159], v[172:175], v[32:35]
	v_mfma_f32_16x16x32_bf16 v[20:23], v[148:151], v[192:195], v[20:23]
	v_mfma_f32_16x16x32_bf16 v[16:19], v[156:159], v[192:195], v[16:19]
	v_mfma_f32_16x16x32_bf16 v[4:7], v[148:151], v[210:213], v[4:7]
	v_mfma_f32_16x16x32_bf16 v[0:3], v[156:159], v[210:213], v[0:3]
	s_setprio 0
	s_barrier
	s_add_i32 s60, 0, 0x18000
	s_add_i32 s61, 0, 0x1c000
	v_add_u32_e32 v140, s60, v202
	v_add_u32_e32 v156, s61, v202
	ds_read_b128 v[128:131], v140
	ds_read_b128 v[132:135], v140 offset:1024
	ds_read_b128 v[136:139], v140 offset:2048
	ds_read_b128 v[140:143], v140 offset:3072
	ds_read_b128 v[144:147], v156
	ds_read_b128 v[148:151], v156 offset:1024
	ds_read_b128 v[152:155], v156 offset:2048
	ds_read_b128 v[156:159], v156 offset:3072
	s_add_u32 s36, s36, 0x40000
	s_addc_u32 s37, s37, 0
	s_mov_b32 m0, s44
	v_lshl_add_u64 v[222:223], s[36:37], 0, v[176:177]
	ds_read_b128 v[160:163], v205 offset:32768
	ds_read_b128 v[164:167], v205 offset:33792
	ds_read_b128 v[168:171], v205 offset:34816
	ds_read_b128 v[172:175], v205 offset:35840
	ds_read_b128 v[188:191], v205 offset:36864
	ds_read_b128 v[192:195], v205 offset:37888
	ds_read_b128 v[196:199], v205 offset:38912
	ds_read_b128 v[210:213], v205 offset:39936
	global_load_lds_dwordx4 v[222:223], off
	v_lshl_add_u64 v[222:223], s[36:37], 0, v[180:181]
	s_mov_b32 m0, s45
	s_nop 0
	global_load_lds_dwordx4 v[222:223], off
	s_waitcnt vmcnt(10)
	s_waitcnt lgkmcnt(0)
	v_add_f32_e32 v112, v112, v232
	v_add_f32_e32 v113, v113, v233
	v_add_f32_e32 v114, v114, v234
	v_add_f32_e32 v115, v115, v235
	global_load_dwordx4 v[232:235], v229, s[68:69] offset:512
	s_setprio 1
	s_waitcnt lgkmcnt(0)
	v_mfma_f32_16x16x32_bf16 v[124:127], v[128:131], v[160:163], v[124:127]
	v_mfma_f32_16x16x32_bf16 v[120:123], v[136:139], v[160:163], v[120:123]
	v_mfma_f32_16x16x32_bf16 v[108:111], v[128:131], v[168:171], v[108:111]
	v_mfma_f32_16x16x32_bf16 v[104:107], v[136:139], v[168:171], v[104:107]
	s_barrier
	v_mfma_f32_16x16x32_bf16 v[92:95], v[128:131], v[188:191], v[92:95]
	v_mfma_f32_16x16x32_bf16 v[88:91], v[136:139], v[188:191], v[88:91]
	v_mfma_f32_16x16x32_bf16 v[76:79], v[128:131], v[196:199], v[76:79]
	v_mfma_f32_16x16x32_bf16 v[72:75], v[136:139], v[196:199], v[72:75]
	v_mfma_f32_16x16x32_bf16 v[124:127], v[132:135], v[164:167], v[124:127]
	v_mfma_f32_16x16x32_bf16 v[120:123], v[140:143], v[164:167], v[120:123]
	v_mfma_f32_16x16x32_bf16 v[108:111], v[132:135], v[172:175], v[108:111]
	v_mfma_f32_16x16x32_bf16 v[104:107], v[140:143], v[172:175], v[104:107]
	v_mfma_f32_16x16x32_bf16 v[92:95], v[132:135], v[192:195], v[92:95]
	v_mfma_f32_16x16x32_bf16 v[88:91], v[140:143], v[192:195], v[88:91]
	v_mfma_f32_16x16x32_bf16 v[76:79], v[132:135], v[210:213], v[76:79]
	v_mfma_f32_16x16x32_bf16 v[72:75], v[140:143], v[210:213], v[72:75]
	s_setprio 0
	s_setprio 1
	v_mfma_f32_16x16x32_bf16 v[116:119], v[144:147], v[160:163], v[116:119]
	v_mfma_f32_16x16x32_bf16 v[112:115], v[152:155], v[160:163], v[112:115]
	v_mfma_f32_16x16x32_bf16 v[100:103], v[144:147], v[168:171], v[100:103]
	v_mfma_f32_16x16x32_bf16 v[96:99], v[152:155], v[168:171], v[96:99]
	v_mfma_f32_16x16x32_bf16 v[84:87], v[144:147], v[188:191], v[84:87]
	v_mfma_f32_16x16x32_bf16 v[80:83], v[152:155], v[188:191], v[80:83]
	v_mfma_f32_16x16x32_bf16 v[68:71], v[144:147], v[196:199], v[68:71]
	v_mfma_f32_16x16x32_bf16 v[64:67], v[152:155], v[196:199], v[64:67]
	v_mfma_f32_16x16x32_bf16 v[116:119], v[148:151], v[164:167], v[116:119]
	v_mfma_f32_16x16x32_bf16 v[112:115], v[156:159], v[164:167], v[112:115]
	v_mfma_f32_16x16x32_bf16 v[100:103], v[148:151], v[172:175], v[100:103]
	v_mfma_f32_16x16x32_bf16 v[96:99], v[156:159], v[172:175], v[96:99]
	v_mfma_f32_16x16x32_bf16 v[84:87], v[148:151], v[192:195], v[84:87]
	v_mfma_f32_16x16x32_bf16 v[80:83], v[156:159], v[192:195], v[80:83]
	v_mfma_f32_16x16x32_bf16 v[68:71], v[148:151], v[210:213], v[68:71]
	v_mfma_f32_16x16x32_bf16 v[64:67], v[156:159], v[210:213], v[64:67]
	s_setprio 0
	s_barrier
; #define PG8_STAGE(bufoff, gbase, voff) do { _Pragma("unroll") for (int _i = 0; _i < 2; ++_i) \
;         __builtin_amdgcn_global_load_lds((const unsigned*)((const char*)(gbase) + (voff)[_i]), (LAS unsigned*)(lds + (bufoff) + ldsw + _i * 8192), 16, 0, 0); } while (0)
; #define PG8_LDA(dst, b, h) do { _Pragma("unroll") for (int m = 0; m < 4; ++m) _Pragma("unroll") for (int k = 0; k < 2; ++k) dst[m][k] = *(const LAS bf16x8*)(lds + PG8_SA(b, h) + aoff + m * 2048 + k * 1024); } while (0)
; template <class Epi, bool ALIGN_EPI, bool SP2>
; __device__ __forceinline__ void gemm_phase(LAS unsigned char* lds, const int K, const Sched& S, const Epi& E) {
;     ...
;         for (int t = 0; t < nt; t += 2) {
;             const bool last = (t == nt - 2);
;             const char* a1 = cA + (size_t)(t + 1) * kstep;
;             const char* a2 = last ? nA : cA + (size_t)(t + 2) * kstep; const char* b2 = last ? nB : cB + (size_t)(t + 2) * kstep;
;             const char* a3 = a2 + kstep; const char* b3 = b2 + kstep;
;             if constexpr (SP2) {
;             PG8_LDB(B0, 0, 0); PG8_LDB(B1, 0, 1); PG8_SCHED; PG8_LDA(At, 0, 0); PG8_STAGE(PG8_SA(1, 1), a1 + hstep, voffA);
;             PG8_WAIT_V(8); PG8_WAIT_L(0); PG8_BAR; PG8_MMA(0, 0, At, B0); PG8_MMA(0, 1, At, B1); PG8_BAR; PG8_SCHED;
;     ...
;             PG8_WAIT_V(8); PG8_WAIT_L(0); PG8_BAR; PG8_MMA(0, 0, At, B0); PG8_MMA(0, 1, At, B1); PG8_BAR; PG8_SCHED;
;             PG8_LDA(At, 1, 1); PG8_STAGE(PG8_SB(1, 0), b3, voffB); PG8_STAGE(PG8_SB(1, 1), b3 + hstep, voffB); PG8_STAGE(PG8_SA(1, 0), a3, voffA);
;             PG8_WAIT_V(8); PG8_WAIT_L(0); PG8_BAR; PG8_MMA(1, 0, At, B0); PG8_MMA(1, 1, At, B1); PG8_BAR; PG8_SCHED;
;     __device__ __forceinline__ void operator()(Acc& acc, const Unit& u, int wr, int wc, int fr, int fq) const {
;     ...
;                     for (int bj = 0; bj < 2; ++bj) { const float* p = basef + (size_t)(row0 + ai * HALF + m * 16) * D + col0 + bj * HALF; rx[m][bj][0] = *(const f32x4*)p; rx[m][bj][1] = *(const f32x4*)(p + 4); }
;                 __builtin_amdgcn_sched_barrier(0);
; #pragma unroll
;                 for (int m = 0; m < 4; ++m) { const int row = row0 + ai * HALF + m * 16; const size_t o = (size_t)row * D + col0; float ss = 0.f;
; #pragma unroll
;                     for (int bj = 0; bj < 2; ++bj) { const f32x4 h0 = rx[m][bj][0] + acc[ai][bj][m][0], h1 = rx[m][bj][1] + acc[ai][bj][m][1];
	s_add_i32 s36, s60, s42
	v_lshl_add_u64 v[214:215], v[214:215], 0, s[14:15]
	s_mov_b32 m0, s36
	ds_read_b128 v[160:163], v205 offset:49152
	ds_read_b128 v[164:167], v205 offset:50176
	ds_read_b128 v[168:171], v205 offset:51200
	ds_read_b128 v[172:175], v205 offset:52224
	ds_read_b128 v[188:191], v205 offset:53248
	ds_read_b128 v[192:195], v205 offset:54272
	ds_read_b128 v[196:199], v205 offset:55296
	ds_read_b128 v[210:213], v205 offset:56320
	global_load_lds_dwordx4 v[214:215], off
	s_add_i32 m0, s36, 0x2000
	s_add_u32 s34, s34, 0x40080
	v_lshl_add_u64 v[214:215], v[216:217], 0, s[14:15]
	s_addc_u32 s35, s35, 0
	s_add_i32 s36, s61, s42
	global_load_lds_dwordx4 v[214:215], off
	v_lshl_add_u64 v[214:215], s[34:35], 0, v[178:179]
	s_mov_b32 m0, s36
	s_nop 0
	global_load_lds_dwordx4 v[214:215], off
	v_lshl_add_u64 v[214:215], s[34:35], 0, v[182:183]
	s_add_i32 m0, s36, 0x2000
	s_nop 0
	global_load_lds_dwordx4 v[214:215], off
	v_lshl_add_u64 v[214:215], v[218:219], 0, s[14:15]
	s_mov_b32 m0, s49
	s_nop 0
	global_load_lds_dwordx4 v[214:215], off
	v_lshl_add_u64 v[214:215], v[220:221], 0, s[14:15]
	s_mov_b32 m0, s50
	s_nop 0
	global_load_lds_dwordx4 v[214:215], off
	s_waitcnt vmcnt(10)
	s_waitcnt lgkmcnt(0)
	v_add_f32_e32 v108, v108, v236
	v_add_f32_e32 v109, v109, v237
	v_add_f32_e32 v110, v110, v238
	v_add_f32_e32 v111, v111, v239
	global_load_dwordx4 v[236:239], v229, s[68:69] offset:528
	s_setprio 1
	s_waitcnt lgkmcnt(0)
	v_mfma_f32_16x16x32_bf16 v[60:63], v[128:131], v[160:163], v[60:63]
	v_mfma_f32_16x16x32_bf16 v[56:59], v[136:139], v[160:163], v[56:59]
	v_mfma_f32_16x16x32_bf16 v[44:47], v[128:131], v[168:171], v[44:47]
	v_mfma_f32_16x16x32_bf16 v[40:43], v[136:139], v[168:171], v[40:43]
	s_barrier
	v_mfma_f32_16x16x32_bf16 v[28:31], v[128:131], v[188:191], v[28:31]
	v_mfma_f32_16x16x32_bf16 v[24:27], v[136:139], v[188:191], v[24:27]
	v_mfma_f32_16x16x32_bf16 v[12:15], v[128:131], v[196:199], v[12:15]
	v_mfma_f32_16x16x32_bf16 v[8:11], v[136:139], v[196:199], v[8:11]
	v_mfma_f32_16x16x32_bf16 v[60:63], v[132:135], v[164:167], v[60:63]
	v_mfma_f32_16x16x32_bf16 v[56:59], v[140:143], v[164:167], v[56:59]
	v_mfma_f32_16x16x32_bf16 v[44:47], v[132:135], v[172:175], v[44:47]
	v_mfma_f32_16x16x32_bf16 v[40:43], v[140:143], v[172:175], v[40:43]
	v_mfma_f32_16x16x32_bf16 v[28:31], v[132:135], v[192:195], v[28:31]
	v_mfma_f32_16x16x32_bf16 v[24:27], v[140:143], v[192:195], v[24:27]
	v_mfma_f32_16x16x32_bf16 v[12:15], v[132:135], v[210:213], v[12:15]
	v_mfma_f32_16x16x32_bf16 v[8:11], v[140:143], v[210:213], v[8:11]
	s_setprio 0
	s_setprio 1
	v_mfma_f32_16x16x32_bf16 v[52:55], v[144:147], v[160:163], v[52:55]
	v_mfma_f32_16x16x32_bf16 v[48:51], v[152:155], v[160:163], v[48:51]
	v_mfma_f32_16x16x32_bf16 v[36:39], v[144:147], v[168:171], v[36:39]
	v_mfma_f32_16x16x32_bf16 v[32:35], v[152:155], v[168:171], v[32:35]
	v_mfma_f32_16x16x32_bf16 v[20:23], v[144:147], v[188:191], v[20:23]
	v_mfma_f32_16x16x32_bf16 v[16:19], v[152:155], v[188:191], v[16:19]
	v_mfma_f32_16x16x32_bf16 v[4:7], v[144:147], v[196:199], v[4:7]
	v_mfma_f32_16x16x32_bf16 v[0:3], v[152:155], v[196:199], v[0:3]
	v_mfma_f32_16x16x32_bf16 v[52:55], v[148:151], v[164:167], v[52:55]
	v_mfma_f32_16x16x32_bf16 v[48:51], v[156:159], v[164:167], v[48:51]
	v_mfma_f32_16x16x32_bf16 v[36:39], v[148:151], v[172:175], v[36:39]
	v_mfma_f32_16x16x32_bf16 v[32:35], v[156:159], v[172:175], v[32:35]
	v_mfma_f32_16x16x32_bf16 v[20:23], v[148:151], v[192:195], v[20:23]
	v_mfma_f32_16x16x32_bf16 v[16:19], v[156:159], v[192:195], v[16:19]
	v_mfma_f32_16x16x32_bf16 v[4:7], v[148:151], v[210:213], v[4:7]
	v_mfma_f32_16x16x32_bf16 v[0:3], v[156:159], v[210:213], v[0:3]
	s_setprio 0
	s_barrier
	s_add_i32 s59, s59, 2
	s_add_u32 s30, s30, 0x100
	s_addc_u32 s31, s31, 0
	s_add_u32 s57, s57, 0x100
	s_addc_u32 s58, s58, 0
	ds_read_b128 v[128:131], v203
	ds_read_b128 v[132:135], v203 offset:1024
	ds_read_b128 v[136:139], v203 offset:2048
	ds_read_b128 v[140:143], v203 offset:3072
	ds_read_b128 v[144:147], v204
	ds_read_b128 v[148:151], v204 offset:1024
	ds_read_b128 v[152:155], v204 offset:2048
	ds_read_b128 v[156:159], v204 offset:3072
	s_add_u32 s34, s30, 0xfffc0080
	s_addc_u32 s35, s31, -1
	s_cmp_eq_u32 s59, 12
	s_cselect_b32 s37, s7, s35
	s_cselect_b32 s36, s19, s34
	s_cselect_b32 s35, s21, s58
	s_cselect_b32 s34, s56, s57
	s_mov_b32 m0, s53
	v_lshl_add_u64 v[214:215], s[30:31], 0, v[184:185]
	ds_read_b128 v[160:163], v205
	ds_read_b128 v[164:167], v205 offset:1024
	ds_read_b128 v[168:171], v205 offset:2048
	ds_read_b128 v[172:175], v205 offset:3072
	ds_read_b128 v[188:191], v205 offset:4096
	ds_read_b128 v[192:195], v205 offset:5120
	ds_read_b128 v[196:199], v205 offset:6144
	ds_read_b128 v[210:213], v205 offset:7168
	global_load_lds_dwordx4 v[214:215], off
	v_lshl_add_u64 v[214:215], s[30:31], 0, v[186:187]
	s_mov_b32 m0, s54
	s_nop 0
	global_load_lds_dwordx4 v[214:215], off
	s_waitcnt vmcnt(10)
	s_waitcnt lgkmcnt(0)
	v_add_f32_e32 v104, v104, v240
	v_add_f32_e32 v105, v105, v241
	v_add_f32_e32 v106, v106, v242
	v_add_f32_e32 v107, v107, v243
	s_add_u32 s68, s70, 0x20000
	s_addc_u32 s69, s71, 0
	global_load_dwordx4 v[240:243], v229, s[68:69]
	s_setprio 1
	s_waitcnt lgkmcnt(0)
	v_mfma_f32_16x16x32_bf16 v[124:127], v[128:131], v[160:163], v[124:127]
	v_mfma_f32_16x16x32_bf16 v[120:123], v[136:139], v[160:163], v[120:123]
	v_mfma_f32_16x16x32_bf16 v[108:111], v[128:131], v[168:171], v[108:111]
	v_mfma_f32_16x16x32_bf16 v[104:107], v[136:139], v[168:171], v[104:107]
	s_barrier
; #define PG8_STAGE(bufoff, gbase, voff) do { _Pragma("unroll") for (int _i = 0; _i < 2; ++_i) \
;         __builtin_amdgcn_global_load_lds((const unsigned*)((const char*)(gbase) + (voff)[_i]), (LAS unsigned*)(lds + (bufoff) + ldsw + _i * 8192), 16, 0, 0); } while (0)
; #define PG8_LDA(dst, b, h) do { _Pragma("unroll") for (int m = 0; m < 4; ++m) _Pragma("unroll") for (int k = 0; k < 2; ++k) dst[m][k] = *(const LAS bf16x8*)(lds + PG8_SA(b, h) + aoff + m * 2048 + k * 1024); } while (0)
; #define PG8_LDB(dst, b, h) do { _Pragma("unroll") for (int n = 0; n < 2; ++n) _Pragma("unroll") for (int k = 0; k < 2; ++k) dst[n][k] = *(const LAS bf16x8*)(lds + PG8_SB(b, h) + boff + n * 2048 + k * 1024); } while (0)
; #define PG8_WAIT_V(n) asm volatile("s_waitcnt vmcnt(" #n ")" ::: "memory")
; #define PG8_WAIT_L(n) asm volatile("s_waitcnt lgkmcnt(" #n ")" ::: "memory")
; #define PG8_BAR __builtin_amdgcn_s_barrier()
; #define PG8_SCHED __builtin_amdgcn_sched_barrier(0)
; template <class Epi, bool ALIGN_EPI, bool SP2>
; __device__ __forceinline__ void gemm_phase(LAS unsigned char* lds, const int K, const Sched& S, const Epi& E) {
;     ...
;             PG8_LDA(At, 0, 1); PG8_STAGE(PG8_SB(0, 0), b2, voffB); PG8_STAGE(PG8_SB(0, 1), b2 + hstep, voffB); PG8_STAGE(PG8_SA(0, 0), a2, voffA);
;             PG8_WAIT_V(8); PG8_WAIT_L(0); PG8_BAR; PG8_MMA(1, 0, At, B0); PG8_MMA(1, 1, At, B1); PG8_BAR; PG8_SCHED;
;             PG8_LDB(B0, 1, 0); PG8_LDB(B1, 1, 1); PG8_SCHED; PG8_LDA(At, 1, 0); PG8_STAGE(PG8_SA(0, 1), a2 + hstep, voffA);
;             PG8_WAIT_V(8); PG8_WAIT_L(0); PG8_BAR; PG8_MMA(0, 0, At, B0); PG8_MMA(0, 1, At, B1); PG8_BAR; PG8_SCHED;
;     __device__ __forceinline__ void operator()(Acc& acc, const Unit& u, int wr, int wc, int fr, int fq) const {
;     ...
;                     for (int bj = 0; bj < 2; ++bj) { const float* p = basef + (size_t)(row0 + ai * HALF + m * 16) * D + col0 + bj * HALF; rx[m][bj][0] = *(const f32x4*)p; rx[m][bj][1] = *(const f32x4*)(p + 4); }
;                 __builtin_amdgcn_sched_barrier(0);
; #pragma unroll
;                 for (int m = 0; m < 4; ++m) { const int row = row0 + ai * HALF + m * 16; const size_t o = (size_t)row * D + col0; float ss = 0.f;
; #pragma unroll
;                     for (int bj = 0; bj < 2; ++bj) { const f32x4 h0 = rx[m][bj][0] + acc[ai][bj][m][0], h1 = rx[m][bj][1] + acc[ai][bj][m][1];
	v_mfma_f32_16x16x32_bf16 v[92:95], v[128:131], v[188:191], v[92:95]
	v_mfma_f32_16x16x32_bf16 v[88:91], v[136:139], v[188:191], v[88:91]
	v_mfma_f32_16x16x32_bf16 v[76:79], v[128:131], v[196:199], v[76:79]
	v_mfma_f32_16x16x32_bf16 v[72:75], v[136:139], v[196:199], v[72:75]
	v_mfma_f32_16x16x32_bf16 v[124:127], v[132:135], v[164:167], v[124:127]
	v_mfma_f32_16x16x32_bf16 v[120:123], v[140:143], v[164:167], v[120:123]
	v_mfma_f32_16x16x32_bf16 v[108:111], v[132:135], v[172:175], v[108:111]
	v_mfma_f32_16x16x32_bf16 v[104:107], v[140:143], v[172:175], v[104:107]
	v_mfma_f32_16x16x32_bf16 v[92:95], v[132:135], v[192:195], v[92:95]
	v_mfma_f32_16x16x32_bf16 v[88:91], v[140:143], v[192:195], v[88:91]
	v_mfma_f32_16x16x32_bf16 v[76:79], v[132:135], v[210:213], v[76:79]
	v_mfma_f32_16x16x32_bf16 v[72:75], v[140:143], v[210:213], v[72:75]
	s_setprio 0
	s_setprio 1
	v_mfma_f32_16x16x32_bf16 v[116:119], v[144:147], v[160:163], v[116:119]
	v_mfma_f32_16x16x32_bf16 v[112:115], v[152:155], v[160:163], v[112:115]
	v_mfma_f32_16x16x32_bf16 v[100:103], v[144:147], v[168:171], v[100:103]
	v_mfma_f32_16x16x32_bf16 v[96:99], v[152:155], v[168:171], v[96:99]
	v_mfma_f32_16x16x32_bf16 v[84:87], v[144:147], v[188:191], v[84:87]
	v_mfma_f32_16x16x32_bf16 v[80:83], v[152:155], v[188:191], v[80:83]
	v_mfma_f32_16x16x32_bf16 v[68:71], v[144:147], v[196:199], v[68:71]
	v_mfma_f32_16x16x32_bf16 v[64:67], v[152:155], v[196:199], v[64:67]
	v_mfma_f32_16x16x32_bf16 v[116:119], v[148:151], v[164:167], v[116:119]
	v_mfma_f32_16x16x32_bf16 v[112:115], v[156:159], v[164:167], v[112:115]
	v_mfma_f32_16x16x32_bf16 v[100:103], v[148:151], v[172:175], v[100:103]
	v_mfma_f32_16x16x32_bf16 v[96:99], v[156:159], v[172:175], v[96:99]
	v_mfma_f32_16x16x32_bf16 v[84:87], v[148:151], v[192:195], v[84:87]
	v_mfma_f32_16x16x32_bf16 v[80:83], v[156:159], v[192:195], v[80:83]
	v_mfma_f32_16x16x32_bf16 v[68:71], v[148:151], v[210:213], v[68:71]
	v_mfma_f32_16x16x32_bf16 v[64:67], v[156:159], v[210:213], v[64:67]
	s_setprio 0
	s_barrier
	s_mov_b32 m0, s55
	v_lshl_add_u64 v[214:215], s[34:35], 0, v[178:179]
	ds_read_b128 v[160:163], v205 offset:16384
	ds_read_b128 v[164:167], v205 offset:17408
	ds_read_b128 v[168:171], v205 offset:18432
	ds_read_b128 v[172:175], v205 offset:19456
	ds_read_b128 v[188:191], v205 offset:20480
	ds_read_b128 v[192:195], v205 offset:21504
	ds_read_b128 v[196:199], v205 offset:22528
	ds_read_b128 v[210:213], v205 offset:23552
	global_load_lds_dwordx4 v[214:215], off
	s_add_i32 m0, s55, 0x2000
	s_add_u32 s60, s34, 0x40000
	v_lshl_add_u64 v[216:217], s[34:35], 0, v[182:183]
	s_addc_u32 s61, s35, 0
	s_add_i32 s62, s51, s42
	global_load_lds_dwordx4 v[216:217], off
	v_lshl_add_u64 v[218:219], s[60:61], 0, v[178:179]
	s_mov_b32 m0, s62
	v_lshl_add_u64 v[220:221], s[36:37], 0, v[180:181]
	global_load_lds_dwordx4 v[218:219], off
	v_lshl_add_u64 v[218:219], s[60:61], 0, v[182:183]
	s_add_i32 m0, s62, 0x2000
	s_nop 0
	global_load_lds_dwordx4 v[218:219], off
	v_lshl_add_u64 v[218:219], s[36:37], 0, v[176:177]
	s_mov_b32 m0, s29
	s_nop 0
	global_load_lds_dwordx4 v[218:219], off
	s_mov_b32 m0, s43
	s_nop 0
	global_load_lds_dwordx4 v[220:221], off
	s_waitcnt vmcnt(10)
	s_waitcnt lgkmcnt(0)
	v_add_f32_e32 v100, v100, v232
	v_add_f32_e32 v101, v101, v233
	v_add_f32_e32 v102, v102, v234
	v_add_f32_e32 v103, v103, v235
	global_load_dwordx4 v[232:235], v229, s[68:69] offset:16
	s_setprio 1
	s_waitcnt lgkmcnt(0)
	v_mfma_f32_16x16x32_bf16 v[60:63], v[128:131], v[160:163], v[60:63]
	v_mfma_f32_16x16x32_bf16 v[56:59], v[136:139], v[160:163], v[56:59]
	v_mfma_f32_16x16x32_bf16 v[44:47], v[128:131], v[168:171], v[44:47]
	v_mfma_f32_16x16x32_bf16 v[40:43], v[136:139], v[168:171], v[40:43]
	s_barrier
	v_mfma_f32_16x16x32_bf16 v[28:31], v[128:131], v[188:191], v[28:31]
	v_mfma_f32_16x16x32_bf16 v[24:27], v[136:139], v[188:191], v[24:27]
	v_mfma_f32_16x16x32_bf16 v[12:15], v[128:131], v[196:199], v[12:15]
	v_mfma_f32_16x16x32_bf16 v[8:11], v[136:139], v[196:199], v[8:11]
	v_mfma_f32_16x16x32_bf16 v[60:63], v[132:135], v[164:167], v[60:63]
	v_mfma_f32_16x16x32_bf16 v[56:59], v[140:143], v[164:167], v[56:59]
	v_mfma_f32_16x16x32_bf16 v[44:47], v[132:135], v[172:175], v[44:47]
	v_mfma_f32_16x16x32_bf16 v[40:43], v[140:143], v[172:175], v[40:43]
	v_mfma_f32_16x16x32_bf16 v[28:31], v[132:135], v[192:195], v[28:31]
	v_mfma_f32_16x16x32_bf16 v[24:27], v[140:143], v[192:195], v[24:27]
	v_mfma_f32_16x16x32_bf16 v[12:15], v[132:135], v[210:213], v[12:15]
	v_mfma_f32_16x16x32_bf16 v[8:11], v[140:143], v[210:213], v[8:11]
	s_setprio 0
	s_setprio 1
	v_mfma_f32_16x16x32_bf16 v[52:55], v[144:147], v[160:163], v[52:55]
	v_mfma_f32_16x16x32_bf16 v[48:51], v[152:155], v[160:163], v[48:51]
	v_mfma_f32_16x16x32_bf16 v[36:39], v[144:147], v[168:171], v[36:39]
	v_mfma_f32_16x16x32_bf16 v[32:35], v[152:155], v[168:171], v[32:35]
	v_mfma_f32_16x16x32_bf16 v[20:23], v[144:147], v[188:191], v[20:23]
	v_mfma_f32_16x16x32_bf16 v[16:19], v[152:155], v[188:191], v[16:19]
	v_mfma_f32_16x16x32_bf16 v[4:7], v[144:147], v[196:199], v[4:7]
	v_mfma_f32_16x16x32_bf16 v[0:3], v[152:155], v[196:199], v[0:3]
	v_mfma_f32_16x16x32_bf16 v[52:55], v[148:151], v[164:167], v[52:55]
	v_mfma_f32_16x16x32_bf16 v[48:51], v[156:159], v[164:167], v[48:51]
	v_mfma_f32_16x16x32_bf16 v[36:39], v[148:151], v[172:175], v[36:39]
	v_mfma_f32_16x16x32_bf16 v[32:35], v[156:159], v[172:175], v[32:35]
	v_mfma_f32_16x16x32_bf16 v[20:23], v[148:151], v[192:195], v[20:23]
	v_mfma_f32_16x16x32_bf16 v[16:19], v[156:159], v[192:195], v[16:19]
	v_mfma_f32_16x16x32_bf16 v[4:7], v[148:151], v[210:213], v[4:7]
	v_mfma_f32_16x16x32_bf16 v[0:3], v[156:159], v[210:213], v[0:3]
	s_setprio 0
	s_barrier
; #define PG8_STAGE(bufoff, gbase, voff) do { _Pragma("unroll") for (int _i = 0; _i < 2; ++_i) \
;         __builtin_amdgcn_global_load_lds((const unsigned*)((const char*)(gbase) + (voff)[_i]), (LAS unsigned*)(lds + (bufoff) + ldsw + _i * 8192), 16, 0, 0); } while (0)
; #define PG8_LDA(dst, b, h) do { _Pragma("unroll") for (int m = 0; m < 4; ++m) _Pragma("unroll") for (int k = 0; k < 2; ++k) dst[m][k] = *(const LAS bf16x8*)(lds + PG8_SA(b, h) + aoff + m * 2048 + k * 1024); } while (0)
; #define PG8_LDB(dst, b, h) do { _Pragma("unroll") for (int n = 0; n < 2; ++n) _Pragma("unroll") for (int k = 0; k < 2; ++k) dst[n][k] = *(const LAS bf16x8*)(lds + PG8_SB(b, h) + boff + n * 2048 + k * 1024); } while (0)
; template <class Epi, bool ALIGN_EPI, bool SP2>
; __device__ __forceinline__ void gemm_phase(LAS unsigned char* lds, const int K, const Sched& S, const Epi& E) {
;     ...
;             PG8_LDA(At, 0, 1); PG8_STAGE(PG8_SB(0, 0), b2, voffB); PG8_STAGE(PG8_SB(0, 1), b2 + hstep, voffB); PG8_STAGE(PG8_SA(0, 0), a2, voffA);
;             PG8_WAIT_V(8); PG8_WAIT_L(0); PG8_BAR; PG8_MMA(1, 0, At, B0); PG8_MMA(1, 1, At, B1); PG8_BAR; PG8_SCHED;
;             PG8_LDB(B0, 1, 0); PG8_LDB(B1, 1, 1); PG8_SCHED; PG8_LDA(At, 1, 0); PG8_STAGE(PG8_SA(0, 1), a2 + hstep, voffA);
;             PG8_WAIT_V(8); PG8_WAIT_L(0); PG8_BAR; PG8_MMA(0, 0, At, B0); PG8_MMA(0, 1, At, B1); PG8_BAR; PG8_SCHED;
;             PG8_LDA(At, 1, 1); PG8_STAGE(PG8_SB(1, 0), b3, voffB); PG8_STAGE(PG8_SB(1, 1), b3 + hstep, voffB); PG8_STAGE(PG8_SA(1, 0), a3, voffA);
;             PG8_WAIT_V(8); PG8_WAIT_L(0); PG8_BAR; PG8_MMA(1, 0, At, B0); PG8_MMA(1, 1, At, B1); PG8_BAR; PG8_SCHED;
;     __device__ __forceinline__ void operator()(Acc& acc, const Unit& u, int wr, int wc, int fr, int fq) const {
;     ...
;                     for (int bj = 0; bj < 2; ++bj) { const float* p = basef + (size_t)(row0 + ai * HALF + m * 16) * D + col0 + bj * HALF; rx[m][bj][0] = *(const f32x4*)p; rx[m][bj][1] = *(const f32x4*)(p + 4); }
;                 __builtin_amdgcn_sched_barrier(0);
; #pragma unroll
;                 for (int m = 0; m < 4; ++m) { const int row = row0 + ai * HALF + m * 16; const size_t o = (size_t)row * D + col0; float ss = 0.f;
; #pragma unroll
;                     for (int bj = 0; bj < 2; ++bj) { const f32x4 h0 = rx[m][bj][0] + acc[ai][bj][m][0], h1 = rx[m][bj][1] + acc[ai][bj][m][1];
	s_add_i32 s60, 0, 0x18000
	s_add_i32 s61, 0, 0x1c000
	v_add_u32_e32 v140, s60, v202
	v_add_u32_e32 v156, s61, v202
	ds_read_b128 v[128:131], v140
	ds_read_b128 v[132:135], v140 offset:1024
	ds_read_b128 v[136:139], v140 offset:2048
	ds_read_b128 v[140:143], v140 offset:3072
	ds_read_b128 v[144:147], v156
	ds_read_b128 v[148:151], v156 offset:1024
	ds_read_b128 v[152:155], v156 offset:2048
	ds_read_b128 v[156:159], v156 offset:3072
	s_add_u32 s36, s36, 0x40000
	s_addc_u32 s37, s37, 0
	s_mov_b32 m0, s44
	v_lshl_add_u64 v[222:223], s[36:37], 0, v[176:177]
	ds_read_b128 v[160:163], v205 offset:32768
	ds_read_b128 v[164:167], v205 offset:33792
	ds_read_b128 v[168:171], v205 offset:34816
	ds_read_b128 v[172:175], v205 offset:35840
	ds_read_b128 v[188:191], v205 offset:36864
	ds_read_b128 v[192:195], v205 offset:37888
	ds_read_b128 v[196:199], v205 offset:38912
	ds_read_b128 v[210:213], v205 offset:39936
	global_load_lds_dwordx4 v[222:223], off
	v_lshl_add_u64 v[222:223], s[36:37], 0, v[180:181]
	s_mov_b32 m0, s45
	s_nop 0
	global_load_lds_dwordx4 v[222:223], off
	s_waitcnt vmcnt(10)
	s_waitcnt lgkmcnt(0)
	v_add_f32_e32 v96, v96, v236
	v_add_f32_e32 v97, v97, v237
	v_add_f32_e32 v98, v98, v238
	v_add_f32_e32 v99, v99, v239
	global_load_dwordx4 v[236:239], v229, s[68:69] offset:512
	s_setprio 1
	s_waitcnt lgkmcnt(0)
	v_mfma_f32_16x16x32_bf16 v[124:127], v[128:131], v[160:163], v[124:127]
	v_mfma_f32_16x16x32_bf16 v[120:123], v[136:139], v[160:163], v[120:123]
	v_mfma_f32_16x16x32_bf16 v[108:111], v[128:131], v[168:171], v[108:111]
	v_mfma_f32_16x16x32_bf16 v[104:107], v[136:139], v[168:171], v[104:107]
	s_barrier
	v_mfma_f32_16x16x32_bf16 v[92:95], v[128:131], v[188:191], v[92:95]
	v_mfma_f32_16x16x32_bf16 v[88:91], v[136:139], v[188:191], v[88:91]
	v_mfma_f32_16x16x32_bf16 v[76:79], v[128:131], v[196:199], v[76:79]
	v_mfma_f32_16x16x32_bf16 v[72:75], v[136:139], v[196:199], v[72:75]
	v_mfma_f32_16x16x32_bf16 v[124:127], v[132:135], v[164:167], v[124:127]
	v_mfma_f32_16x16x32_bf16 v[120:123], v[140:143], v[164:167], v[120:123]
	v_mfma_f32_16x16x32_bf16 v[108:111], v[132:135], v[172:175], v[108:111]
	v_mfma_f32_16x16x32_bf16 v[104:107], v[140:143], v[172:175], v[104:107]
	v_mfma_f32_16x16x32_bf16 v[92:95], v[132:135], v[192:195], v[92:95]
	v_mfma_f32_16x16x32_bf16 v[88:91], v[140:143], v[192:195], v[88:91]
	v_mfma_f32_16x16x32_bf16 v[76:79], v[132:135], v[210:213], v[76:79]
	v_mfma_f32_16x16x32_bf16 v[72:75], v[140:143], v[210:213], v[72:75]
	s_setprio 0
	s_setprio 1
	v_mfma_f32_16x16x32_bf16 v[116:119], v[144:147], v[160:163], v[116:119]
	v_mfma_f32_16x16x32_bf16 v[112:115], v[152:155], v[160:163], v[112:115]
	v_mfma_f32_16x16x32_bf16 v[100:103], v[144:147], v[168:171], v[100:103]
	v_mfma_f32_16x16x32_bf16 v[96:99], v[152:155], v[168:171], v[96:99]
	v_mfma_f32_16x16x32_bf16 v[84:87], v[144:147], v[188:191], v[84:87]
	v_mfma_f32_16x16x32_bf16 v[80:83], v[152:155], v[188:191], v[80:83]
	v_mfma_f32_16x16x32_bf16 v[68:71], v[144:147], v[196:199], v[68:71]
	v_mfma_f32_16x16x32_bf16 v[64:67], v[152:155], v[196:199], v[64:67]
	v_mfma_f32_16x16x32_bf16 v[116:119], v[148:151], v[164:167], v[116:119]
	v_mfma_f32_16x16x32_bf16 v[112:115], v[156:159], v[164:167], v[112:115]
	v_mfma_f32_16x16x32_bf16 v[100:103], v[148:151], v[172:175], v[100:103]
	v_mfma_f32_16x16x32_bf16 v[96:99], v[156:159], v[172:175], v[96:99]
	v_mfma_f32_16x16x32_bf16 v[84:87], v[148:151], v[192:195], v[84:87]
	v_mfma_f32_16x16x32_bf16 v[80:83], v[156:159], v[192:195], v[80:83]
	v_mfma_f32_16x16x32_bf16 v[68:71], v[148:151], v[210:213], v[68:71]
	v_mfma_f32_16x16x32_bf16 v[64:67], v[156:159], v[210:213], v[64:67]
	s_setprio 0
	s_barrier
	s_add_i32 s36, s60, s42
	v_lshl_add_u64 v[214:215], v[214:215], 0, s[14:15]
	s_mov_b32 m0, s36
	ds_read_b128 v[160:163], v205 offset:49152
	ds_read_b128 v[164:167], v205 offset:50176
	ds_read_b128 v[168:171], v205 offset:51200
	ds_read_b128 v[172:175], v205 offset:52224
	ds_read_b128 v[188:191], v205 offset:53248
	ds_read_b128 v[192:195], v205 offset:54272
	ds_read_b128 v[196:199], v205 offset:55296
	ds_read_b128 v[210:213], v205 offset:56320
	global_load_lds_dwordx4 v[214:215], off
	s_add_i32 m0, s36, 0x2000
	s_add_u32 s34, s34, 0x40080
	v_lshl_add_u64 v[214:215], v[216:217], 0, s[14:15]
	s_addc_u32 s35, s35, 0
	s_add_i32 s36, s61, s42
	global_load_lds_dwordx4 v[214:215], off
	v_lshl_add_u64 v[214:215], s[34:35], 0, v[178:179]
	s_mov_b32 m0, s36
	s_nop 0
	global_load_lds_dwordx4 v[214:215], off
	v_lshl_add_u64 v[214:215], s[34:35], 0, v[182:183]
	s_add_i32 m0, s36, 0x2000
	s_nop 0
	global_load_lds_dwordx4 v[214:215], off
	v_lshl_add_u64 v[214:215], v[218:219], 0, s[14:15]
	s_mov_b32 m0, s49
	s_nop 0
	global_load_lds_dwordx4 v[214:215], off
	v_lshl_add_u64 v[214:215], v[220:221], 0, s[14:15]
	s_mov_b32 m0, s50
	s_nop 0
	global_load_lds_dwordx4 v[214:215], off
	s_waitcnt vmcnt(10)
	s_waitcnt lgkmcnt(0)
	v_add_f32_e32 v92, v92, v240
	v_add_f32_e32 v93, v93, v241
	v_add_f32_e32 v94, v94, v242
	v_add_f32_e32 v95, v95, v243
	global_load_dwordx4 v[240:243], v229, s[68:69] offset:528
	s_setprio 1
	s_waitcnt lgkmcnt(0)
	v_mfma_f32_16x16x32_bf16 v[60:63], v[128:131], v[160:163], v[60:63]
	v_mfma_f32_16x16x32_bf16 v[56:59], v[136:139], v[160:163], v[56:59]
	v_mfma_f32_16x16x32_bf16 v[44:47], v[128:131], v[168:171], v[44:47]
	v_mfma_f32_16x16x32_bf16 v[40:43], v[136:139], v[168:171], v[40:43]
	s_barrier
; #define PG8_STAGE(bufoff, gbase, voff) do { _Pragma("unroll") for (int _i = 0; _i < 2; ++_i) \
;         __builtin_amdgcn_global_load_lds((const unsigned*)((const char*)(gbase) + (voff)[_i]), (LAS unsigned*)(lds + (bufoff) + ldsw + _i * 8192), 16, 0, 0); } while (0)
; #define PG8_LDA(dst, b, h) do { _Pragma("unroll") for (int m = 0; m < 4; ++m) _Pragma("unroll") for (int k = 0; k < 2; ++k) dst[m][k] = *(const LAS bf16x8*)(lds + PG8_SA(b, h) + aoff + m * 2048 + k * 1024); } while (0)
; template <class Epi, bool ALIGN_EPI, bool SP2>
; __device__ __forceinline__ void gemm_phase(LAS unsigned char* lds, const int K, const Sched& S, const Epi& E) {
;     ...
;         for (int t = 0; t < nt; t += 2) {
;             const bool last = (t == nt - 2);
;             const char* a1 = cA + (size_t)(t + 1) * kstep;
;             const char* a2 = last ? nA : cA + (size_t)(t + 2) * kstep; const char* b2 = last ? nB : cB + (size_t)(t + 2) * kstep;
;             const char* a3 = a2 + kstep; const char* b3 = b2 + kstep;
;             if constexpr (SP2) {
;             PG8_LDB(B0, 0, 0); PG8_LDB(B1, 0, 1); PG8_SCHED; PG8_LDA(At, 0, 0); PG8_STAGE(PG8_SA(1, 1), a1 + hstep, voffA);
;             PG8_WAIT_V(8); PG8_WAIT_L(0); PG8_BAR; PG8_MMA(0, 0, At, B0); PG8_MMA(0, 1, At, B1); PG8_BAR; PG8_SCHED;
;     ...
;             PG8_WAIT_V(8); PG8_WAIT_L(0); PG8_BAR; PG8_MMA(0, 0, At, B0); PG8_MMA(0, 1, At, B1); PG8_BAR; PG8_SCHED;
;             PG8_LDA(At, 1, 1); PG8_STAGE(PG8_SB(1, 0), b3, voffB); PG8_STAGE(PG8_SB(1, 1), b3 + hstep, voffB); PG8_STAGE(PG8_SA(1, 0), a3, voffA);
;             PG8_WAIT_V(8); PG8_WAIT_L(0); PG8_BAR; PG8_MMA(1, 0, At, B0); PG8_MMA(1, 1, At, B1); PG8_BAR; PG8_SCHED;
;     __device__ __forceinline__ void operator()(Acc& acc, const Unit& u, int wr, int wc, int fr, int fq) const {
;     ...
;                     for (int bj = 0; bj < 2; ++bj) { const float* p = basef + (size_t)(row0 + ai * HALF + m * 16) * D + col0 + bj * HALF; rx[m][bj][0] = *(const f32x4*)p; rx[m][bj][1] = *(const f32x4*)(p + 4); }
;                 __builtin_amdgcn_sched_barrier(0);
; #pragma unroll
;                 for (int m = 0; m < 4; ++m) { const int row = row0 + ai * HALF + m * 16; const size_t o = (size_t)row * D + col0; float ss = 0.f;
; #pragma unroll
;                     for (int bj = 0; bj < 2; ++bj) { const f32x4 h0 = rx[m][bj][0] + acc[ai][bj][m][0], h1 = rx[m][bj][1] + acc[ai][bj][m][1];
	v_mfma_f32_16x16x32_bf16 v[28:31], v[128:131], v[188:191], v[28:31]
	v_mfma_f32_16x16x32_bf16 v[24:27], v[136:139], v[188:191], v[24:27]
	v_mfma_f32_16x16x32_bf16 v[12:15], v[128:131], v[196:199], v[12:15]
	v_mfma_f32_16x16x32_bf16 v[8:11], v[136:139], v[196:199], v[8:11]
	v_mfma_f32_16x16x32_bf16 v[60:63], v[132:135], v[164:167], v[60:63]
	v_mfma_f32_16x16x32_bf16 v[56:59], v[140:143], v[164:167], v[56:59]
	v_mfma_f32_16x16x32_bf16 v[44:47], v[132:135], v[172:175], v[44:47]
	v_mfma_f32_16x16x32_bf16 v[40:43], v[140:143], v[172:175], v[40:43]
	v_mfma_f32_16x16x32_bf16 v[28:31], v[132:135], v[192:195], v[28:31]
	v_mfma_f32_16x16x32_bf16 v[24:27], v[140:143], v[192:195], v[24:27]
	v_mfma_f32_16x16x32_bf16 v[12:15], v[132:135], v[210:213], v[12:15]
	v_mfma_f32_16x16x32_bf16 v[8:11], v[140:143], v[210:213], v[8:11]
	s_setprio 0
	s_setprio 1
	v_mfma_f32_16x16x32_bf16 v[52:55], v[144:147], v[160:163], v[52:55]
	v_mfma_f32_16x16x32_bf16 v[48:51], v[152:155], v[160:163], v[48:51]
	v_mfma_f32_16x16x32_bf16 v[36:39], v[144:147], v[168:171], v[36:39]
	v_mfma_f32_16x16x32_bf16 v[32:35], v[152:155], v[168:171], v[32:35]
	v_mfma_f32_16x16x32_bf16 v[20:23], v[144:147], v[188:191], v[20:23]
	v_mfma_f32_16x16x32_bf16 v[16:19], v[152:155], v[188:191], v[16:19]
	v_mfma_f32_16x16x32_bf16 v[4:7], v[144:147], v[196:199], v[4:7]
	v_mfma_f32_16x16x32_bf16 v[0:3], v[152:155], v[196:199], v[0:3]
	v_mfma_f32_16x16x32_bf16 v[52:55], v[148:151], v[164:167], v[52:55]
	v_mfma_f32_16x16x32_bf16 v[48:51], v[156:159], v[164:167], v[48:51]
	v_mfma_f32_16x16x32_bf16 v[36:39], v[148:151], v[172:175], v[36:39]
	v_mfma_f32_16x16x32_bf16 v[32:35], v[156:159], v[172:175], v[32:35]
	v_mfma_f32_16x16x32_bf16 v[20:23], v[148:151], v[192:195], v[20:23]
	v_mfma_f32_16x16x32_bf16 v[16:19], v[156:159], v[192:195], v[16:19]
	v_mfma_f32_16x16x32_bf16 v[4:7], v[148:151], v[210:213], v[4:7]
	v_mfma_f32_16x16x32_bf16 v[0:3], v[156:159], v[210:213], v[0:3]
	s_setprio 0
	s_barrier
	s_add_i32 s59, s59, 2
	s_add_u32 s30, s30, 0x100
	s_addc_u32 s31, s31, 0
	s_add_u32 s57, s57, 0x100
	s_addc_u32 s58, s58, 0
	ds_read_b128 v[128:131], v203
	ds_read_b128 v[132:135], v203 offset:1024
	ds_read_b128 v[136:139], v203 offset:2048
	ds_read_b128 v[140:143], v203 offset:3072
	ds_read_b128 v[144:147], v204
	ds_read_b128 v[148:151], v204 offset:1024
	ds_read_b128 v[152:155], v204 offset:2048
	ds_read_b128 v[156:159], v204 offset:3072
	s_add_u32 s34, s30, 0xfffc0080
	s_addc_u32 s35, s31, -1
	s_cmp_eq_u32 s59, 12
	s_cselect_b32 s37, s7, s35
	s_cselect_b32 s36, s19, s34
	s_cselect_b32 s35, s21, s58
	s_cselect_b32 s34, s56, s57
	s_mov_b32 m0, s53
	v_lshl_add_u64 v[214:215], s[30:31], 0, v[184:185]
	ds_read_b128 v[160:163], v205
	ds_read_b128 v[164:167], v205 offset:1024
	ds_read_b128 v[168:171], v205 offset:2048
	ds_read_b128 v[172:175], v205 offset:3072
	ds_read_b128 v[188:191], v205 offset:4096
	ds_read_b128 v[192:195], v205 offset:5120
	ds_read_b128 v[196:199], v205 offset:6144
	ds_read_b128 v[210:213], v205 offset:7168
	global_load_lds_dwordx4 v[214:215], off
	v_lshl_add_u64 v[214:215], s[30:31], 0, v[186:187]
	s_mov_b32 m0, s54
	s_nop 0
	global_load_lds_dwordx4 v[214:215], off
	s_waitcnt vmcnt(10)
	s_waitcnt lgkmcnt(0)
	v_add_f32_e32 v88, v88, v232
	v_add_f32_e32 v89, v89, v233
	v_add_f32_e32 v90, v90, v234
	v_add_f32_e32 v91, v91, v235
	s_add_u32 s68, s70, 0x30000
	s_addc_u32 s69, s71, 0
	global_load_dwordx4 v[232:235], v229, s[68:69]
	s_setprio 1
	s_waitcnt lgkmcnt(0)
	v_mfma_f32_16x16x32_bf16 v[124:127], v[128:131], v[160:163], v[124:127]
	v_mfma_f32_16x16x32_bf16 v[120:123], v[136:139], v[160:163], v[120:123]
	v_mfma_f32_16x16x32_bf16 v[108:111], v[128:131], v[168:171], v[108:111]
	v_mfma_f32_16x16x32_bf16 v[104:107], v[136:139], v[168:171], v[104:107]
	s_barrier
	v_mfma_f32_16x16x32_bf16 v[92:95], v[128:131], v[188:191], v[92:95]
	v_mfma_f32_16x16x32_bf16 v[88:91], v[136:139], v[188:191], v[88:91]
	v_mfma_f32_16x16x32_bf16 v[76:79], v[128:131], v[196:199], v[76:79]
	v_mfma_f32_16x16x32_bf16 v[72:75], v[136:139], v[196:199], v[72:75]
	v_mfma_f32_16x16x32_bf16 v[124:127], v[132:135], v[164:167], v[124:127]
	v_mfma_f32_16x16x32_bf16 v[120:123], v[140:143], v[164:167], v[120:123]
	v_mfma_f32_16x16x32_bf16 v[108:111], v[132:135], v[172:175], v[108:111]
	v_mfma_f32_16x16x32_bf16 v[104:107], v[140:143], v[172:175], v[104:107]
	v_mfma_f32_16x16x32_bf16 v[92:95], v[132:135], v[192:195], v[92:95]
	v_mfma_f32_16x16x32_bf16 v[88:91], v[140:143], v[192:195], v[88:91]
	v_mfma_f32_16x16x32_bf16 v[76:79], v[132:135], v[210:213], v[76:79]
	v_mfma_f32_16x16x32_bf16 v[72:75], v[140:143], v[210:213], v[72:75]
	s_setprio 0
	s_setprio 1
	v_mfma_f32_16x16x32_bf16 v[116:119], v[144:147], v[160:163], v[116:119]
	v_mfma_f32_16x16x32_bf16 v[112:115], v[152:155], v[160:163], v[112:115]
	v_mfma_f32_16x16x32_bf16 v[100:103], v[144:147], v[168:171], v[100:103]
	v_mfma_f32_16x16x32_bf16 v[96:99], v[152:155], v[168:171], v[96:99]
	v_mfma_f32_16x16x32_bf16 v[84:87], v[144:147], v[188:191], v[84:87]
	v_mfma_f32_16x16x32_bf16 v[80:83], v[152:155], v[188:191], v[80:83]
	v_mfma_f32_16x16x32_bf16 v[68:71], v[144:147], v[196:199], v[68:71]
	v_mfma_f32_16x16x32_bf16 v[64:67], v[152:155], v[196:199], v[64:67]
	v_mfma_f32_16x16x32_bf16 v[116:119], v[148:151], v[164:167], v[116:119]
	v_mfma_f32_16x16x32_bf16 v[112:115], v[156:159], v[164:167], v[112:115]
	v_mfma_f32_16x16x32_bf16 v[100:103], v[148:151], v[172:175], v[100:103]
	v_mfma_f32_16x16x32_bf16 v[96:99], v[156:159], v[172:175], v[96:99]
	v_mfma_f32_16x16x32_bf16 v[84:87], v[148:151], v[192:195], v[84:87]
	v_mfma_f32_16x16x32_bf16 v[80:83], v[156:159], v[192:195], v[80:83]
	v_mfma_f32_16x16x32_bf16 v[68:71], v[148:151], v[210:213], v[68:71]
	v_mfma_f32_16x16x32_bf16 v[64:67], v[156:159], v[210:213], v[64:67]
	s_setprio 0
	s_barrier
; #define PG8_STAGE(bufoff, gbase, voff) do { _Pragma("unroll") for (int _i = 0; _i < 2; ++_i) \
;         __builtin_amdgcn_global_load_lds((const unsigned*)((const char*)(gbase) + (voff)[_i]), (LAS unsigned*)(lds + (bufoff) + ldsw + _i * 8192), 16, 0, 0); } while (0)
; #define PG8_LDA(dst, b, h) do { _Pragma("unroll") for (int m = 0; m < 4; ++m) _Pragma("unroll") for (int k = 0; k < 2; ++k) dst[m][k] = *(const LAS bf16x8*)(lds + PG8_SA(b, h) + aoff + m * 2048 + k * 1024); } while (0)
; #define PG8_LDB(dst, b, h) do { _Pragma("unroll") for (int n = 0; n < 2; ++n) _Pragma("unroll") for (int k = 0; k < 2; ++k) dst[n][k] = *(const LAS bf16x8*)(lds + PG8_SB(b, h) + boff + n * 2048 + k * 1024); } while (0)
; template <class Epi, bool ALIGN_EPI, bool SP2>
; __device__ __forceinline__ void gemm_phase(LAS unsigned char* lds, const int K, const Sched& S, const Epi& E) {
;     ...
;             PG8_LDA(At, 0, 1); PG8_STAGE(PG8_SB(0, 0), b2, voffB); PG8_STAGE(PG8_SB(0, 1), b2 + hstep, voffB); PG8_STAGE(PG8_SA(0, 0), a2, voffA);
;             PG8_WAIT_V(8); PG8_WAIT_L(0); PG8_BAR; PG8_MMA(1, 0, At, B0); PG8_MMA(1, 1, At, B1); PG8_BAR; PG8_SCHED;
;             PG8_LDB(B0, 1, 0); PG8_LDB(B1, 1, 1); PG8_SCHED; PG8_LDA(At, 1, 0); PG8_STAGE(PG8_SA(0, 1), a2 + hstep, voffA);
;             PG8_WAIT_V(8); PG8_WAIT_L(0); PG8_BAR; PG8_MMA(0, 0, At, B0); PG8_MMA(0, 1, At, B1); PG8_BAR; PG8_SCHED;
;             PG8_LDA(At, 1, 1); PG8_STAGE(PG8_SB(1, 0), b3, voffB); PG8_STAGE(PG8_SB(1, 1), b3 + hstep, voffB); PG8_STAGE(PG8_SA(1, 0), a3, voffA);
;             PG8_WAIT_V(8); PG8_WAIT_L(0); PG8_BAR; PG8_MMA(1, 0, At, B0); PG8_MMA(1, 1, At, B1); PG8_BAR; PG8_SCHED;
;     __device__ __forceinline__ void operator()(Acc& acc, const Unit& u, int wr, int wc, int fr, int fq) const {
;     ...
;                     for (int bj = 0; bj < 2; ++bj) { const float* p = basef + (size_t)(row0 + ai * HALF + m * 16) * D + col0 + bj * HALF; rx[m][bj][0] = *(const f32x4*)p; rx[m][bj][1] = *(const f32x4*)(p + 4); }
;                 __builtin_amdgcn_sched_barrier(0);
; #pragma unroll
;                 for (int m = 0; m < 4; ++m) { const int row = row0 + ai * HALF + m * 16; const size_t o = (size_t)row * D + col0; float ss = 0.f;
; #pragma unroll
;                     for (int bj = 0; bj < 2; ++bj) { const f32x4 h0 = rx[m][bj][0] + acc[ai][bj][m][0], h1 = rx[m][bj][1] + acc[ai][bj][m][1];
	s_mov_b32 m0, s55
	v_lshl_add_u64 v[214:215], s[34:35], 0, v[178:179]
	ds_read_b128 v[160:163], v205 offset:16384
	ds_read_b128 v[164:167], v205 offset:17408
	ds_read_b128 v[168:171], v205 offset:18432
	ds_read_b128 v[172:175], v205 offset:19456
	ds_read_b128 v[188:191], v205 offset:20480
	ds_read_b128 v[192:195], v205 offset:21504
	ds_read_b128 v[196:199], v205 offset:22528
	ds_read_b128 v[210:213], v205 offset:23552
	global_load_lds_dwordx4 v[214:215], off
	s_add_i32 m0, s55, 0x2000
	s_add_u32 s60, s34, 0x40000
	v_lshl_add_u64 v[216:217], s[34:35], 0, v[182:183]
	s_addc_u32 s61, s35, 0
	s_add_i32 s62, s51, s42
	global_load_lds_dwordx4 v[216:217], off
	v_lshl_add_u64 v[218:219], s[60:61], 0, v[178:179]
	s_mov_b32 m0, s62
	v_lshl_add_u64 v[220:221], s[36:37], 0, v[180:181]
	global_load_lds_dwordx4 v[218:219], off
	v_lshl_add_u64 v[218:219], s[60:61], 0, v[182:183]
	s_add_i32 m0, s62, 0x2000
	s_nop 0
	global_load_lds_dwordx4 v[218:219], off
	v_lshl_add_u64 v[218:219], s[36:37], 0, v[176:177]
	s_mov_b32 m0, s29
	s_nop 0
	global_load_lds_dwordx4 v[218:219], off
	s_mov_b32 m0, s43
	s_nop 0
	global_load_lds_dwordx4 v[220:221], off
	s_waitcnt vmcnt(10)
	s_waitcnt lgkmcnt(0)
	v_add_f32_e32 v84, v84, v236
	v_add_f32_e32 v85, v85, v237
	v_add_f32_e32 v86, v86, v238
	v_add_f32_e32 v87, v87, v239
	global_load_dwordx4 v[236:239], v229, s[68:69] offset:16
	s_setprio 1
	s_waitcnt lgkmcnt(0)
	v_mfma_f32_16x16x32_bf16 v[60:63], v[128:131], v[160:163], v[60:63]
	v_mfma_f32_16x16x32_bf16 v[56:59], v[136:139], v[160:163], v[56:59]
	v_mfma_f32_16x16x32_bf16 v[44:47], v[128:131], v[168:171], v[44:47]
	v_mfma_f32_16x16x32_bf16 v[40:43], v[136:139], v[168:171], v[40:43]
	s_barrier
	v_mfma_f32_16x16x32_bf16 v[28:31], v[128:131], v[188:191], v[28:31]
	v_mfma_f32_16x16x32_bf16 v[24:27], v[136:139], v[188:191], v[24:27]
	v_mfma_f32_16x16x32_bf16 v[12:15], v[128:131], v[196:199], v[12:15]
	v_mfma_f32_16x16x32_bf16 v[8:11], v[136:139], v[196:199], v[8:11]
	v_mfma_f32_16x16x32_bf16 v[60:63], v[132:135], v[164:167], v[60:63]
	v_mfma_f32_16x16x32_bf16 v[56:59], v[140:143], v[164:167], v[56:59]
	v_mfma_f32_16x16x32_bf16 v[44:47], v[132:135], v[172:175], v[44:47]
	v_mfma_f32_16x16x32_bf16 v[40:43], v[140:143], v[172:175], v[40:43]
	v_mfma_f32_16x16x32_bf16 v[28:31], v[132:135], v[192:195], v[28:31]
	v_mfma_f32_16x16x32_bf16 v[24:27], v[140:143], v[192:195], v[24:27]
	v_mfma_f32_16x16x32_bf16 v[12:15], v[132:135], v[210:213], v[12:15]
	v_mfma_f32_16x16x32_bf16 v[8:11], v[140:143], v[210:213], v[8:11]
	s_setprio 0
	s_setprio 1
	v_mfma_f32_16x16x32_bf16 v[52:55], v[144:147], v[160:163], v[52:55]
	v_mfma_f32_16x16x32_bf16 v[48:51], v[152:155], v[160:163], v[48:51]
	v_mfma_f32_16x16x32_bf16 v[36:39], v[144:147], v[168:171], v[36:39]
	v_mfma_f32_16x16x32_bf16 v[32:35], v[152:155], v[168:171], v[32:35]
	v_mfma_f32_16x16x32_bf16 v[20:23], v[144:147], v[188:191], v[20:23]
	v_mfma_f32_16x16x32_bf16 v[16:19], v[152:155], v[188:191], v[16:19]
	v_mfma_f32_16x16x32_bf16 v[4:7], v[144:147], v[196:199], v[4:7]
	v_mfma_f32_16x16x32_bf16 v[0:3], v[152:155], v[196:199], v[0:3]
	v_mfma_f32_16x16x32_bf16 v[52:55], v[148:151], v[164:167], v[52:55]
	v_mfma_f32_16x16x32_bf16 v[48:51], v[156:159], v[164:167], v[48:51]
	v_mfma_f32_16x16x32_bf16 v[36:39], v[148:151], v[172:175], v[36:39]
	v_mfma_f32_16x16x32_bf16 v[32:35], v[156:159], v[172:175], v[32:35]
	v_mfma_f32_16x16x32_bf16 v[20:23], v[148:151], v[192:195], v[20:23]
	v_mfma_f32_16x16x32_bf16 v[16:19], v[156:159], v[192:195], v[16:19]
	v_mfma_f32_16x16x32_bf16 v[4:7], v[148:151], v[210:213], v[4:7]
	v_mfma_f32_16x16x32_bf16 v[0:3], v[156:159], v[210:213], v[0:3]
	s_setprio 0
	s_barrier
	s_add_i32 s60, 0, 0x18000
	s_add_i32 s61, 0, 0x1c000
	v_add_u32_e32 v140, s60, v202
	v_add_u32_e32 v156, s61, v202
	ds_read_b128 v[128:131], v140
	ds_read_b128 v[132:135], v140 offset:1024
	ds_read_b128 v[136:139], v140 offset:2048
	ds_read_b128 v[140:143], v140 offset:3072
	ds_read_b128 v[144:147], v156
	ds_read_b128 v[148:151], v156 offset:1024
	ds_read_b128 v[152:155], v156 offset:2048
	ds_read_b128 v[156:159], v156 offset:3072
	s_add_u32 s36, s36, 0x40000
	s_addc_u32 s37, s37, 0
	s_mov_b32 m0, s44
	v_lshl_add_u64 v[222:223], s[36:37], 0, v[176:177]
	ds_read_b128 v[160:163], v205 offset:32768
	ds_read_b128 v[164:167], v205 offset:33792
	ds_read_b128 v[168:171], v205 offset:34816
	ds_read_b128 v[172:175], v205 offset:35840
	ds_read_b128 v[188:191], v205 offset:36864
	ds_read_b128 v[192:195], v205 offset:37888
	ds_read_b128 v[196:199], v205 offset:38912
	ds_read_b128 v[210:213], v205 offset:39936
	global_load_lds_dwordx4 v[222:223], off
	v_lshl_add_u64 v[222:223], s[36:37], 0, v[180:181]
	s_mov_b32 m0, s45
	s_nop 0
	global_load_lds_dwordx4 v[222:223], off
	s_waitcnt vmcnt(10)
	s_waitcnt lgkmcnt(0)
	v_add_f32_e32 v80, v80, v240
	v_add_f32_e32 v81, v81, v241
	v_add_f32_e32 v82, v82, v242
	v_add_f32_e32 v83, v83, v243
	global_load_dwordx4 v[240:243], v229, s[68:69] offset:512
	s_setprio 1
	s_waitcnt lgkmcnt(0)
	v_mfma_f32_16x16x32_bf16 v[124:127], v[128:131], v[160:163], v[124:127]
	v_mfma_f32_16x16x32_bf16 v[120:123], v[136:139], v[160:163], v[120:123]
	v_mfma_f32_16x16x32_bf16 v[108:111], v[128:131], v[168:171], v[108:111]
	v_mfma_f32_16x16x32_bf16 v[104:107], v[136:139], v[168:171], v[104:107]
	s_barrier
; #define PG8_STAGE(bufoff, gbase, voff) do { _Pragma("unroll") for (int _i = 0; _i < 2; ++_i) \
;         __builtin_amdgcn_global_load_lds((const unsigned*)((const char*)(gbase) + (voff)[_i]), (LAS unsigned*)(lds + (bufoff) + ldsw + _i * 8192), 16, 0, 0); } while (0)
; #define PG8_LDA(dst, b, h) do { _Pragma("unroll") for (int m = 0; m < 4; ++m) _Pragma("unroll") for (int k = 0; k < 2; ++k) dst[m][k] = *(const LAS bf16x8*)(lds + PG8_SA(b, h) + aoff + m * 2048 + k * 1024); } while (0)
; #define PG8_MMA(ai, bj, At, Bt) do { __builtin_amdgcn_s_setprio(1); _Pragma("unroll") for (int m = 0; m < 4; ++m) _Pragma("unroll") for (int n = 0; n < 2; ++n) _Pragma("unroll") for (int k = 0; k < 2; ++k) \
;         acc[ai][bj][m][n] = __builtin_amdgcn_mfma_f32_16x16x32_bf16(Bt[n][k], At[m][k], acc[ai][bj][m][n], 0, 0, 0); __builtin_amdgcn_s_setprio(0); } while (0)
; #define PG8_WAIT_V(n) asm volatile("s_waitcnt vmcnt(" #n ")" ::: "memory")
; #define PG8_WAIT_L(n) asm volatile("s_waitcnt lgkmcnt(" #n ")" ::: "memory")
; #define PG8_BAR __builtin_amdgcn_s_barrier()
; #define PG8_SCHED __builtin_amdgcn_sched_barrier(0)
; template <class Epi, bool ALIGN_EPI, bool SP2>
; __device__ __forceinline__ void gemm_phase(LAS unsigned char* lds, const int K, const Sched& S, const Epi& E) {
;     ...
;             PG8_WAIT_V(8); PG8_WAIT_L(0); PG8_BAR; PG8_MMA(0, 0, At, B0); PG8_MMA(0, 1, At, B1); PG8_BAR; PG8_SCHED;
;             PG8_LDA(At, 1, 1); PG8_STAGE(PG8_SB(1, 0), b3, voffB); PG8_STAGE(PG8_SB(1, 1), b3 + hstep, voffB); PG8_STAGE(PG8_SA(1, 0), a3, voffA);
;             PG8_WAIT_V(8); PG8_WAIT_L(0); PG8_BAR; PG8_MMA(1, 0, At, B0); PG8_MMA(1, 1, At, B1); PG8_BAR; PG8_SCHED;
;     __device__ __forceinline__ void operator()(Acc& acc, const Unit& u, int wr, int wc, int fr, int fq) const {
;     ...
;                     for (int bj = 0; bj < 2; ++bj) { const float* p = basef + (size_t)(row0 + ai * HALF + m * 16) * D + col0 + bj * HALF; rx[m][bj][0] = *(const f32x4*)p; rx[m][bj][1] = *(const f32x4*)(p + 4); }
;                 __builtin_amdgcn_sched_barrier(0);
; #pragma unroll
;                 for (int m = 0; m < 4; ++m) { const int row = row0 + ai * HALF + m * 16; const size_t o = (size_t)row * D + col0; float ss = 0.f;
; #pragma unroll
;                     for (int bj = 0; bj < 2; ++bj) { const f32x4 h0 = rx[m][bj][0] + acc[ai][bj][m][0], h1 = rx[m][bj][1] + acc[ai][bj][m][1];
	v_mfma_f32_16x16x32_bf16 v[92:95], v[128:131], v[188:191], v[92:95]
	v_mfma_f32_16x16x32_bf16 v[88:91], v[136:139], v[188:191], v[88:91]
	v_mfma_f32_16x16x32_bf16 v[76:79], v[128:131], v[196:199], v[76:79]
	v_mfma_f32_16x16x32_bf16 v[72:75], v[136:139], v[196:199], v[72:75]
	v_mfma_f32_16x16x32_bf16 v[124:127], v[132:135], v[164:167], v[124:127]
	v_mfma_f32_16x16x32_bf16 v[120:123], v[140:143], v[164:167], v[120:123]
	v_mfma_f32_16x16x32_bf16 v[108:111], v[132:135], v[172:175], v[108:111]
	v_mfma_f32_16x16x32_bf16 v[104:107], v[140:143], v[172:175], v[104:107]
	v_mfma_f32_16x16x32_bf16 v[92:95], v[132:135], v[192:195], v[92:95]
	v_mfma_f32_16x16x32_bf16 v[88:91], v[140:143], v[192:195], v[88:91]
	v_mfma_f32_16x16x32_bf16 v[76:79], v[132:135], v[210:213], v[76:79]
	v_mfma_f32_16x16x32_bf16 v[72:75], v[140:143], v[210:213], v[72:75]
	s_setprio 0
	s_setprio 1
	v_mfma_f32_16x16x32_bf16 v[116:119], v[144:147], v[160:163], v[116:119]
	v_mfma_f32_16x16x32_bf16 v[112:115], v[152:155], v[160:163], v[112:115]
	v_mfma_f32_16x16x32_bf16 v[100:103], v[144:147], v[168:171], v[100:103]
	v_mfma_f32_16x16x32_bf16 v[96:99], v[152:155], v[168:171], v[96:99]
	v_mfma_f32_16x16x32_bf16 v[84:87], v[144:147], v[188:191], v[84:87]
	v_mfma_f32_16x16x32_bf16 v[80:83], v[152:155], v[188:191], v[80:83]
	v_mfma_f32_16x16x32_bf16 v[68:71], v[144:147], v[196:199], v[68:71]
	v_mfma_f32_16x16x32_bf16 v[64:67], v[152:155], v[196:199], v[64:67]
	v_mfma_f32_16x16x32_bf16 v[116:119], v[148:151], v[164:167], v[116:119]
	v_mfma_f32_16x16x32_bf16 v[112:115], v[156:159], v[164:167], v[112:115]
	v_mfma_f32_16x16x32_bf16 v[100:103], v[148:151], v[172:175], v[100:103]
	v_mfma_f32_16x16x32_bf16 v[96:99], v[156:159], v[172:175], v[96:99]
	v_mfma_f32_16x16x32_bf16 v[84:87], v[148:151], v[192:195], v[84:87]
	v_mfma_f32_16x16x32_bf16 v[80:83], v[156:159], v[192:195], v[80:83]
	v_mfma_f32_16x16x32_bf16 v[68:71], v[148:151], v[210:213], v[68:71]
	v_mfma_f32_16x16x32_bf16 v[64:67], v[156:159], v[210:213], v[64:67]
	s_setprio 0
	s_barrier
	s_add_i32 s36, s60, s42
	v_lshl_add_u64 v[214:215], v[214:215], 0, s[14:15]
	s_mov_b32 m0, s36
	ds_read_b128 v[160:163], v205 offset:49152
	ds_read_b128 v[164:167], v205 offset:50176
	ds_read_b128 v[168:171], v205 offset:51200
	ds_read_b128 v[172:175], v205 offset:52224
	ds_read_b128 v[188:191], v205 offset:53248
	ds_read_b128 v[192:195], v205 offset:54272
	ds_read_b128 v[196:199], v205 offset:55296
	ds_read_b128 v[210:213], v205 offset:56320
	global_load_lds_dwordx4 v[214:215], off
	s_add_i32 m0, s36, 0x2000
	s_add_u32 s34, s34, 0x40080
	v_lshl_add_u64 v[214:215], v[216:217], 0, s[14:15]
	s_addc_u32 s35, s35, 0
	s_add_i32 s36, s61, s42
	global_load_lds_dwordx4 v[214:215], off
	v_lshl_add_u64 v[214:215], s[34:35], 0, v[178:179]
	s_mov_b32 m0, s36
	s_nop 0
	global_load_lds_dwordx4 v[214:215], off
	v_lshl_add_u64 v[214:215], s[34:35], 0, v[182:183]
	s_add_i32 m0, s36, 0x2000
	s_nop 0
	global_load_lds_dwordx4 v[214:215], off
	v_lshl_add_u64 v[214:215], v[218:219], 0, s[14:15]
	s_mov_b32 m0, s49
	s_nop 0
	global_load_lds_dwordx4 v[214:215], off
	v_lshl_add_u64 v[214:215], v[220:221], 0, s[14:15]
	s_mov_b32 m0, s50
	s_nop 0
	global_load_lds_dwordx4 v[214:215], off
	s_waitcnt vmcnt(10)
	s_waitcnt lgkmcnt(0)
	v_add_f32_e32 v76, v76, v232
	v_add_f32_e32 v77, v77, v233
	v_add_f32_e32 v78, v78, v234
	v_add_f32_e32 v79, v79, v235
	global_load_dwordx4 v[232:235], v229, s[68:69] offset:528
	s_setprio 1
	s_waitcnt lgkmcnt(0)
	v_mfma_f32_16x16x32_bf16 v[60:63], v[128:131], v[160:163], v[60:63]
	v_mfma_f32_16x16x32_bf16 v[56:59], v[136:139], v[160:163], v[56:59]
	v_mfma_f32_16x16x32_bf16 v[44:47], v[128:131], v[168:171], v[44:47]
	v_mfma_f32_16x16x32_bf16 v[40:43], v[136:139], v[168:171], v[40:43]
	s_barrier
	v_mfma_f32_16x16x32_bf16 v[28:31], v[128:131], v[188:191], v[28:31]
	v_mfma_f32_16x16x32_bf16 v[24:27], v[136:139], v[188:191], v[24:27]
	v_mfma_f32_16x16x32_bf16 v[12:15], v[128:131], v[196:199], v[12:15]
	v_mfma_f32_16x16x32_bf16 v[8:11], v[136:139], v[196:199], v[8:11]
	v_mfma_f32_16x16x32_bf16 v[60:63], v[132:135], v[164:167], v[60:63]
	v_mfma_f32_16x16x32_bf16 v[56:59], v[140:143], v[164:167], v[56:59]
	v_mfma_f32_16x16x32_bf16 v[44:47], v[132:135], v[172:175], v[44:47]
	v_mfma_f32_16x16x32_bf16 v[40:43], v[140:143], v[172:175], v[40:43]
	v_mfma_f32_16x16x32_bf16 v[28:31], v[132:135], v[192:195], v[28:31]
	v_mfma_f32_16x16x32_bf16 v[24:27], v[140:143], v[192:195], v[24:27]
	v_mfma_f32_16x16x32_bf16 v[12:15], v[132:135], v[210:213], v[12:15]
	v_mfma_f32_16x16x32_bf16 v[8:11], v[140:143], v[210:213], v[8:11]
	s_setprio 0
	s_setprio 1
	v_mfma_f32_16x16x32_bf16 v[52:55], v[144:147], v[160:163], v[52:55]
	v_mfma_f32_16x16x32_bf16 v[48:51], v[152:155], v[160:163], v[48:51]
	v_mfma_f32_16x16x32_bf16 v[36:39], v[144:147], v[168:171], v[36:39]
	v_mfma_f32_16x16x32_bf16 v[32:35], v[152:155], v[168:171], v[32:35]
	v_mfma_f32_16x16x32_bf16 v[20:23], v[144:147], v[188:191], v[20:23]
	v_mfma_f32_16x16x32_bf16 v[16:19], v[152:155], v[188:191], v[16:19]
	v_mfma_f32_16x16x32_bf16 v[4:7], v[144:147], v[196:199], v[4:7]
	v_mfma_f32_16x16x32_bf16 v[0:3], v[152:155], v[196:199], v[0:3]
	v_mfma_f32_16x16x32_bf16 v[52:55], v[148:151], v[164:167], v[52:55]
	v_mfma_f32_16x16x32_bf16 v[48:51], v[156:159], v[164:167], v[48:51]
	v_mfma_f32_16x16x32_bf16 v[36:39], v[148:151], v[172:175], v[36:39]
	v_mfma_f32_16x16x32_bf16 v[32:35], v[156:159], v[172:175], v[32:35]
	v_mfma_f32_16x16x32_bf16 v[20:23], v[148:151], v[192:195], v[20:23]
	v_mfma_f32_16x16x32_bf16 v[16:19], v[156:159], v[192:195], v[16:19]
	v_mfma_f32_16x16x32_bf16 v[4:7], v[148:151], v[210:213], v[4:7]
	v_mfma_f32_16x16x32_bf16 v[0:3], v[156:159], v[210:213], v[0:3]
	s_setprio 0
	s_barrier
; #define PG8_STAGE(bufoff, gbase, voff) do { _Pragma("unroll") for (int _i = 0; _i < 2; ++_i) \
;         __builtin_amdgcn_global_load_lds((const unsigned*)((const char*)(gbase) + (voff)[_i]), (LAS unsigned*)(lds + (bufoff) + ldsw + _i * 8192), 16, 0, 0); } while (0)
; #define PG8_WAIT_V(n) asm volatile("s_waitcnt vmcnt(" #n ")" ::: "memory")
; template <class Epi, bool ALIGN_EPI, bool SP2>
; __device__ __forceinline__ void gemm_phase(LAS unsigned char* lds, const int K, const Sched& S, const Epi& E) {
;     ...
;         for (int t = 0; t < nt; t += 2) {
;             const bool last = (t == nt - 2);
;             const char* a1 = cA + (size_t)(t + 1) * kstep;
;             const char* a2 = last ? nA : cA + (size_t)(t + 2) * kstep; const char* b2 = last ? nB : cB + (size_t)(t + 2) * kstep;
;             const char* a3 = a2 + kstep; const char* b3 = b2 + kstep;
;             if constexpr (SP2) {
;             PG8_LDB(B0, 0, 0); PG8_LDB(B1, 0, 1); PG8_SCHED; PG8_LDA(At, 0, 0); PG8_STAGE(PG8_SA(1, 1), a1 + hstep, voffA);
;             PG8_WAIT_V(8); PG8_WAIT_L(0); PG8_BAR; PG8_MMA(0, 0, At, B0); PG8_MMA(0, 1, At, B1); PG8_BAR; PG8_SCHED;
;             PG8_LDA(At, 0, 1); PG8_STAGE(PG8_SB(0, 0), b2, voffB); PG8_STAGE(PG8_SB(0, 1), b2 + hstep, voffB); PG8_STAGE(PG8_SA(0, 0), a2, voffA);
;             PG8_WAIT_V(8); PG8_WAIT_L(0); PG8_BAR; PG8_MMA(1, 0, At, B0); PG8_MMA(1, 1, At, B1); PG8_BAR; PG8_SCHED;
;             PG8_LDB(B0, 1, 0); PG8_LDB(B1, 1, 1); PG8_SCHED; PG8_LDA(At, 1, 0); PG8_STAGE(PG8_SA(0, 1), a2 + hstep, voffA);
;             PG8_WAIT_V(8); PG8_WAIT_L(0); PG8_BAR; PG8_MMA(0, 0, At, B0); PG8_MMA(0, 1, At, B1); PG8_BAR; PG8_SCHED;
;     __device__ __forceinline__ void operator()(Acc& acc, const Unit& u, int wr, int wc, int fr, int fq) const {
;     ...
;                     for (int bj = 0; bj < 2; ++bj) { const float* p = basef + (size_t)(row0 + ai * HALF + m * 16) * D + col0 + bj * HALF; rx[m][bj][0] = *(const f32x4*)p; rx[m][bj][1] = *(const f32x4*)(p + 4); }
;                 __builtin_amdgcn_sched_barrier(0);
; #pragma unroll
;                 for (int m = 0; m < 4; ++m) { const int row = row0 + ai * HALF + m * 16; const size_t o = (size_t)row * D + col0; float ss = 0.f;
; #pragma unroll
;                     for (int bj = 0; bj < 2; ++bj) { const f32x4 h0 = rx[m][bj][0] + acc[ai][bj][m][0], h1 = rx[m][bj][1] + acc[ai][bj][m][1];
	s_add_i32 s59, s59, 2
	s_add_u32 s30, s30, 0x100
	s_addc_u32 s31, s31, 0
	s_add_u32 s57, s57, 0x100
	s_addc_u32 s58, s58, 0
	ds_read_b128 v[128:131], v203
	ds_read_b128 v[132:135], v203 offset:1024
	ds_read_b128 v[136:139], v203 offset:2048
	ds_read_b128 v[140:143], v203 offset:3072
	ds_read_b128 v[144:147], v204
	ds_read_b128 v[148:151], v204 offset:1024
	ds_read_b128 v[152:155], v204 offset:2048
	ds_read_b128 v[156:159], v204 offset:3072
	s_add_u32 s34, s30, 0xfffc0080
	s_addc_u32 s35, s31, -1
	s_cmp_eq_u32 s59, 12
	s_cselect_b32 s37, s7, s35
	s_cselect_b32 s36, s19, s34
	s_cselect_b32 s35, s21, s58
	s_cselect_b32 s34, s56, s57
	s_mov_b32 m0, s53
	v_lshl_add_u64 v[214:215], s[30:31], 0, v[184:185]
	ds_read_b128 v[160:163], v205
	ds_read_b128 v[164:167], v205 offset:1024
	ds_read_b128 v[168:171], v205 offset:2048
	ds_read_b128 v[172:175], v205 offset:3072
	ds_read_b128 v[188:191], v205 offset:4096
	ds_read_b128 v[192:195], v205 offset:5120
	ds_read_b128 v[196:199], v205 offset:6144
	ds_read_b128 v[210:213], v205 offset:7168
	global_load_lds_dwordx4 v[214:215], off
	v_lshl_add_u64 v[214:215], s[30:31], 0, v[186:187]
	s_mov_b32 m0, s54
	s_nop 0
	global_load_lds_dwordx4 v[214:215], off
	s_waitcnt vmcnt(10)
	s_waitcnt lgkmcnt(0)
	v_add_f32_e32 v72, v72, v236
	v_add_f32_e32 v73, v73, v237
	v_add_f32_e32 v74, v74, v238
	v_add_f32_e32 v75, v75, v239
	s_add_u32 s68, s70, 0x80000
	s_addc_u32 s69, s71, 0
	global_load_dwordx4 v[236:239], v229, s[68:69]
	s_setprio 1
	s_waitcnt lgkmcnt(0)
	v_mfma_f32_16x16x32_bf16 v[124:127], v[128:131], v[160:163], v[124:127]
	v_mfma_f32_16x16x32_bf16 v[120:123], v[136:139], v[160:163], v[120:123]
	v_mfma_f32_16x16x32_bf16 v[108:111], v[128:131], v[168:171], v[108:111]
	v_mfma_f32_16x16x32_bf16 v[104:107], v[136:139], v[168:171], v[104:107]
	s_barrier
	v_mfma_f32_16x16x32_bf16 v[92:95], v[128:131], v[188:191], v[92:95]
	v_mfma_f32_16x16x32_bf16 v[88:91], v[136:139], v[188:191], v[88:91]
	v_mfma_f32_16x16x32_bf16 v[76:79], v[128:131], v[196:199], v[76:79]
	v_mfma_f32_16x16x32_bf16 v[72:75], v[136:139], v[196:199], v[72:75]
	v_mfma_f32_16x16x32_bf16 v[124:127], v[132:135], v[164:167], v[124:127]
	v_mfma_f32_16x16x32_bf16 v[120:123], v[140:143], v[164:167], v[120:123]
	v_mfma_f32_16x16x32_bf16 v[108:111], v[132:135], v[172:175], v[108:111]
	v_mfma_f32_16x16x32_bf16 v[104:107], v[140:143], v[172:175], v[104:107]
	v_mfma_f32_16x16x32_bf16 v[92:95], v[132:135], v[192:195], v[92:95]
	v_mfma_f32_16x16x32_bf16 v[88:91], v[140:143], v[192:195], v[88:91]
	v_mfma_f32_16x16x32_bf16 v[76:79], v[132:135], v[210:213], v[76:79]
	v_mfma_f32_16x16x32_bf16 v[72:75], v[140:143], v[210:213], v[72:75]
	s_setprio 0
	s_setprio 1
	v_mfma_f32_16x16x32_bf16 v[116:119], v[144:147], v[160:163], v[116:119]
	v_mfma_f32_16x16x32_bf16 v[112:115], v[152:155], v[160:163], v[112:115]
	v_mfma_f32_16x16x32_bf16 v[100:103], v[144:147], v[168:171], v[100:103]
	v_mfma_f32_16x16x32_bf16 v[96:99], v[152:155], v[168:171], v[96:99]
	v_mfma_f32_16x16x32_bf16 v[84:87], v[144:147], v[188:191], v[84:87]
	v_mfma_f32_16x16x32_bf16 v[80:83], v[152:155], v[188:191], v[80:83]
	v_mfma_f32_16x16x32_bf16 v[68:71], v[144:147], v[196:199], v[68:71]
	v_mfma_f32_16x16x32_bf16 v[64:67], v[152:155], v[196:199], v[64:67]
	v_mfma_f32_16x16x32_bf16 v[116:119], v[148:151], v[164:167], v[116:119]
	v_mfma_f32_16x16x32_bf16 v[112:115], v[156:159], v[164:167], v[112:115]
	v_mfma_f32_16x16x32_bf16 v[100:103], v[148:151], v[172:175], v[100:103]
	v_mfma_f32_16x16x32_bf16 v[96:99], v[156:159], v[172:175], v[96:99]
	v_mfma_f32_16x16x32_bf16 v[84:87], v[148:151], v[192:195], v[84:87]
	v_mfma_f32_16x16x32_bf16 v[80:83], v[156:159], v[192:195], v[80:83]
	v_mfma_f32_16x16x32_bf16 v[68:71], v[148:151], v[210:213], v[68:71]
	v_mfma_f32_16x16x32_bf16 v[64:67], v[156:159], v[210:213], v[64:67]
	s_setprio 0
	s_barrier
	s_mov_b32 m0, s55
	v_lshl_add_u64 v[214:215], s[34:35], 0, v[178:179]
	ds_read_b128 v[160:163], v205 offset:16384
	ds_read_b128 v[164:167], v205 offset:17408
	ds_read_b128 v[168:171], v205 offset:18432
	ds_read_b128 v[172:175], v205 offset:19456
	ds_read_b128 v[188:191], v205 offset:20480
	ds_read_b128 v[192:195], v205 offset:21504
	ds_read_b128 v[196:199], v205 offset:22528
	ds_read_b128 v[210:213], v205 offset:23552
	global_load_lds_dwordx4 v[214:215], off
	s_add_i32 m0, s55, 0x2000
	s_add_u32 s60, s34, 0x40000
	v_lshl_add_u64 v[216:217], s[34:35], 0, v[182:183]
	s_addc_u32 s61, s35, 0
	s_add_i32 s62, s51, s42
	global_load_lds_dwordx4 v[216:217], off
	v_lshl_add_u64 v[218:219], s[60:61], 0, v[178:179]
	s_mov_b32 m0, s62
	v_lshl_add_u64 v[220:221], s[36:37], 0, v[180:181]
	global_load_lds_dwordx4 v[218:219], off
	v_lshl_add_u64 v[218:219], s[60:61], 0, v[182:183]
	s_add_i32 m0, s62, 0x2000
	s_nop 0
	global_load_lds_dwordx4 v[218:219], off
	v_lshl_add_u64 v[218:219], s[36:37], 0, v[176:177]
	s_mov_b32 m0, s29
	s_nop 0
	global_load_lds_dwordx4 v[218:219], off
	s_mov_b32 m0, s43
	s_nop 0
	global_load_lds_dwordx4 v[220:221], off
	s_waitcnt vmcnt(10)
	s_waitcnt lgkmcnt(0)
	v_add_f32_e32 v68, v68, v240
	v_add_f32_e32 v69, v69, v241
	v_add_f32_e32 v70, v70, v242
	v_add_f32_e32 v71, v71, v243
	global_load_dwordx4 v[240:243], v229, s[68:69] offset:16
	s_setprio 1
	s_waitcnt lgkmcnt(0)
	v_mfma_f32_16x16x32_bf16 v[60:63], v[128:131], v[160:163], v[60:63]
	v_mfma_f32_16x16x32_bf16 v[56:59], v[136:139], v[160:163], v[56:59]
	v_mfma_f32_16x16x32_bf16 v[44:47], v[128:131], v[168:171], v[44:47]
	v_mfma_f32_16x16x32_bf16 v[40:43], v[136:139], v[168:171], v[40:43]
	s_barrier
; #define PG8_STAGE(bufoff, gbase, voff) do { _Pragma("unroll") for (int _i = 0; _i < 2; ++_i) \
;         __builtin_amdgcn_global_load_lds((const unsigned*)((const char*)(gbase) + (voff)[_i]), (LAS unsigned*)(lds + (bufoff) + ldsw + _i * 8192), 16, 0, 0); } while (0)
; #define PG8_LDA(dst, b, h) do { _Pragma("unroll") for (int m = 0; m < 4; ++m) _Pragma("unroll") for (int k = 0; k < 2; ++k) dst[m][k] = *(const LAS bf16x8*)(lds + PG8_SA(b, h) + aoff + m * 2048 + k * 1024); } while (0)
; #define PG8_LDB(dst, b, h) do { _Pragma("unroll") for (int n = 0; n < 2; ++n) _Pragma("unroll") for (int k = 0; k < 2; ++k) dst[n][k] = *(const LAS bf16x8*)(lds + PG8_SB(b, h) + boff + n * 2048 + k * 1024); } while (0)
; template <class Epi, bool ALIGN_EPI, bool SP2>
; __device__ __forceinline__ void gemm_phase(LAS unsigned char* lds, const int K, const Sched& S, const Epi& E) {
;     ...
;             PG8_LDA(At, 0, 1); PG8_STAGE(PG8_SB(0, 0), b2, voffB); PG8_STAGE(PG8_SB(0, 1), b2 + hstep, voffB); PG8_STAGE(PG8_SA(0, 0), a2, voffA);
;             PG8_WAIT_V(8); PG8_WAIT_L(0); PG8_BAR; PG8_MMA(1, 0, At, B0); PG8_MMA(1, 1, At, B1); PG8_BAR; PG8_SCHED;
;             PG8_LDB(B0, 1, 0); PG8_LDB(B1, 1, 1); PG8_SCHED; PG8_LDA(At, 1, 0); PG8_STAGE(PG8_SA(0, 1), a2 + hstep, voffA);
;             PG8_WAIT_V(8); PG8_WAIT_L(0); PG8_BAR; PG8_MMA(0, 0, At, B0); PG8_MMA(0, 1, At, B1); PG8_BAR; PG8_SCHED;
;             PG8_LDA(At, 1, 1); PG8_STAGE(PG8_SB(1, 0), b3, voffB); PG8_STAGE(PG8_SB(1, 1), b3 + hstep, voffB); PG8_STAGE(PG8_SA(1, 0), a3, voffA);
;             PG8_WAIT_V(8); PG8_WAIT_L(0); PG8_BAR; PG8_MMA(1, 0, At, B0); PG8_MMA(1, 1, At, B1); PG8_BAR; PG8_SCHED;
;     __device__ __forceinline__ void operator()(Acc& acc, const Unit& u, int wr, int wc, int fr, int fq) const {
;     ...
;                     for (int bj = 0; bj < 2; ++bj) { const float* p = basef + (size_t)(row0 + ai * HALF + m * 16) * D + col0 + bj * HALF; rx[m][bj][0] = *(const f32x4*)p; rx[m][bj][1] = *(const f32x4*)(p + 4); }
;                 __builtin_amdgcn_sched_barrier(0);
; #pragma unroll
;                 for (int m = 0; m < 4; ++m) { const int row = row0 + ai * HALF + m * 16; const size_t o = (size_t)row * D + col0; float ss = 0.f;
; #pragma unroll
;                     for (int bj = 0; bj < 2; ++bj) { const f32x4 h0 = rx[m][bj][0] + acc[ai][bj][m][0], h1 = rx[m][bj][1] + acc[ai][bj][m][1];
	v_mfma_f32_16x16x32_bf16 v[28:31], v[128:131], v[188:191], v[28:31]
	v_mfma_f32_16x16x32_bf16 v[24:27], v[136:139], v[188:191], v[24:27]
	v_mfma_f32_16x16x32_bf16 v[12:15], v[128:131], v[196:199], v[12:15]
	v_mfma_f32_16x16x32_bf16 v[8:11], v[136:139], v[196:199], v[8:11]
	v_mfma_f32_16x16x32_bf16 v[60:63], v[132:135], v[164:167], v[60:63]
	v_mfma_f32_16x16x32_bf16 v[56:59], v[140:143], v[164:167], v[56:59]
	v_mfma_f32_16x16x32_bf16 v[44:47], v[132:135], v[172:175], v[44:47]
	v_mfma_f32_16x16x32_bf16 v[40:43], v[140:143], v[172:175], v[40:43]
	v_mfma_f32_16x16x32_bf16 v[28:31], v[132:135], v[192:195], v[28:31]
	v_mfma_f32_16x16x32_bf16 v[24:27], v[140:143], v[192:195], v[24:27]
	v_mfma_f32_16x16x32_bf16 v[12:15], v[132:135], v[210:213], v[12:15]
	v_mfma_f32_16x16x32_bf16 v[8:11], v[140:143], v[210:213], v[8:11]
	s_setprio 0
	s_setprio 1
	v_mfma_f32_16x16x32_bf16 v[52:55], v[144:147], v[160:163], v[52:55]
	v_mfma_f32_16x16x32_bf16 v[48:51], v[152:155], v[160:163], v[48:51]
	v_mfma_f32_16x16x32_bf16 v[36:39], v[144:147], v[168:171], v[36:39]
	v_mfma_f32_16x16x32_bf16 v[32:35], v[152:155], v[168:171], v[32:35]
	v_mfma_f32_16x16x32_bf16 v[20:23], v[144:147], v[188:191], v[20:23]
	v_mfma_f32_16x16x32_bf16 v[16:19], v[152:155], v[188:191], v[16:19]
	v_mfma_f32_16x16x32_bf16 v[4:7], v[144:147], v[196:199], v[4:7]
	v_mfma_f32_16x16x32_bf16 v[0:3], v[152:155], v[196:199], v[0:3]
	v_mfma_f32_16x16x32_bf16 v[52:55], v[148:151], v[164:167], v[52:55]
	v_mfma_f32_16x16x32_bf16 v[48:51], v[156:159], v[164:167], v[48:51]
	v_mfma_f32_16x16x32_bf16 v[36:39], v[148:151], v[172:175], v[36:39]
	v_mfma_f32_16x16x32_bf16 v[32:35], v[156:159], v[172:175], v[32:35]
	v_mfma_f32_16x16x32_bf16 v[20:23], v[148:151], v[192:195], v[20:23]
	v_mfma_f32_16x16x32_bf16 v[16:19], v[156:159], v[192:195], v[16:19]
	v_mfma_f32_16x16x32_bf16 v[4:7], v[148:151], v[210:213], v[4:7]
	v_mfma_f32_16x16x32_bf16 v[0:3], v[156:159], v[210:213], v[0:3]
	s_setprio 0
	s_barrier
	s_add_i32 s60, 0, 0x18000
	s_add_i32 s61, 0, 0x1c000
	v_add_u32_e32 v140, s60, v202
	v_add_u32_e32 v156, s61, v202
	ds_read_b128 v[128:131], v140
	ds_read_b128 v[132:135], v140 offset:1024
	ds_read_b128 v[136:139], v140 offset:2048
	ds_read_b128 v[140:143], v140 offset:3072
	ds_read_b128 v[144:147], v156
	ds_read_b128 v[148:151], v156 offset:1024
	ds_read_b128 v[152:155], v156 offset:2048
	ds_read_b128 v[156:159], v156 offset:3072
	s_add_u32 s36, s36, 0x40000
	s_addc_u32 s37, s37, 0
	s_mov_b32 m0, s44
	v_lshl_add_u64 v[222:223], s[36:37], 0, v[176:177]
	ds_read_b128 v[160:163], v205 offset:32768
	ds_read_b128 v[164:167], v205 offset:33792
	ds_read_b128 v[168:171], v205 offset:34816
	ds_read_b128 v[172:175], v205 offset:35840
	ds_read_b128 v[188:191], v205 offset:36864
	ds_read_b128 v[192:195], v205 offset:37888
	ds_read_b128 v[196:199], v205 offset:38912
	ds_read_b128 v[210:213], v205 offset:39936
	global_load_lds_dwordx4 v[222:223], off
	v_lshl_add_u64 v[222:223], s[36:37], 0, v[180:181]
	s_mov_b32 m0, s45
	s_nop 0
	global_load_lds_dwordx4 v[222:223], off
	s_waitcnt vmcnt(10)
	s_waitcnt lgkmcnt(0)
	v_add_f32_e32 v64, v64, v232
	v_add_f32_e32 v65, v65, v233
	v_add_f32_e32 v66, v66, v234
	v_add_f32_e32 v67, v67, v235
	global_load_dwordx4 v[232:235], v229, s[68:69] offset:512
	s_setprio 1
	s_waitcnt lgkmcnt(0)
	v_mfma_f32_16x16x32_bf16 v[124:127], v[128:131], v[160:163], v[124:127]
	v_mfma_f32_16x16x32_bf16 v[120:123], v[136:139], v[160:163], v[120:123]
	v_mfma_f32_16x16x32_bf16 v[108:111], v[128:131], v[168:171], v[108:111]
	v_mfma_f32_16x16x32_bf16 v[104:107], v[136:139], v[168:171], v[104:107]
	s_barrier
	v_mfma_f32_16x16x32_bf16 v[92:95], v[128:131], v[188:191], v[92:95]
	v_mfma_f32_16x16x32_bf16 v[88:91], v[136:139], v[188:191], v[88:91]
	v_mfma_f32_16x16x32_bf16 v[76:79], v[128:131], v[196:199], v[76:79]
	v_mfma_f32_16x16x32_bf16 v[72:75], v[136:139], v[196:199], v[72:75]
	v_mfma_f32_16x16x32_bf16 v[124:127], v[132:135], v[164:167], v[124:127]
	v_mfma_f32_16x16x32_bf16 v[120:123], v[140:143], v[164:167], v[120:123]
	v_mfma_f32_16x16x32_bf16 v[108:111], v[132:135], v[172:175], v[108:111]
	v_mfma_f32_16x16x32_bf16 v[104:107], v[140:143], v[172:175], v[104:107]
	v_mfma_f32_16x16x32_bf16 v[92:95], v[132:135], v[192:195], v[92:95]
	v_mfma_f32_16x16x32_bf16 v[88:91], v[140:143], v[192:195], v[88:91]
	v_mfma_f32_16x16x32_bf16 v[76:79], v[132:135], v[210:213], v[76:79]
	v_mfma_f32_16x16x32_bf16 v[72:75], v[140:143], v[210:213], v[72:75]
	s_setprio 0
	s_setprio 1
	v_mfma_f32_16x16x32_bf16 v[116:119], v[144:147], v[160:163], v[116:119]
	v_mfma_f32_16x16x32_bf16 v[112:115], v[152:155], v[160:163], v[112:115]
	v_mfma_f32_16x16x32_bf16 v[100:103], v[144:147], v[168:171], v[100:103]
	v_mfma_f32_16x16x32_bf16 v[96:99], v[152:155], v[168:171], v[96:99]
	v_mfma_f32_16x16x32_bf16 v[84:87], v[144:147], v[188:191], v[84:87]
	v_mfma_f32_16x16x32_bf16 v[80:83], v[152:155], v[188:191], v[80:83]
	v_mfma_f32_16x16x32_bf16 v[68:71], v[144:147], v[196:199], v[68:71]
	v_mfma_f32_16x16x32_bf16 v[64:67], v[152:155], v[196:199], v[64:67]
	v_mfma_f32_16x16x32_bf16 v[116:119], v[148:151], v[164:167], v[116:119]
	v_mfma_f32_16x16x32_bf16 v[112:115], v[156:159], v[164:167], v[112:115]
	v_mfma_f32_16x16x32_bf16 v[100:103], v[148:151], v[172:175], v[100:103]
	v_mfma_f32_16x16x32_bf16 v[96:99], v[156:159], v[172:175], v[96:99]
	v_mfma_f32_16x16x32_bf16 v[84:87], v[148:151], v[192:195], v[84:87]
	v_mfma_f32_16x16x32_bf16 v[80:83], v[156:159], v[192:195], v[80:83]
	v_mfma_f32_16x16x32_bf16 v[68:71], v[148:151], v[210:213], v[68:71]
	v_mfma_f32_16x16x32_bf16 v[64:67], v[156:159], v[210:213], v[64:67]
	s_setprio 0
	s_barrier
; #define PG8_STAGE(bufoff, gbase, voff) do { _Pragma("unroll") for (int _i = 0; _i < 2; ++_i) \
;         __builtin_amdgcn_global_load_lds((const unsigned*)((const char*)(gbase) + (voff)[_i]), (LAS unsigned*)(lds + (bufoff) + ldsw + _i * 8192), 16, 0, 0); } while (0)
; #define PG8_LDA(dst, b, h) do { _Pragma("unroll") for (int m = 0; m < 4; ++m) _Pragma("unroll") for (int k = 0; k < 2; ++k) dst[m][k] = *(const LAS bf16x8*)(lds + PG8_SA(b, h) + aoff + m * 2048 + k * 1024); } while (0)
; template <class Epi, bool ALIGN_EPI, bool SP2>
; __device__ __forceinline__ void gemm_phase(LAS unsigned char* lds, const int K, const Sched& S, const Epi& E) {
;     ...
;         for (int t = 0; t < nt; t += 2) {
;             const bool last = (t == nt - 2);
;             const char* a1 = cA + (size_t)(t + 1) * kstep;
;             const char* a2 = last ? nA : cA + (size_t)(t + 2) * kstep; const char* b2 = last ? nB : cB + (size_t)(t + 2) * kstep;
;             const char* a3 = a2 + kstep; const char* b3 = b2 + kstep;
;             if constexpr (SP2) {
;             PG8_LDB(B0, 0, 0); PG8_LDB(B1, 0, 1); PG8_SCHED; PG8_LDA(At, 0, 0); PG8_STAGE(PG8_SA(1, 1), a1 + hstep, voffA);
;             PG8_WAIT_V(8); PG8_WAIT_L(0); PG8_BAR; PG8_MMA(0, 0, At, B0); PG8_MMA(0, 1, At, B1); PG8_BAR; PG8_SCHED;
;     ...
;             PG8_WAIT_V(8); PG8_WAIT_L(0); PG8_BAR; PG8_MMA(0, 0, At, B0); PG8_MMA(0, 1, At, B1); PG8_BAR; PG8_SCHED;
;             PG8_LDA(At, 1, 1); PG8_STAGE(PG8_SB(1, 0), b3, voffB); PG8_STAGE(PG8_SB(1, 1), b3 + hstep, voffB); PG8_STAGE(PG8_SA(1, 0), a3, voffA);
;             PG8_WAIT_V(8); PG8_WAIT_L(0); PG8_BAR; PG8_MMA(1, 0, At, B0); PG8_MMA(1, 1, At, B1); PG8_BAR; PG8_SCHED;
;     __device__ __forceinline__ void operator()(Acc& acc, const Unit& u, int wr, int wc, int fr, int fq) const {
;     ...
;                     for (int bj = 0; bj < 2; ++bj) { const float* p = basef + (size_t)(row0 + ai * HALF + m * 16) * D + col0 + bj * HALF; rx[m][bj][0] = *(const f32x4*)p; rx[m][bj][1] = *(const f32x4*)(p + 4); }
;                 __builtin_amdgcn_sched_barrier(0);
; #pragma unroll
;                 for (int m = 0; m < 4; ++m) { const int row = row0 + ai * HALF + m * 16; const size_t o = (size_t)row * D + col0; float ss = 0.f;
; #pragma unroll
;                     for (int bj = 0; bj < 2; ++bj) { const f32x4 h0 = rx[m][bj][0] + acc[ai][bj][m][0], h1 = rx[m][bj][1] + acc[ai][bj][m][1];
	s_add_i32 s36, s60, s42
	v_lshl_add_u64 v[214:215], v[214:215], 0, s[14:15]
	s_mov_b32 m0, s36
	ds_read_b128 v[160:163], v205 offset:49152
	ds_read_b128 v[164:167], v205 offset:50176
	ds_read_b128 v[168:171], v205 offset:51200
	ds_read_b128 v[172:175], v205 offset:52224
	ds_read_b128 v[188:191], v205 offset:53248
	ds_read_b128 v[192:195], v205 offset:54272
	ds_read_b128 v[196:199], v205 offset:55296
	ds_read_b128 v[210:213], v205 offset:56320
	global_load_lds_dwordx4 v[214:215], off
	s_add_i32 m0, s36, 0x2000
	s_add_u32 s34, s34, 0x40080
	v_lshl_add_u64 v[214:215], v[216:217], 0, s[14:15]
	s_addc_u32 s35, s35, 0
	s_add_i32 s36, s61, s42
	global_load_lds_dwordx4 v[214:215], off
	v_lshl_add_u64 v[214:215], s[34:35], 0, v[178:179]
	s_mov_b32 m0, s36
	s_nop 0
	global_load_lds_dwordx4 v[214:215], off
	v_lshl_add_u64 v[214:215], s[34:35], 0, v[182:183]
	s_add_i32 m0, s36, 0x2000
	s_nop 0
	global_load_lds_dwordx4 v[214:215], off
	v_lshl_add_u64 v[214:215], v[218:219], 0, s[14:15]
	s_mov_b32 m0, s49
	s_nop 0
	global_load_lds_dwordx4 v[214:215], off
	v_lshl_add_u64 v[214:215], v[220:221], 0, s[14:15]
	s_mov_b32 m0, s50
	s_nop 0
	global_load_lds_dwordx4 v[214:215], off
	s_waitcnt vmcnt(10)
	s_waitcnt lgkmcnt(0)
	v_add_f32_e32 v60, v60, v236
	v_add_f32_e32 v61, v61, v237
	v_add_f32_e32 v62, v62, v238
	v_add_f32_e32 v63, v63, v239
	global_load_dwordx4 v[236:239], v229, s[68:69] offset:528
	s_setprio 1
	s_waitcnt lgkmcnt(0)
	v_mfma_f32_16x16x32_bf16 v[60:63], v[128:131], v[160:163], v[60:63]
	v_mfma_f32_16x16x32_bf16 v[56:59], v[136:139], v[160:163], v[56:59]
	v_mfma_f32_16x16x32_bf16 v[44:47], v[128:131], v[168:171], v[44:47]
	v_mfma_f32_16x16x32_bf16 v[40:43], v[136:139], v[168:171], v[40:43]
	s_barrier
	v_mfma_f32_16x16x32_bf16 v[28:31], v[128:131], v[188:191], v[28:31]
	v_mfma_f32_16x16x32_bf16 v[24:27], v[136:139], v[188:191], v[24:27]
	v_mfma_f32_16x16x32_bf16 v[12:15], v[128:131], v[196:199], v[12:15]
	v_mfma_f32_16x16x32_bf16 v[8:11], v[136:139], v[196:199], v[8:11]
	v_mfma_f32_16x16x32_bf16 v[60:63], v[132:135], v[164:167], v[60:63]
	v_mfma_f32_16x16x32_bf16 v[56:59], v[140:143], v[164:167], v[56:59]
	v_mfma_f32_16x16x32_bf16 v[44:47], v[132:135], v[172:175], v[44:47]
	v_mfma_f32_16x16x32_bf16 v[40:43], v[140:143], v[172:175], v[40:43]
	v_mfma_f32_16x16x32_bf16 v[28:31], v[132:135], v[192:195], v[28:31]
	v_mfma_f32_16x16x32_bf16 v[24:27], v[140:143], v[192:195], v[24:27]
	v_mfma_f32_16x16x32_bf16 v[12:15], v[132:135], v[210:213], v[12:15]
	v_mfma_f32_16x16x32_bf16 v[8:11], v[140:143], v[210:213], v[8:11]
	s_setprio 0
	s_setprio 1
	v_mfma_f32_16x16x32_bf16 v[52:55], v[144:147], v[160:163], v[52:55]
	v_mfma_f32_16x16x32_bf16 v[48:51], v[152:155], v[160:163], v[48:51]
	v_mfma_f32_16x16x32_bf16 v[36:39], v[144:147], v[168:171], v[36:39]
	v_mfma_f32_16x16x32_bf16 v[32:35], v[152:155], v[168:171], v[32:35]
	v_mfma_f32_16x16x32_bf16 v[20:23], v[144:147], v[188:191], v[20:23]
	v_mfma_f32_16x16x32_bf16 v[16:19], v[152:155], v[188:191], v[16:19]
	v_mfma_f32_16x16x32_bf16 v[4:7], v[144:147], v[196:199], v[4:7]
	v_mfma_f32_16x16x32_bf16 v[0:3], v[152:155], v[196:199], v[0:3]
	v_mfma_f32_16x16x32_bf16 v[52:55], v[148:151], v[164:167], v[52:55]
	v_mfma_f32_16x16x32_bf16 v[48:51], v[156:159], v[164:167], v[48:51]
	v_mfma_f32_16x16x32_bf16 v[36:39], v[148:151], v[172:175], v[36:39]
	v_mfma_f32_16x16x32_bf16 v[32:35], v[156:159], v[172:175], v[32:35]
	v_mfma_f32_16x16x32_bf16 v[20:23], v[148:151], v[192:195], v[20:23]
	v_mfma_f32_16x16x32_bf16 v[16:19], v[156:159], v[192:195], v[16:19]
	v_mfma_f32_16x16x32_bf16 v[4:7], v[148:151], v[210:213], v[4:7]
	v_mfma_f32_16x16x32_bf16 v[0:3], v[156:159], v[210:213], v[0:3]
	s_setprio 0
	s_barrier
	s_add_i32 s59, s59, 2
	s_add_u32 s30, s30, 0x100
	s_addc_u32 s31, s31, 0
	s_add_u32 s57, s57, 0x100
	s_addc_u32 s58, s58, 0
	ds_read_b128 v[128:131], v203
	ds_read_b128 v[132:135], v203 offset:1024
	ds_read_b128 v[136:139], v203 offset:2048
	ds_read_b128 v[140:143], v203 offset:3072
	ds_read_b128 v[144:147], v204
	ds_read_b128 v[148:151], v204 offset:1024
	ds_read_b128 v[152:155], v204 offset:2048
	ds_read_b128 v[156:159], v204 offset:3072
	s_add_u32 s34, s30, 0xfffc0080
	s_addc_u32 s35, s31, -1
	s_cmp_eq_u32 s59, 12
	s_cselect_b32 s37, s7, s35
	s_cselect_b32 s36, s19, s34
	s_cselect_b32 s35, s21, s58
	s_cselect_b32 s34, s56, s57
	s_mov_b32 m0, s53
	v_lshl_add_u64 v[214:215], s[30:31], 0, v[184:185]
	ds_read_b128 v[160:163], v205
	ds_read_b128 v[164:167], v205 offset:1024
	ds_read_b128 v[168:171], v205 offset:2048
	ds_read_b128 v[172:175], v205 offset:3072
	ds_read_b128 v[188:191], v205 offset:4096
	ds_read_b128 v[192:195], v205 offset:5120
	ds_read_b128 v[196:199], v205 offset:6144
	ds_read_b128 v[210:213], v205 offset:7168
	global_load_lds_dwordx4 v[214:215], off
	v_lshl_add_u64 v[214:215], s[30:31], 0, v[186:187]
	s_mov_b32 m0, s54
	s_nop 0
	global_load_lds_dwordx4 v[214:215], off
	s_waitcnt vmcnt(10)
	s_waitcnt lgkmcnt(0)
	v_add_f32_e32 v56, v56, v240
	v_add_f32_e32 v57, v57, v241
	v_add_f32_e32 v58, v58, v242
	v_add_f32_e32 v59, v59, v243
	s_add_u32 s68, s70, 0x90000
	s_addc_u32 s69, s71, 0
	global_load_dwordx4 v[240:243], v229, s[68:69]
	s_setprio 1
	s_waitcnt lgkmcnt(0)
	v_mfma_f32_16x16x32_bf16 v[124:127], v[128:131], v[160:163], v[124:127]
	v_mfma_f32_16x16x32_bf16 v[120:123], v[136:139], v[160:163], v[120:123]
	v_mfma_f32_16x16x32_bf16 v[108:111], v[128:131], v[168:171], v[108:111]
	v_mfma_f32_16x16x32_bf16 v[104:107], v[136:139], v[168:171], v[104:107]
	s_barrier
; #define PG8_STAGE(bufoff, gbase, voff) do { _Pragma("unroll") for (int _i = 0; _i < 2; ++_i) \
;         __builtin_amdgcn_global_load_lds((const unsigned*)((const char*)(gbase) + (voff)[_i]), (LAS unsigned*)(lds + (bufoff) + ldsw + _i * 8192), 16, 0, 0); } while (0)
; #define PG8_LDA(dst, b, h) do { _Pragma("unroll") for (int m = 0; m < 4; ++m) _Pragma("unroll") for (int k = 0; k < 2; ++k) dst[m][k] = *(const LAS bf16x8*)(lds + PG8_SA(b, h) + aoff + m * 2048 + k * 1024); } while (0)
; #define PG8_LDB(dst, b, h) do { _Pragma("unroll") for (int n = 0; n < 2; ++n) _Pragma("unroll") for (int k = 0; k < 2; ++k) dst[n][k] = *(const LAS bf16x8*)(lds + PG8_SB(b, h) + boff + n * 2048 + k * 1024); } while (0)
; #define PG8_WAIT_V(n) asm volatile("s_waitcnt vmcnt(" #n ")" ::: "memory")
; #define PG8_WAIT_L(n) asm volatile("s_waitcnt lgkmcnt(" #n ")" ::: "memory")
; #define PG8_BAR __builtin_amdgcn_s_barrier()
; #define PG8_SCHED __builtin_amdgcn_sched_barrier(0)
; template <class Epi, bool ALIGN_EPI, bool SP2>
; __device__ __forceinline__ void gemm_phase(LAS unsigned char* lds, const int K, const Sched& S, const Epi& E) {
;     ...
;             PG8_LDA(At, 0, 1); PG8_STAGE(PG8_SB(0, 0), b2, voffB); PG8_STAGE(PG8_SB(0, 1), b2 + hstep, voffB); PG8_STAGE(PG8_SA(0, 0), a2, voffA);
;             PG8_WAIT_V(8); PG8_WAIT_L(0); PG8_BAR; PG8_MMA(1, 0, At, B0); PG8_MMA(1, 1, At, B1); PG8_BAR; PG8_SCHED;
;             PG8_LDB(B0, 1, 0); PG8_LDB(B1, 1, 1); PG8_SCHED; PG8_LDA(At, 1, 0); PG8_STAGE(PG8_SA(0, 1), a2 + hstep, voffA);
;             PG8_WAIT_V(8); PG8_WAIT_L(0); PG8_BAR; PG8_MMA(0, 0, At, B0); PG8_MMA(0, 1, At, B1); PG8_BAR; PG8_SCHED;
;     __device__ __forceinline__ void operator()(Acc& acc, const Unit& u, int wr, int wc, int fr, int fq) const {
;     ...
;                     for (int bj = 0; bj < 2; ++bj) { const float* p = basef + (size_t)(row0 + ai * HALF + m * 16) * D + col0 + bj * HALF; rx[m][bj][0] = *(const f32x4*)p; rx[m][bj][1] = *(const f32x4*)(p + 4); }
;                 __builtin_amdgcn_sched_barrier(0);
; #pragma unroll
;                 for (int m = 0; m < 4; ++m) { const int row = row0 + ai * HALF + m * 16; const size_t o = (size_t)row * D + col0; float ss = 0.f;
; #pragma unroll
;                     for (int bj = 0; bj < 2; ++bj) { const f32x4 h0 = rx[m][bj][0] + acc[ai][bj][m][0], h1 = rx[m][bj][1] + acc[ai][bj][m][1];
	v_mfma_f32_16x16x32_bf16 v[92:95], v[128:131], v[188:191], v[92:95]
	v_mfma_f32_16x16x32_bf16 v[88:91], v[136:139], v[188:191], v[88:91]
	v_mfma_f32_16x16x32_bf16 v[76:79], v[128:131], v[196:199], v[76:79]
	v_mfma_f32_16x16x32_bf16 v[72:75], v[136:139], v[196:199], v[72:75]
	v_mfma_f32_16x16x32_bf16 v[124:127], v[132:135], v[164:167], v[124:127]
	v_mfma_f32_16x16x32_bf16 v[120:123], v[140:143], v[164:167], v[120:123]
	v_mfma_f32_16x16x32_bf16 v[108:111], v[132:135], v[172:175], v[108:111]
	v_mfma_f32_16x16x32_bf16 v[104:107], v[140:143], v[172:175], v[104:107]
	v_mfma_f32_16x16x32_bf16 v[92:95], v[132:135], v[192:195], v[92:95]
	v_mfma_f32_16x16x32_bf16 v[88:91], v[140:143], v[192:195], v[88:91]
	v_mfma_f32_16x16x32_bf16 v[76:79], v[132:135], v[210:213], v[76:79]
	v_mfma_f32_16x16x32_bf16 v[72:75], v[140:143], v[210:213], v[72:75]
	s_setprio 0
	s_setprio 1
	v_mfma_f32_16x16x32_bf16 v[116:119], v[144:147], v[160:163], v[116:119]
	v_mfma_f32_16x16x32_bf16 v[112:115], v[152:155], v[160:163], v[112:115]
	v_mfma_f32_16x16x32_bf16 v[100:103], v[144:147], v[168:171], v[100:103]
	v_mfma_f32_16x16x32_bf16 v[96:99], v[152:155], v[168:171], v[96:99]
	v_mfma_f32_16x16x32_bf16 v[84:87], v[144:147], v[188:191], v[84:87]
	v_mfma_f32_16x16x32_bf16 v[80:83], v[152:155], v[188:191], v[80:83]
	v_mfma_f32_16x16x32_bf16 v[68:71], v[144:147], v[196:199], v[68:71]
	v_mfma_f32_16x16x32_bf16 v[64:67], v[152:155], v[196:199], v[64:67]
	v_mfma_f32_16x16x32_bf16 v[116:119], v[148:151], v[164:167], v[116:119]
	v_mfma_f32_16x16x32_bf16 v[112:115], v[156:159], v[164:167], v[112:115]
	v_mfma_f32_16x16x32_bf16 v[100:103], v[148:151], v[172:175], v[100:103]
	v_mfma_f32_16x16x32_bf16 v[96:99], v[156:159], v[172:175], v[96:99]
	v_mfma_f32_16x16x32_bf16 v[84:87], v[148:151], v[192:195], v[84:87]
	v_mfma_f32_16x16x32_bf16 v[80:83], v[156:159], v[192:195], v[80:83]
	v_mfma_f32_16x16x32_bf16 v[68:71], v[148:151], v[210:213], v[68:71]
	v_mfma_f32_16x16x32_bf16 v[64:67], v[156:159], v[210:213], v[64:67]
	s_setprio 0
	s_barrier
	s_mov_b32 m0, s55
	v_lshl_add_u64 v[214:215], s[34:35], 0, v[178:179]
	ds_read_b128 v[160:163], v205 offset:16384
	ds_read_b128 v[164:167], v205 offset:17408
	ds_read_b128 v[168:171], v205 offset:18432
	ds_read_b128 v[172:175], v205 offset:19456
	ds_read_b128 v[188:191], v205 offset:20480
	ds_read_b128 v[192:195], v205 offset:21504
	ds_read_b128 v[196:199], v205 offset:22528
	ds_read_b128 v[210:213], v205 offset:23552
	global_load_lds_dwordx4 v[214:215], off
	s_add_i32 m0, s55, 0x2000
	s_add_u32 s60, s34, 0x40000
	v_lshl_add_u64 v[216:217], s[34:35], 0, v[182:183]
	s_addc_u32 s61, s35, 0
	s_add_i32 s62, s51, s42
	global_load_lds_dwordx4 v[216:217], off
	v_lshl_add_u64 v[218:219], s[60:61], 0, v[178:179]
	s_mov_b32 m0, s62
	v_lshl_add_u64 v[220:221], s[36:37], 0, v[180:181]
	global_load_lds_dwordx4 v[218:219], off
	v_lshl_add_u64 v[218:219], s[60:61], 0, v[182:183]
	s_add_i32 m0, s62, 0x2000
	s_nop 0
	global_load_lds_dwordx4 v[218:219], off
	v_lshl_add_u64 v[218:219], s[36:37], 0, v[176:177]
	s_mov_b32 m0, s29
	s_nop 0
	global_load_lds_dwordx4 v[218:219], off
	s_mov_b32 m0, s43
	s_nop 0
	global_load_lds_dwordx4 v[220:221], off
	s_waitcnt vmcnt(10)
	s_waitcnt lgkmcnt(0)
	v_add_f32_e32 v52, v52, v232
	v_add_f32_e32 v53, v53, v233
	v_add_f32_e32 v54, v54, v234
	v_add_f32_e32 v55, v55, v235
	global_load_dwordx4 v[232:235], v229, s[68:69] offset:16
	s_setprio 1
	s_waitcnt lgkmcnt(0)
	v_mfma_f32_16x16x32_bf16 v[60:63], v[128:131], v[160:163], v[60:63]
	v_mfma_f32_16x16x32_bf16 v[56:59], v[136:139], v[160:163], v[56:59]
	v_mfma_f32_16x16x32_bf16 v[44:47], v[128:131], v[168:171], v[44:47]
	v_mfma_f32_16x16x32_bf16 v[40:43], v[136:139], v[168:171], v[40:43]
	s_barrier
	v_mfma_f32_16x16x32_bf16 v[28:31], v[128:131], v[188:191], v[28:31]
	v_mfma_f32_16x16x32_bf16 v[24:27], v[136:139], v[188:191], v[24:27]
	v_mfma_f32_16x16x32_bf16 v[12:15], v[128:131], v[196:199], v[12:15]
	v_mfma_f32_16x16x32_bf16 v[8:11], v[136:139], v[196:199], v[8:11]
	v_mfma_f32_16x16x32_bf16 v[60:63], v[132:135], v[164:167], v[60:63]
	v_mfma_f32_16x16x32_bf16 v[56:59], v[140:143], v[164:167], v[56:59]
	v_mfma_f32_16x16x32_bf16 v[44:47], v[132:135], v[172:175], v[44:47]
	v_mfma_f32_16x16x32_bf16 v[40:43], v[140:143], v[172:175], v[40:43]
	v_mfma_f32_16x16x32_bf16 v[28:31], v[132:135], v[192:195], v[28:31]
	v_mfma_f32_16x16x32_bf16 v[24:27], v[140:143], v[192:195], v[24:27]
	v_mfma_f32_16x16x32_bf16 v[12:15], v[132:135], v[210:213], v[12:15]
	v_mfma_f32_16x16x32_bf16 v[8:11], v[140:143], v[210:213], v[8:11]
	s_setprio 0
	s_setprio 1
	v_mfma_f32_16x16x32_bf16 v[52:55], v[144:147], v[160:163], v[52:55]
	v_mfma_f32_16x16x32_bf16 v[48:51], v[152:155], v[160:163], v[48:51]
	v_mfma_f32_16x16x32_bf16 v[36:39], v[144:147], v[168:171], v[36:39]
	v_mfma_f32_16x16x32_bf16 v[32:35], v[152:155], v[168:171], v[32:35]
	v_mfma_f32_16x16x32_bf16 v[20:23], v[144:147], v[188:191], v[20:23]
	v_mfma_f32_16x16x32_bf16 v[16:19], v[152:155], v[188:191], v[16:19]
	v_mfma_f32_16x16x32_bf16 v[4:7], v[144:147], v[196:199], v[4:7]
	v_mfma_f32_16x16x32_bf16 v[0:3], v[152:155], v[196:199], v[0:3]
	v_mfma_f32_16x16x32_bf16 v[52:55], v[148:151], v[164:167], v[52:55]
	v_mfma_f32_16x16x32_bf16 v[48:51], v[156:159], v[164:167], v[48:51]
	v_mfma_f32_16x16x32_bf16 v[36:39], v[148:151], v[172:175], v[36:39]
	v_mfma_f32_16x16x32_bf16 v[32:35], v[156:159], v[172:175], v[32:35]
	v_mfma_f32_16x16x32_bf16 v[20:23], v[148:151], v[192:195], v[20:23]
	v_mfma_f32_16x16x32_bf16 v[16:19], v[156:159], v[192:195], v[16:19]
	v_mfma_f32_16x16x32_bf16 v[4:7], v[148:151], v[210:213], v[4:7]
	v_mfma_f32_16x16x32_bf16 v[0:3], v[156:159], v[210:213], v[0:3]
	s_setprio 0
	s_barrier
; #define PG8_STAGE(bufoff, gbase, voff) do { _Pragma("unroll") for (int _i = 0; _i < 2; ++_i) \
;         __builtin_amdgcn_global_load_lds((const unsigned*)((const char*)(gbase) + (voff)[_i]), (LAS unsigned*)(lds + (bufoff) + ldsw + _i * 8192), 16, 0, 0); } while (0)
; #define PG8_LDA(dst, b, h) do { _Pragma("unroll") for (int m = 0; m < 4; ++m) _Pragma("unroll") for (int k = 0; k < 2; ++k) dst[m][k] = *(const LAS bf16x8*)(lds + PG8_SA(b, h) + aoff + m * 2048 + k * 1024); } while (0)
; #define PG8_LDB(dst, b, h) do { _Pragma("unroll") for (int n = 0; n < 2; ++n) _Pragma("unroll") for (int k = 0; k < 2; ++k) dst[n][k] = *(const LAS bf16x8*)(lds + PG8_SB(b, h) + boff + n * 2048 + k * 1024); } while (0)
; template <class Epi, bool ALIGN_EPI, bool SP2>
; __device__ __forceinline__ void gemm_phase(LAS unsigned char* lds, const int K, const Sched& S, const Epi& E) {
;     ...
;             PG8_LDA(At, 0, 1); PG8_STAGE(PG8_SB(0, 0), b2, voffB); PG8_STAGE(PG8_SB(0, 1), b2 + hstep, voffB); PG8_STAGE(PG8_SA(0, 0), a2, voffA);
;             PG8_WAIT_V(8); PG8_WAIT_L(0); PG8_BAR; PG8_MMA(1, 0, At, B0); PG8_MMA(1, 1, At, B1); PG8_BAR; PG8_SCHED;
;             PG8_LDB(B0, 1, 0); PG8_LDB(B1, 1, 1); PG8_SCHED; PG8_LDA(At, 1, 0); PG8_STAGE(PG8_SA(0, 1), a2 + hstep, voffA);
;             PG8_WAIT_V(8); PG8_WAIT_L(0); PG8_BAR; PG8_MMA(0, 0, At, B0); PG8_MMA(0, 1, At, B1); PG8_BAR; PG8_SCHED;
;             PG8_LDA(At, 1, 1); PG8_STAGE(PG8_SB(1, 0), b3, voffB); PG8_STAGE(PG8_SB(1, 1), b3 + hstep, voffB); PG8_STAGE(PG8_SA(1, 0), a3, voffA);
;             PG8_WAIT_V(8); PG8_WAIT_L(0); PG8_BAR; PG8_MMA(1, 0, At, B0); PG8_MMA(1, 1, At, B1); PG8_BAR; PG8_SCHED;
;     __device__ __forceinline__ void operator()(Acc& acc, const Unit& u, int wr, int wc, int fr, int fq) const {
;     ...
;                     for (int bj = 0; bj < 2; ++bj) { const float* p = basef + (size_t)(row0 + ai * HALF + m * 16) * D + col0 + bj * HALF; rx[m][bj][0] = *(const f32x4*)p; rx[m][bj][1] = *(const f32x4*)(p + 4); }
;                 __builtin_amdgcn_sched_barrier(0);
; #pragma unroll
;                 for (int m = 0; m < 4; ++m) { const int row = row0 + ai * HALF + m * 16; const size_t o = (size_t)row * D + col0; float ss = 0.f;
; #pragma unroll
;                     for (int bj = 0; bj < 2; ++bj) { const f32x4 h0 = rx[m][bj][0] + acc[ai][bj][m][0], h1 = rx[m][bj][1] + acc[ai][bj][m][1];
	s_add_i32 s60, 0, 0x18000
	s_add_i32 s61, 0, 0x1c000
	v_add_u32_e32 v140, s60, v202
	v_add_u32_e32 v156, s61, v202
	ds_read_b128 v[128:131], v140
	ds_read_b128 v[132:135], v140 offset:1024
	ds_read_b128 v[136:139], v140 offset:2048
	ds_read_b128 v[140:143], v140 offset:3072
	ds_read_b128 v[144:147], v156
	ds_read_b128 v[148:151], v156 offset:1024
	ds_read_b128 v[152:155], v156 offset:2048
	ds_read_b128 v[156:159], v156 offset:3072
	s_add_u32 s36, s36, 0x40000
	s_addc_u32 s37, s37, 0
	s_mov_b32 m0, s44
	v_lshl_add_u64 v[222:223], s[36:37], 0, v[176:177]
	ds_read_b128 v[160:163], v205 offset:32768
	ds_read_b128 v[164:167], v205 offset:33792
	ds_read_b128 v[168:171], v205 offset:34816
	ds_read_b128 v[172:175], v205 offset:35840
	ds_read_b128 v[188:191], v205 offset:36864
	ds_read_b128 v[192:195], v205 offset:37888
	ds_read_b128 v[196:199], v205 offset:38912
	ds_read_b128 v[210:213], v205 offset:39936
	global_load_lds_dwordx4 v[222:223], off
	v_lshl_add_u64 v[222:223], s[36:37], 0, v[180:181]
	s_mov_b32 m0, s45
	s_nop 0
	global_load_lds_dwordx4 v[222:223], off
	s_waitcnt vmcnt(10)
	s_waitcnt lgkmcnt(0)
	v_add_f32_e32 v48, v48, v236
	v_add_f32_e32 v49, v49, v237
	v_add_f32_e32 v50, v50, v238
	v_add_f32_e32 v51, v51, v239
	global_load_dwordx4 v[236:239], v229, s[68:69] offset:512
	s_setprio 1
	s_waitcnt lgkmcnt(0)
	v_mfma_f32_16x16x32_bf16 v[124:127], v[128:131], v[160:163], v[124:127]
	v_mfma_f32_16x16x32_bf16 v[120:123], v[136:139], v[160:163], v[120:123]
	v_mfma_f32_16x16x32_bf16 v[108:111], v[128:131], v[168:171], v[108:111]
	v_mfma_f32_16x16x32_bf16 v[104:107], v[136:139], v[168:171], v[104:107]
	s_barrier
	v_mfma_f32_16x16x32_bf16 v[92:95], v[128:131], v[188:191], v[92:95]
	v_mfma_f32_16x16x32_bf16 v[88:91], v[136:139], v[188:191], v[88:91]
	v_mfma_f32_16x16x32_bf16 v[76:79], v[128:131], v[196:199], v[76:79]
	v_mfma_f32_16x16x32_bf16 v[72:75], v[136:139], v[196:199], v[72:75]
	v_mfma_f32_16x16x32_bf16 v[124:127], v[132:135], v[164:167], v[124:127]
	v_mfma_f32_16x16x32_bf16 v[120:123], v[140:143], v[164:167], v[120:123]
	v_mfma_f32_16x16x32_bf16 v[108:111], v[132:135], v[172:175], v[108:111]
	v_mfma_f32_16x16x32_bf16 v[104:107], v[140:143], v[172:175], v[104:107]
	v_mfma_f32_16x16x32_bf16 v[92:95], v[132:135], v[192:195], v[92:95]
	v_mfma_f32_16x16x32_bf16 v[88:91], v[140:143], v[192:195], v[88:91]
	v_mfma_f32_16x16x32_bf16 v[76:79], v[132:135], v[210:213], v[76:79]
	v_mfma_f32_16x16x32_bf16 v[72:75], v[140:143], v[210:213], v[72:75]
	s_setprio 0
	s_setprio 1
	v_mfma_f32_16x16x32_bf16 v[116:119], v[144:147], v[160:163], v[116:119]
	v_mfma_f32_16x16x32_bf16 v[112:115], v[152:155], v[160:163], v[112:115]
	v_mfma_f32_16x16x32_bf16 v[100:103], v[144:147], v[168:171], v[100:103]
	v_mfma_f32_16x16x32_bf16 v[96:99], v[152:155], v[168:171], v[96:99]
	v_mfma_f32_16x16x32_bf16 v[84:87], v[144:147], v[188:191], v[84:87]
	v_mfma_f32_16x16x32_bf16 v[80:83], v[152:155], v[188:191], v[80:83]
	v_mfma_f32_16x16x32_bf16 v[68:71], v[144:147], v[196:199], v[68:71]
	v_mfma_f32_16x16x32_bf16 v[64:67], v[152:155], v[196:199], v[64:67]
	v_mfma_f32_16x16x32_bf16 v[116:119], v[148:151], v[164:167], v[116:119]
	v_mfma_f32_16x16x32_bf16 v[112:115], v[156:159], v[164:167], v[112:115]
	v_mfma_f32_16x16x32_bf16 v[100:103], v[148:151], v[172:175], v[100:103]
	v_mfma_f32_16x16x32_bf16 v[96:99], v[156:159], v[172:175], v[96:99]
	v_mfma_f32_16x16x32_bf16 v[84:87], v[148:151], v[192:195], v[84:87]
	v_mfma_f32_16x16x32_bf16 v[80:83], v[156:159], v[192:195], v[80:83]
	v_mfma_f32_16x16x32_bf16 v[68:71], v[148:151], v[210:213], v[68:71]
	v_mfma_f32_16x16x32_bf16 v[64:67], v[156:159], v[210:213], v[64:67]
	s_setprio 0
	s_barrier
	s_add_i32 s36, s60, s42
	v_lshl_add_u64 v[214:215], v[214:215], 0, s[14:15]
	s_mov_b32 m0, s36
	ds_read_b128 v[160:163], v205 offset:49152
	ds_read_b128 v[164:167], v205 offset:50176
	ds_read_b128 v[168:171], v205 offset:51200
	ds_read_b128 v[172:175], v205 offset:52224
	ds_read_b128 v[188:191], v205 offset:53248
	ds_read_b128 v[192:195], v205 offset:54272
	ds_read_b128 v[196:199], v205 offset:55296
	ds_read_b128 v[210:213], v205 offset:56320
	global_load_lds_dwordx4 v[214:215], off
	s_add_i32 m0, s36, 0x2000
	s_add_u32 s34, s34, 0x40080
	v_lshl_add_u64 v[214:215], v[216:217], 0, s[14:15]
	s_addc_u32 s35, s35, 0
	s_add_i32 s36, s61, s42
	global_load_lds_dwordx4 v[214:215], off
	v_lshl_add_u64 v[214:215], s[34:35], 0, v[178:179]
	s_mov_b32 m0, s36
	s_nop 0
	global_load_lds_dwordx4 v[214:215], off
	v_lshl_add_u64 v[214:215], s[34:35], 0, v[182:183]
	s_add_i32 m0, s36, 0x2000
	s_nop 0
	global_load_lds_dwordx4 v[214:215], off
	v_lshl_add_u64 v[214:215], v[218:219], 0, s[14:15]
	s_mov_b32 m0, s49
	s_nop 0
	global_load_lds_dwordx4 v[214:215], off
	v_lshl_add_u64 v[214:215], v[220:221], 0, s[14:15]
	s_mov_b32 m0, s50
	s_nop 0
	global_load_lds_dwordx4 v[214:215], off
	s_waitcnt vmcnt(10)
	s_waitcnt lgkmcnt(0)
	v_add_f32_e32 v44, v44, v240
	v_add_f32_e32 v45, v45, v241
	v_add_f32_e32 v46, v46, v242
	v_add_f32_e32 v47, v47, v243
	global_load_dwordx4 v[240:243], v229, s[68:69] offset:528
	s_setprio 1
	s_waitcnt lgkmcnt(0)
	v_mfma_f32_16x16x32_bf16 v[60:63], v[128:131], v[160:163], v[60:63]
	v_mfma_f32_16x16x32_bf16 v[56:59], v[136:139], v[160:163], v[56:59]
	v_mfma_f32_16x16x32_bf16 v[44:47], v[128:131], v[168:171], v[44:47]
	v_mfma_f32_16x16x32_bf16 v[40:43], v[136:139], v[168:171], v[40:43]
	s_barrier
; #define PG8_STAGE(bufoff, gbase, voff) do { _Pragma("unroll") for (int _i = 0; _i < 2; ++_i) \
;         __builtin_amdgcn_global_load_lds((const unsigned*)((const char*)(gbase) + (voff)[_i]), (LAS unsigned*)(lds + (bufoff) + ldsw + _i * 8192), 16, 0, 0); } while (0)
; #define PG8_LDA(dst, b, h) do { _Pragma("unroll") for (int m = 0; m < 4; ++m) _Pragma("unroll") for (int k = 0; k < 2; ++k) dst[m][k] = *(const LAS bf16x8*)(lds + PG8_SA(b, h) + aoff + m * 2048 + k * 1024); } while (0)
; template <class Epi, bool ALIGN_EPI, bool SP2>
; __device__ __forceinline__ void gemm_phase(LAS unsigned char* lds, const int K, const Sched& S, const Epi& E) {
;     ...
;         for (int t = 0; t < nt; t += 2) {
;             const bool last = (t == nt - 2);
;             const char* a1 = cA + (size_t)(t + 1) * kstep;
;             const char* a2 = last ? nA : cA + (size_t)(t + 2) * kstep; const char* b2 = last ? nB : cB + (size_t)(t + 2) * kstep;
;             const char* a3 = a2 + kstep; const char* b3 = b2 + kstep;
;             if constexpr (SP2) {
;             PG8_LDB(B0, 0, 0); PG8_LDB(B1, 0, 1); PG8_SCHED; PG8_LDA(At, 0, 0); PG8_STAGE(PG8_SA(1, 1), a1 + hstep, voffA);
;             PG8_WAIT_V(8); PG8_WAIT_L(0); PG8_BAR; PG8_MMA(0, 0, At, B0); PG8_MMA(0, 1, At, B1); PG8_BAR; PG8_SCHED;
;     ...
;             PG8_WAIT_V(8); PG8_WAIT_L(0); PG8_BAR; PG8_MMA(0, 0, At, B0); PG8_MMA(0, 1, At, B1); PG8_BAR; PG8_SCHED;
;             PG8_LDA(At, 1, 1); PG8_STAGE(PG8_SB(1, 0), b3, voffB); PG8_STAGE(PG8_SB(1, 1), b3 + hstep, voffB); PG8_STAGE(PG8_SA(1, 0), a3, voffA);
;             PG8_WAIT_V(8); PG8_WAIT_L(0); PG8_BAR; PG8_MMA(1, 0, At, B0); PG8_MMA(1, 1, At, B1); PG8_BAR; PG8_SCHED;
;     __device__ __forceinline__ void operator()(Acc& acc, const Unit& u, int wr, int wc, int fr, int fq) const {
;     ...
;                     for (int bj = 0; bj < 2; ++bj) { const float* p = basef + (size_t)(row0 + ai * HALF + m * 16) * D + col0 + bj * HALF; rx[m][bj][0] = *(const f32x4*)p; rx[m][bj][1] = *(const f32x4*)(p + 4); }
;                 __builtin_amdgcn_sched_barrier(0);
; #pragma unroll
;                 for (int m = 0; m < 4; ++m) { const int row = row0 + ai * HALF + m * 16; const size_t o = (size_t)row * D + col0; float ss = 0.f;
; #pragma unroll
;                     for (int bj = 0; bj < 2; ++bj) { const f32x4 h0 = rx[m][bj][0] + acc[ai][bj][m][0], h1 = rx[m][bj][1] + acc[ai][bj][m][1];
	v_mfma_f32_16x16x32_bf16 v[28:31], v[128:131], v[188:191], v[28:31]
	v_mfma_f32_16x16x32_bf16 v[24:27], v[136:139], v[188:191], v[24:27]
	v_mfma_f32_16x16x32_bf16 v[12:15], v[128:131], v[196:199], v[12:15]
	v_mfma_f32_16x16x32_bf16 v[8:11], v[136:139], v[196:199], v[8:11]
	v_mfma_f32_16x16x32_bf16 v[60:63], v[132:135], v[164:167], v[60:63]
	v_mfma_f32_16x16x32_bf16 v[56:59], v[140:143], v[164:167], v[56:59]
	v_mfma_f32_16x16x32_bf16 v[44:47], v[132:135], v[172:175], v[44:47]
	v_mfma_f32_16x16x32_bf16 v[40:43], v[140:143], v[172:175], v[40:43]
	v_mfma_f32_16x16x32_bf16 v[28:31], v[132:135], v[192:195], v[28:31]
	v_mfma_f32_16x16x32_bf16 v[24:27], v[140:143], v[192:195], v[24:27]
	v_mfma_f32_16x16x32_bf16 v[12:15], v[132:135], v[210:213], v[12:15]
	v_mfma_f32_16x16x32_bf16 v[8:11], v[140:143], v[210:213], v[8:11]
	s_setprio 0
	s_setprio 1
	v_mfma_f32_16x16x32_bf16 v[52:55], v[144:147], v[160:163], v[52:55]
	v_mfma_f32_16x16x32_bf16 v[48:51], v[152:155], v[160:163], v[48:51]
	v_mfma_f32_16x16x32_bf16 v[36:39], v[144:147], v[168:171], v[36:39]
	v_mfma_f32_16x16x32_bf16 v[32:35], v[152:155], v[168:171], v[32:35]
	v_mfma_f32_16x16x32_bf16 v[20:23], v[144:147], v[188:191], v[20:23]
	v_mfma_f32_16x16x32_bf16 v[16:19], v[152:155], v[188:191], v[16:19]
	v_mfma_f32_16x16x32_bf16 v[4:7], v[144:147], v[196:199], v[4:7]
	v_mfma_f32_16x16x32_bf16 v[0:3], v[152:155], v[196:199], v[0:3]
	v_mfma_f32_16x16x32_bf16 v[52:55], v[148:151], v[164:167], v[52:55]
	v_mfma_f32_16x16x32_bf16 v[48:51], v[156:159], v[164:167], v[48:51]
	v_mfma_f32_16x16x32_bf16 v[36:39], v[148:151], v[172:175], v[36:39]
	v_mfma_f32_16x16x32_bf16 v[32:35], v[156:159], v[172:175], v[32:35]
	v_mfma_f32_16x16x32_bf16 v[20:23], v[148:151], v[192:195], v[20:23]
	v_mfma_f32_16x16x32_bf16 v[16:19], v[156:159], v[192:195], v[16:19]
	v_mfma_f32_16x16x32_bf16 v[4:7], v[148:151], v[210:213], v[4:7]
	v_mfma_f32_16x16x32_bf16 v[0:3], v[156:159], v[210:213], v[0:3]
	s_setprio 0
	s_barrier
	s_add_i32 s59, s59, 2
	s_add_u32 s30, s30, 0x100
	s_addc_u32 s31, s31, 0
	s_add_u32 s57, s57, 0x100
	s_addc_u32 s58, s58, 0
	ds_read_b128 v[128:131], v203
	ds_read_b128 v[132:135], v203 offset:1024
	ds_read_b128 v[136:139], v203 offset:2048
	ds_read_b128 v[140:143], v203 offset:3072
	ds_read_b128 v[144:147], v204
	ds_read_b128 v[148:151], v204 offset:1024
	ds_read_b128 v[152:155], v204 offset:2048
	ds_read_b128 v[156:159], v204 offset:3072
	s_add_u32 s34, s30, 0xfffc0080
	s_addc_u32 s35, s31, -1
	s_cmp_eq_u32 s59, 12
	s_cselect_b32 s37, s7, s35
	s_cselect_b32 s36, s19, s34
	s_cselect_b32 s35, s21, s58
	s_cselect_b32 s34, s56, s57
	s_mov_b32 m0, s53
	v_lshl_add_u64 v[214:215], s[30:31], 0, v[184:185]
	ds_read_b128 v[160:163], v205
	ds_read_b128 v[164:167], v205 offset:1024
	ds_read_b128 v[168:171], v205 offset:2048
	ds_read_b128 v[172:175], v205 offset:3072
	ds_read_b128 v[188:191], v205 offset:4096
	ds_read_b128 v[192:195], v205 offset:5120
	ds_read_b128 v[196:199], v205 offset:6144
	ds_read_b128 v[210:213], v205 offset:7168
	global_load_lds_dwordx4 v[214:215], off
	v_lshl_add_u64 v[214:215], s[30:31], 0, v[186:187]
	s_mov_b32 m0, s54
	s_nop 0
	global_load_lds_dwordx4 v[214:215], off
	s_waitcnt vmcnt(10)
	s_waitcnt lgkmcnt(0)
	v_add_f32_e32 v40, v40, v232
	v_add_f32_e32 v41, v41, v233
	v_add_f32_e32 v42, v42, v234
	v_add_f32_e32 v43, v43, v235
	s_add_u32 s68, s70, 0xa0000
	s_addc_u32 s69, s71, 0
	global_load_dwordx4 v[232:235], v229, s[68:69]
	s_setprio 1
	s_waitcnt lgkmcnt(0)
	v_mfma_f32_16x16x32_bf16 v[124:127], v[128:131], v[160:163], v[124:127]
	v_mfma_f32_16x16x32_bf16 v[120:123], v[136:139], v[160:163], v[120:123]
	v_mfma_f32_16x16x32_bf16 v[108:111], v[128:131], v[168:171], v[108:111]
	v_mfma_f32_16x16x32_bf16 v[104:107], v[136:139], v[168:171], v[104:107]
	s_barrier
	v_mfma_f32_16x16x32_bf16 v[92:95], v[128:131], v[188:191], v[92:95]
	v_mfma_f32_16x16x32_bf16 v[88:91], v[136:139], v[188:191], v[88:91]
	v_mfma_f32_16x16x32_bf16 v[76:79], v[128:131], v[196:199], v[76:79]
	v_mfma_f32_16x16x32_bf16 v[72:75], v[136:139], v[196:199], v[72:75]
	v_mfma_f32_16x16x32_bf16 v[124:127], v[132:135], v[164:167], v[124:127]
	v_mfma_f32_16x16x32_bf16 v[120:123], v[140:143], v[164:167], v[120:123]
	v_mfma_f32_16x16x32_bf16 v[108:111], v[132:135], v[172:175], v[108:111]
	v_mfma_f32_16x16x32_bf16 v[104:107], v[140:143], v[172:175], v[104:107]
	v_mfma_f32_16x16x32_bf16 v[92:95], v[132:135], v[192:195], v[92:95]
	v_mfma_f32_16x16x32_bf16 v[88:91], v[140:143], v[192:195], v[88:91]
	v_mfma_f32_16x16x32_bf16 v[76:79], v[132:135], v[210:213], v[76:79]
	v_mfma_f32_16x16x32_bf16 v[72:75], v[140:143], v[210:213], v[72:75]
	s_setprio 0
	s_setprio 1
	v_mfma_f32_16x16x32_bf16 v[116:119], v[144:147], v[160:163], v[116:119]
	v_mfma_f32_16x16x32_bf16 v[112:115], v[152:155], v[160:163], v[112:115]
	v_mfma_f32_16x16x32_bf16 v[100:103], v[144:147], v[168:171], v[100:103]
	v_mfma_f32_16x16x32_bf16 v[96:99], v[152:155], v[168:171], v[96:99]
	v_mfma_f32_16x16x32_bf16 v[84:87], v[144:147], v[188:191], v[84:87]
	v_mfma_f32_16x16x32_bf16 v[80:83], v[152:155], v[188:191], v[80:83]
	v_mfma_f32_16x16x32_bf16 v[68:71], v[144:147], v[196:199], v[68:71]
	v_mfma_f32_16x16x32_bf16 v[64:67], v[152:155], v[196:199], v[64:67]
	v_mfma_f32_16x16x32_bf16 v[116:119], v[148:151], v[164:167], v[116:119]
	v_mfma_f32_16x16x32_bf16 v[112:115], v[156:159], v[164:167], v[112:115]
	v_mfma_f32_16x16x32_bf16 v[100:103], v[148:151], v[172:175], v[100:103]
	v_mfma_f32_16x16x32_bf16 v[96:99], v[156:159], v[172:175], v[96:99]
	v_mfma_f32_16x16x32_bf16 v[84:87], v[148:151], v[192:195], v[84:87]
	v_mfma_f32_16x16x32_bf16 v[80:83], v[156:159], v[192:195], v[80:83]
	v_mfma_f32_16x16x32_bf16 v[68:71], v[148:151], v[210:213], v[68:71]
	v_mfma_f32_16x16x32_bf16 v[64:67], v[156:159], v[210:213], v[64:67]
	s_setprio 0
	s_barrier
; #define PG8_STAGE(bufoff, gbase, voff) do { _Pragma("unroll") for (int _i = 0; _i < 2; ++_i) \
;         __builtin_amdgcn_global_load_lds((const unsigned*)((const char*)(gbase) + (voff)[_i]), (LAS unsigned*)(lds + (bufoff) + ldsw + _i * 8192), 16, 0, 0); } while (0)
; #define PG8_LDA(dst, b, h) do { _Pragma("unroll") for (int m = 0; m < 4; ++m) _Pragma("unroll") for (int k = 0; k < 2; ++k) dst[m][k] = *(const LAS bf16x8*)(lds + PG8_SA(b, h) + aoff + m * 2048 + k * 1024); } while (0)
; #define PG8_LDB(dst, b, h) do { _Pragma("unroll") for (int n = 0; n < 2; ++n) _Pragma("unroll") for (int k = 0; k < 2; ++k) dst[n][k] = *(const LAS bf16x8*)(lds + PG8_SB(b, h) + boff + n * 2048 + k * 1024); } while (0)
; template <class Epi, bool ALIGN_EPI, bool SP2>
; __device__ __forceinline__ void gemm_phase(LAS unsigned char* lds, const int K, const Sched& S, const Epi& E) {
;     ...
;             PG8_LDA(At, 0, 1); PG8_STAGE(PG8_SB(0, 0), b2, voffB); PG8_STAGE(PG8_SB(0, 1), b2 + hstep, voffB); PG8_STAGE(PG8_SA(0, 0), a2, voffA);
;             PG8_WAIT_V(8); PG8_WAIT_L(0); PG8_BAR; PG8_MMA(1, 0, At, B0); PG8_MMA(1, 1, At, B1); PG8_BAR; PG8_SCHED;
;             PG8_LDB(B0, 1, 0); PG8_LDB(B1, 1, 1); PG8_SCHED; PG8_LDA(At, 1, 0); PG8_STAGE(PG8_SA(0, 1), a2 + hstep, voffA);
;             PG8_WAIT_V(8); PG8_WAIT_L(0); PG8_BAR; PG8_MMA(0, 0, At, B0); PG8_MMA(0, 1, At, B1); PG8_BAR; PG8_SCHED;
;             PG8_LDA(At, 1, 1); PG8_STAGE(PG8_SB(1, 0), b3, voffB); PG8_STAGE(PG8_SB(1, 1), b3 + hstep, voffB); PG8_STAGE(PG8_SA(1, 0), a3, voffA);
;             PG8_WAIT_V(8); PG8_WAIT_L(0); PG8_BAR; PG8_MMA(1, 0, At, B0); PG8_MMA(1, 1, At, B1); PG8_BAR; PG8_SCHED;
;     __device__ __forceinline__ void operator()(Acc& acc, const Unit& u, int wr, int wc, int fr, int fq) const {
;     ...
;                     for (int bj = 0; bj < 2; ++bj) { const float* p = basef + (size_t)(row0 + ai * HALF + m * 16) * D + col0 + bj * HALF; rx[m][bj][0] = *(const f32x4*)p; rx[m][bj][1] = *(const f32x4*)(p + 4); }
;                 __builtin_amdgcn_sched_barrier(0);
; #pragma unroll
;                 for (int m = 0; m < 4; ++m) { const int row = row0 + ai * HALF + m * 16; const size_t o = (size_t)row * D + col0; float ss = 0.f;
; #pragma unroll
;                     for (int bj = 0; bj < 2; ++bj) { const f32x4 h0 = rx[m][bj][0] + acc[ai][bj][m][0], h1 = rx[m][bj][1] + acc[ai][bj][m][1];
	s_mov_b32 m0, s55
	v_lshl_add_u64 v[214:215], s[34:35], 0, v[178:179]
	ds_read_b128 v[160:163], v205 offset:16384
	ds_read_b128 v[164:167], v205 offset:17408
	ds_read_b128 v[168:171], v205 offset:18432
	ds_read_b128 v[172:175], v205 offset:19456
	ds_read_b128 v[188:191], v205 offset:20480
	ds_read_b128 v[192:195], v205 offset:21504
	ds_read_b128 v[196:199], v205 offset:22528
	ds_read_b128 v[210:213], v205 offset:23552
	global_load_lds_dwordx4 v[214:215], off
	s_add_i32 m0, s55, 0x2000
	s_add_u32 s60, s34, 0x40000
	v_lshl_add_u64 v[216:217], s[34:35], 0, v[182:183]
	s_addc_u32 s61, s35, 0
	s_add_i32 s62, s51, s42
	global_load_lds_dwordx4 v[216:217], off
	v_lshl_add_u64 v[218:219], s[60:61], 0, v[178:179]
	s_mov_b32 m0, s62
	v_lshl_add_u64 v[220:221], s[36:37], 0, v[180:181]
	global_load_lds_dwordx4 v[218:219], off
	v_lshl_add_u64 v[218:219], s[60:61], 0, v[182:183]
	s_add_i32 m0, s62, 0x2000
	s_nop 0
	global_load_lds_dwordx4 v[218:219], off
	v_lshl_add_u64 v[218:219], s[36:37], 0, v[176:177]
	s_mov_b32 m0, s29
	s_nop 0
	global_load_lds_dwordx4 v[218:219], off
	s_mov_b32 m0, s43
	s_nop 0
	global_load_lds_dwordx4 v[220:221], off
	s_waitcnt vmcnt(10)
	s_waitcnt lgkmcnt(0)
	v_add_f32_e32 v36, v36, v236
	v_add_f32_e32 v37, v37, v237
	v_add_f32_e32 v38, v38, v238
	v_add_f32_e32 v39, v39, v239
	global_load_dwordx4 v[236:239], v229, s[68:69] offset:16
	s_setprio 1
	s_waitcnt lgkmcnt(0)
	v_mfma_f32_16x16x32_bf16 v[60:63], v[128:131], v[160:163], v[60:63]
	v_mfma_f32_16x16x32_bf16 v[56:59], v[136:139], v[160:163], v[56:59]
	v_mfma_f32_16x16x32_bf16 v[44:47], v[128:131], v[168:171], v[44:47]
	v_mfma_f32_16x16x32_bf16 v[40:43], v[136:139], v[168:171], v[40:43]
	s_barrier
	v_mfma_f32_16x16x32_bf16 v[28:31], v[128:131], v[188:191], v[28:31]
	v_mfma_f32_16x16x32_bf16 v[24:27], v[136:139], v[188:191], v[24:27]
	v_mfma_f32_16x16x32_bf16 v[12:15], v[128:131], v[196:199], v[12:15]
	v_mfma_f32_16x16x32_bf16 v[8:11], v[136:139], v[196:199], v[8:11]
	v_mfma_f32_16x16x32_bf16 v[60:63], v[132:135], v[164:167], v[60:63]
	v_mfma_f32_16x16x32_bf16 v[56:59], v[140:143], v[164:167], v[56:59]
	v_mfma_f32_16x16x32_bf16 v[44:47], v[132:135], v[172:175], v[44:47]
	v_mfma_f32_16x16x32_bf16 v[40:43], v[140:143], v[172:175], v[40:43]
	v_mfma_f32_16x16x32_bf16 v[28:31], v[132:135], v[192:195], v[28:31]
	v_mfma_f32_16x16x32_bf16 v[24:27], v[140:143], v[192:195], v[24:27]
	v_mfma_f32_16x16x32_bf16 v[12:15], v[132:135], v[210:213], v[12:15]
	v_mfma_f32_16x16x32_bf16 v[8:11], v[140:143], v[210:213], v[8:11]
	s_setprio 0
	s_setprio 1
	v_mfma_f32_16x16x32_bf16 v[52:55], v[144:147], v[160:163], v[52:55]
	v_mfma_f32_16x16x32_bf16 v[48:51], v[152:155], v[160:163], v[48:51]
	v_mfma_f32_16x16x32_bf16 v[36:39], v[144:147], v[168:171], v[36:39]
	v_mfma_f32_16x16x32_bf16 v[32:35], v[152:155], v[168:171], v[32:35]
	v_mfma_f32_16x16x32_bf16 v[20:23], v[144:147], v[188:191], v[20:23]
	v_mfma_f32_16x16x32_bf16 v[16:19], v[152:155], v[188:191], v[16:19]
	v_mfma_f32_16x16x32_bf16 v[4:7], v[144:147], v[196:199], v[4:7]
	v_mfma_f32_16x16x32_bf16 v[0:3], v[152:155], v[196:199], v[0:3]
	v_mfma_f32_16x16x32_bf16 v[52:55], v[148:151], v[164:167], v[52:55]
	v_mfma_f32_16x16x32_bf16 v[48:51], v[156:159], v[164:167], v[48:51]
	v_mfma_f32_16x16x32_bf16 v[36:39], v[148:151], v[172:175], v[36:39]
	v_mfma_f32_16x16x32_bf16 v[32:35], v[156:159], v[172:175], v[32:35]
	v_mfma_f32_16x16x32_bf16 v[20:23], v[148:151], v[192:195], v[20:23]
	v_mfma_f32_16x16x32_bf16 v[16:19], v[156:159], v[192:195], v[16:19]
	v_mfma_f32_16x16x32_bf16 v[4:7], v[148:151], v[210:213], v[4:7]
	v_mfma_f32_16x16x32_bf16 v[0:3], v[156:159], v[210:213], v[0:3]
	s_setprio 0
	s_barrier
	s_add_i32 s60, 0, 0x18000
	s_add_i32 s61, 0, 0x1c000
	v_add_u32_e32 v140, s60, v202
	v_add_u32_e32 v156, s61, v202
	ds_read_b128 v[128:131], v140
	ds_read_b128 v[132:135], v140 offset:1024
	ds_read_b128 v[136:139], v140 offset:2048
	ds_read_b128 v[140:143], v140 offset:3072
	ds_read_b128 v[144:147], v156
	ds_read_b128 v[148:151], v156 offset:1024
	ds_read_b128 v[152:155], v156 offset:2048
	ds_read_b128 v[156:159], v156 offset:3072
	s_add_u32 s36, s36, 0x40000
	s_addc_u32 s37, s37, 0
	s_mov_b32 m0, s44
	v_lshl_add_u64 v[222:223], s[36:37], 0, v[176:177]
	ds_read_b128 v[160:163], v205 offset:32768
	ds_read_b128 v[164:167], v205 offset:33792
	ds_read_b128 v[168:171], v205 offset:34816
	ds_read_b128 v[172:175], v205 offset:35840
	ds_read_b128 v[188:191], v205 offset:36864
	ds_read_b128 v[192:195], v205 offset:37888
	ds_read_b128 v[196:199], v205 offset:38912
	ds_read_b128 v[210:213], v205 offset:39936
	global_load_lds_dwordx4 v[222:223], off
	v_lshl_add_u64 v[222:223], s[36:37], 0, v[180:181]
	s_mov_b32 m0, s45
	s_nop 0
	global_load_lds_dwordx4 v[222:223], off
	s_waitcnt vmcnt(10)
	s_waitcnt lgkmcnt(0)
	v_add_f32_e32 v32, v32, v240
	v_add_f32_e32 v33, v33, v241
	v_add_f32_e32 v34, v34, v242
	v_add_f32_e32 v35, v35, v243
	global_load_dwordx4 v[240:243], v229, s[68:69] offset:512
	s_setprio 1
	s_waitcnt lgkmcnt(0)
	v_mfma_f32_16x16x32_bf16 v[124:127], v[128:131], v[160:163], v[124:127]
	v_mfma_f32_16x16x32_bf16 v[120:123], v[136:139], v[160:163], v[120:123]
	v_mfma_f32_16x16x32_bf16 v[108:111], v[128:131], v[168:171], v[108:111]
	v_mfma_f32_16x16x32_bf16 v[104:107], v[136:139], v[168:171], v[104:107]
	s_barrier
; #define PG8_STAGE(bufoff, gbase, voff) do { _Pragma("unroll") for (int _i = 0; _i < 2; ++_i) \
;         __builtin_amdgcn_global_load_lds((const unsigned*)((const char*)(gbase) + (voff)[_i]), (LAS unsigned*)(lds + (bufoff) + ldsw + _i * 8192), 16, 0, 0); } while (0)
; #define PG8_LDA(dst, b, h) do { _Pragma("unroll") for (int m = 0; m < 4; ++m) _Pragma("unroll") for (int k = 0; k < 2; ++k) dst[m][k] = *(const LAS bf16x8*)(lds + PG8_SA(b, h) + aoff + m * 2048 + k * 1024); } while (0)
; #define PG8_MMA(ai, bj, At, Bt) do { __builtin_amdgcn_s_setprio(1); _Pragma("unroll") for (int m = 0; m < 4; ++m) _Pragma("unroll") for (int n = 0; n < 2; ++n) _Pragma("unroll") for (int k = 0; k < 2; ++k) \
;         acc[ai][bj][m][n] = __builtin_amdgcn_mfma_f32_16x16x32_bf16(Bt[n][k], At[m][k], acc[ai][bj][m][n], 0, 0, 0); __builtin_amdgcn_s_setprio(0); } while (0)
; #define PG8_WAIT_V(n) asm volatile("s_waitcnt vmcnt(" #n ")" ::: "memory")
; #define PG8_WAIT_L(n) asm volatile("s_waitcnt lgkmcnt(" #n ")" ::: "memory")
; #define PG8_BAR __builtin_amdgcn_s_barrier()
; #define PG8_SCHED __builtin_amdgcn_sched_barrier(0)
; template <class Epi, bool ALIGN_EPI, bool SP2>
; __device__ __forceinline__ void gemm_phase(LAS unsigned char* lds, const int K, const Sched& S, const Epi& E) {
;     ...
;             PG8_WAIT_V(8); PG8_WAIT_L(0); PG8_BAR; PG8_MMA(0, 0, At, B0); PG8_MMA(0, 1, At, B1); PG8_BAR; PG8_SCHED;
;             PG8_LDA(At, 1, 1); PG8_STAGE(PG8_SB(1, 0), b3, voffB); PG8_STAGE(PG8_SB(1, 1), b3 + hstep, voffB); PG8_STAGE(PG8_SA(1, 0), a3, voffA);
;             PG8_WAIT_V(8); PG8_WAIT_L(0); PG8_BAR; PG8_MMA(1, 0, At, B0); PG8_MMA(1, 1, At, B1); PG8_BAR; PG8_SCHED;
;     __device__ __forceinline__ void operator()(Acc& acc, const Unit& u, int wr, int wc, int fr, int fq) const {
;     ...
;                     for (int bj = 0; bj < 2; ++bj) { const float* p = basef + (size_t)(row0 + ai * HALF + m * 16) * D + col0 + bj * HALF; rx[m][bj][0] = *(const f32x4*)p; rx[m][bj][1] = *(const f32x4*)(p + 4); }
;                 __builtin_amdgcn_sched_barrier(0);
; #pragma unroll
;                 for (int m = 0; m < 4; ++m) { const int row = row0 + ai * HALF + m * 16; const size_t o = (size_t)row * D + col0; float ss = 0.f;
; #pragma unroll
;                     for (int bj = 0; bj < 2; ++bj) { const f32x4 h0 = rx[m][bj][0] + acc[ai][bj][m][0], h1 = rx[m][bj][1] + acc[ai][bj][m][1];
	v_mfma_f32_16x16x32_bf16 v[92:95], v[128:131], v[188:191], v[92:95]
	v_mfma_f32_16x16x32_bf16 v[88:91], v[136:139], v[188:191], v[88:91]
	v_mfma_f32_16x16x32_bf16 v[76:79], v[128:131], v[196:199], v[76:79]
	v_mfma_f32_16x16x32_bf16 v[72:75], v[136:139], v[196:199], v[72:75]
	v_mfma_f32_16x16x32_bf16 v[124:127], v[132:135], v[164:167], v[124:127]
	v_mfma_f32_16x16x32_bf16 v[120:123], v[140:143], v[164:167], v[120:123]
	v_mfma_f32_16x16x32_bf16 v[108:111], v[132:135], v[172:175], v[108:111]
	v_mfma_f32_16x16x32_bf16 v[104:107], v[140:143], v[172:175], v[104:107]
	v_mfma_f32_16x16x32_bf16 v[92:95], v[132:135], v[192:195], v[92:95]
	v_mfma_f32_16x16x32_bf16 v[88:91], v[140:143], v[192:195], v[88:91]
	v_mfma_f32_16x16x32_bf16 v[76:79], v[132:135], v[210:213], v[76:79]
	v_mfma_f32_16x16x32_bf16 v[72:75], v[140:143], v[210:213], v[72:75]
	s_setprio 0
	s_setprio 1
	v_mfma_f32_16x16x32_bf16 v[116:119], v[144:147], v[160:163], v[116:119]
	v_mfma_f32_16x16x32_bf16 v[112:115], v[152:155], v[160:163], v[112:115]
	v_mfma_f32_16x16x32_bf16 v[100:103], v[144:147], v[168:171], v[100:103]
	v_mfma_f32_16x16x32_bf16 v[96:99], v[152:155], v[168:171], v[96:99]
	v_mfma_f32_16x16x32_bf16 v[84:87], v[144:147], v[188:191], v[84:87]
	v_mfma_f32_16x16x32_bf16 v[80:83], v[152:155], v[188:191], v[80:83]
	v_mfma_f32_16x16x32_bf16 v[68:71], v[144:147], v[196:199], v[68:71]
	v_mfma_f32_16x16x32_bf16 v[64:67], v[152:155], v[196:199], v[64:67]
	v_mfma_f32_16x16x32_bf16 v[116:119], v[148:151], v[164:167], v[116:119]
	v_mfma_f32_16x16x32_bf16 v[112:115], v[156:159], v[164:167], v[112:115]
	v_mfma_f32_16x16x32_bf16 v[100:103], v[148:151], v[172:175], v[100:103]
	v_mfma_f32_16x16x32_bf16 v[96:99], v[156:159], v[172:175], v[96:99]
	v_mfma_f32_16x16x32_bf16 v[84:87], v[148:151], v[192:195], v[84:87]
	v_mfma_f32_16x16x32_bf16 v[80:83], v[156:159], v[192:195], v[80:83]
	v_mfma_f32_16x16x32_bf16 v[68:71], v[148:151], v[210:213], v[68:71]
	v_mfma_f32_16x16x32_bf16 v[64:67], v[156:159], v[210:213], v[64:67]
	s_setprio 0
	s_barrier
	s_add_i32 s36, s60, s42
	v_lshl_add_u64 v[214:215], v[214:215], 0, s[14:15]
	s_mov_b32 m0, s36
	ds_read_b128 v[160:163], v205 offset:49152
	ds_read_b128 v[164:167], v205 offset:50176
	ds_read_b128 v[168:171], v205 offset:51200
	ds_read_b128 v[172:175], v205 offset:52224
	ds_read_b128 v[188:191], v205 offset:53248
	ds_read_b128 v[192:195], v205 offset:54272
	ds_read_b128 v[196:199], v205 offset:55296
	ds_read_b128 v[210:213], v205 offset:56320
	global_load_lds_dwordx4 v[214:215], off
	s_add_i32 m0, s36, 0x2000
	s_add_u32 s34, s34, 0x40080
	v_lshl_add_u64 v[214:215], v[216:217], 0, s[14:15]
	s_addc_u32 s35, s35, 0
	s_add_i32 s36, s61, s42
	global_load_lds_dwordx4 v[214:215], off
	v_lshl_add_u64 v[214:215], s[34:35], 0, v[178:179]
	s_mov_b32 m0, s36
	s_nop 0
	global_load_lds_dwordx4 v[214:215], off
	v_lshl_add_u64 v[214:215], s[34:35], 0, v[182:183]
	s_add_i32 m0, s36, 0x2000
	s_nop 0
	global_load_lds_dwordx4 v[214:215], off
	v_lshl_add_u64 v[214:215], v[218:219], 0, s[14:15]
	s_mov_b32 m0, s49
	s_nop 0
	global_load_lds_dwordx4 v[214:215], off
	v_lshl_add_u64 v[214:215], v[220:221], 0, s[14:15]
	s_mov_b32 m0, s50
	s_nop 0
	global_load_lds_dwordx4 v[214:215], off
	s_waitcnt vmcnt(10)
	s_waitcnt lgkmcnt(0)
	v_add_f32_e32 v28, v28, v232
	v_add_f32_e32 v29, v29, v233
	v_add_f32_e32 v30, v30, v234
	v_add_f32_e32 v31, v31, v235
	global_load_dwordx4 v[232:235], v229, s[68:69] offset:528
	s_setprio 1
	s_waitcnt lgkmcnt(0)
	v_mfma_f32_16x16x32_bf16 v[60:63], v[128:131], v[160:163], v[60:63]
	v_mfma_f32_16x16x32_bf16 v[56:59], v[136:139], v[160:163], v[56:59]
	v_mfma_f32_16x16x32_bf16 v[44:47], v[128:131], v[168:171], v[44:47]
	v_mfma_f32_16x16x32_bf16 v[40:43], v[136:139], v[168:171], v[40:43]
	s_barrier
	v_mfma_f32_16x16x32_bf16 v[28:31], v[128:131], v[188:191], v[28:31]
	v_mfma_f32_16x16x32_bf16 v[24:27], v[136:139], v[188:191], v[24:27]
	v_mfma_f32_16x16x32_bf16 v[12:15], v[128:131], v[196:199], v[12:15]
	v_mfma_f32_16x16x32_bf16 v[8:11], v[136:139], v[196:199], v[8:11]
	v_mfma_f32_16x16x32_bf16 v[60:63], v[132:135], v[164:167], v[60:63]
	v_mfma_f32_16x16x32_bf16 v[56:59], v[140:143], v[164:167], v[56:59]
	v_mfma_f32_16x16x32_bf16 v[44:47], v[132:135], v[172:175], v[44:47]
	v_mfma_f32_16x16x32_bf16 v[40:43], v[140:143], v[172:175], v[40:43]
	v_mfma_f32_16x16x32_bf16 v[28:31], v[132:135], v[192:195], v[28:31]
	v_mfma_f32_16x16x32_bf16 v[24:27], v[140:143], v[192:195], v[24:27]
	v_mfma_f32_16x16x32_bf16 v[12:15], v[132:135], v[210:213], v[12:15]
	v_mfma_f32_16x16x32_bf16 v[8:11], v[140:143], v[210:213], v[8:11]
	s_setprio 0
	s_setprio 1
	v_mfma_f32_16x16x32_bf16 v[52:55], v[144:147], v[160:163], v[52:55]
	v_mfma_f32_16x16x32_bf16 v[48:51], v[152:155], v[160:163], v[48:51]
	v_mfma_f32_16x16x32_bf16 v[36:39], v[144:147], v[168:171], v[36:39]
	v_mfma_f32_16x16x32_bf16 v[32:35], v[152:155], v[168:171], v[32:35]
	v_mfma_f32_16x16x32_bf16 v[20:23], v[144:147], v[188:191], v[20:23]
	v_mfma_f32_16x16x32_bf16 v[16:19], v[152:155], v[188:191], v[16:19]
	v_mfma_f32_16x16x32_bf16 v[4:7], v[144:147], v[196:199], v[4:7]
	v_mfma_f32_16x16x32_bf16 v[0:3], v[152:155], v[196:199], v[0:3]
	v_mfma_f32_16x16x32_bf16 v[52:55], v[148:151], v[164:167], v[52:55]
	v_mfma_f32_16x16x32_bf16 v[48:51], v[156:159], v[164:167], v[48:51]
	v_mfma_f32_16x16x32_bf16 v[36:39], v[148:151], v[172:175], v[36:39]
	v_mfma_f32_16x16x32_bf16 v[32:35], v[156:159], v[172:175], v[32:35]
	v_mfma_f32_16x16x32_bf16 v[20:23], v[148:151], v[192:195], v[20:23]
	v_mfma_f32_16x16x32_bf16 v[16:19], v[156:159], v[192:195], v[16:19]
	v_mfma_f32_16x16x32_bf16 v[4:7], v[148:151], v[210:213], v[4:7]
	v_mfma_f32_16x16x32_bf16 v[0:3], v[156:159], v[210:213], v[0:3]
	s_setprio 0
	s_barrier
; #define PG8_STAGE(bufoff, gbase, voff) do { _Pragma("unroll") for (int _i = 0; _i < 2; ++_i) \
;         __builtin_amdgcn_global_load_lds((const unsigned*)((const char*)(gbase) + (voff)[_i]), (LAS unsigned*)(lds + (bufoff) + ldsw + _i * 8192), 16, 0, 0); } while (0)
; #define PG8_WAIT_V(n) asm volatile("s_waitcnt vmcnt(" #n ")" ::: "memory")
; template <class Epi, bool ALIGN_EPI, bool SP2>
; __device__ __forceinline__ void gemm_phase(LAS unsigned char* lds, const int K, const Sched& S, const Epi& E) {
;     ...
;         for (int t = 0; t < nt; t += 2) {
;             const bool last = (t == nt - 2);
;             const char* a1 = cA + (size_t)(t + 1) * kstep;
;             const char* a2 = last ? nA : cA + (size_t)(t + 2) * kstep; const char* b2 = last ? nB : cB + (size_t)(t + 2) * kstep;
;             const char* a3 = a2 + kstep; const char* b3 = b2 + kstep;
;             if constexpr (SP2) {
;             PG8_LDB(B0, 0, 0); PG8_LDB(B1, 0, 1); PG8_SCHED; PG8_LDA(At, 0, 0); PG8_STAGE(PG8_SA(1, 1), a1 + hstep, voffA);
;             PG8_WAIT_V(8); PG8_WAIT_L(0); PG8_BAR; PG8_MMA(0, 0, At, B0); PG8_MMA(0, 1, At, B1); PG8_BAR; PG8_SCHED;
;             PG8_LDA(At, 0, 1); PG8_STAGE(PG8_SB(0, 0), b2, voffB); PG8_STAGE(PG8_SB(0, 1), b2 + hstep, voffB); PG8_STAGE(PG8_SA(0, 0), a2, voffA);
;             PG8_WAIT_V(8); PG8_WAIT_L(0); PG8_BAR; PG8_MMA(1, 0, At, B0); PG8_MMA(1, 1, At, B1); PG8_BAR; PG8_SCHED;
;             PG8_LDB(B0, 1, 0); PG8_LDB(B1, 1, 1); PG8_SCHED; PG8_LDA(At, 1, 0); PG8_STAGE(PG8_SA(0, 1), a2 + hstep, voffA);
;             PG8_WAIT_V(8); PG8_WAIT_L(0); PG8_BAR; PG8_MMA(0, 0, At, B0); PG8_MMA(0, 1, At, B1); PG8_BAR; PG8_SCHED;
;     __device__ __forceinline__ void operator()(Acc& acc, const Unit& u, int wr, int wc, int fr, int fq) const {
;     ...
;                     for (int bj = 0; bj < 2; ++bj) { const float* p = basef + (size_t)(row0 + ai * HALF + m * 16) * D + col0 + bj * HALF; rx[m][bj][0] = *(const f32x4*)p; rx[m][bj][1] = *(const f32x4*)(p + 4); }
;                 __builtin_amdgcn_sched_barrier(0);
; #pragma unroll
;                 for (int m = 0; m < 4; ++m) { const int row = row0 + ai * HALF + m * 16; const size_t o = (size_t)row * D + col0; float ss = 0.f;
; #pragma unroll
;                     for (int bj = 0; bj < 2; ++bj) { const f32x4 h0 = rx[m][bj][0] + acc[ai][bj][m][0], h1 = rx[m][bj][1] + acc[ai][bj][m][1];
	s_add_i32 s59, s59, 2
	s_add_u32 s30, s30, 0x100
	s_addc_u32 s31, s31, 0
	s_add_u32 s57, s57, 0x100
	s_addc_u32 s58, s58, 0
	ds_read_b128 v[128:131], v203
	ds_read_b128 v[132:135], v203 offset:1024
	ds_read_b128 v[136:139], v203 offset:2048
	ds_read_b128 v[140:143], v203 offset:3072
	ds_read_b128 v[144:147], v204
	ds_read_b128 v[148:151], v204 offset:1024
	ds_read_b128 v[152:155], v204 offset:2048
	ds_read_b128 v[156:159], v204 offset:3072
	s_add_u32 s34, s30, 0xfffc0080
	s_addc_u32 s35, s31, -1
	s_cmp_eq_u32 s59, 12
	s_cselect_b32 s37, s7, s35
	s_cselect_b32 s36, s19, s34
	s_cselect_b32 s35, s21, s58
	s_cselect_b32 s34, s56, s57
	s_mov_b32 m0, s53
	v_lshl_add_u64 v[214:215], s[30:31], 0, v[184:185]
	ds_read_b128 v[160:163], v205
	ds_read_b128 v[164:167], v205 offset:1024
	ds_read_b128 v[168:171], v205 offset:2048
	ds_read_b128 v[172:175], v205 offset:3072
	ds_read_b128 v[188:191], v205 offset:4096
	ds_read_b128 v[192:195], v205 offset:5120
	ds_read_b128 v[196:199], v205 offset:6144
	ds_read_b128 v[210:213], v205 offset:7168
	global_load_lds_dwordx4 v[214:215], off
	v_lshl_add_u64 v[214:215], s[30:31], 0, v[186:187]
	s_mov_b32 m0, s54
	s_nop 0
	global_load_lds_dwordx4 v[214:215], off
	s_waitcnt vmcnt(10)
	s_waitcnt lgkmcnt(0)
	v_add_f32_e32 v24, v24, v236
	v_add_f32_e32 v25, v25, v237
	v_add_f32_e32 v26, v26, v238
	v_add_f32_e32 v27, v27, v239
	s_add_u32 s68, s70, 0xb0000
	s_addc_u32 s69, s71, 0
	global_load_dwordx4 v[236:239], v229, s[68:69]
	s_setprio 1
	s_waitcnt lgkmcnt(0)
	v_mfma_f32_16x16x32_bf16 v[124:127], v[128:131], v[160:163], v[124:127]
	v_mfma_f32_16x16x32_bf16 v[120:123], v[136:139], v[160:163], v[120:123]
	v_mfma_f32_16x16x32_bf16 v[108:111], v[128:131], v[168:171], v[108:111]
	v_mfma_f32_16x16x32_bf16 v[104:107], v[136:139], v[168:171], v[104:107]
	s_barrier
	v_mfma_f32_16x16x32_bf16 v[92:95], v[128:131], v[188:191], v[92:95]
	v_mfma_f32_16x16x32_bf16 v[88:91], v[136:139], v[188:191], v[88:91]
	v_mfma_f32_16x16x32_bf16 v[76:79], v[128:131], v[196:199], v[76:79]
	v_mfma_f32_16x16x32_bf16 v[72:75], v[136:139], v[196:199], v[72:75]
	v_mfma_f32_16x16x32_bf16 v[124:127], v[132:135], v[164:167], v[124:127]
	v_mfma_f32_16x16x32_bf16 v[120:123], v[140:143], v[164:167], v[120:123]
	v_mfma_f32_16x16x32_bf16 v[108:111], v[132:135], v[172:175], v[108:111]
	v_mfma_f32_16x16x32_bf16 v[104:107], v[140:143], v[172:175], v[104:107]
	v_mfma_f32_16x16x32_bf16 v[92:95], v[132:135], v[192:195], v[92:95]
	v_mfma_f32_16x16x32_bf16 v[88:91], v[140:143], v[192:195], v[88:91]
	v_mfma_f32_16x16x32_bf16 v[76:79], v[132:135], v[210:213], v[76:79]
	v_mfma_f32_16x16x32_bf16 v[72:75], v[140:143], v[210:213], v[72:75]
	s_setprio 0
	s_setprio 1
	v_mfma_f32_16x16x32_bf16 v[116:119], v[144:147], v[160:163], v[116:119]
	v_mfma_f32_16x16x32_bf16 v[112:115], v[152:155], v[160:163], v[112:115]
	v_mfma_f32_16x16x32_bf16 v[100:103], v[144:147], v[168:171], v[100:103]
	v_mfma_f32_16x16x32_bf16 v[96:99], v[152:155], v[168:171], v[96:99]
	v_mfma_f32_16x16x32_bf16 v[84:87], v[144:147], v[188:191], v[84:87]
	v_mfma_f32_16x16x32_bf16 v[80:83], v[152:155], v[188:191], v[80:83]
	v_mfma_f32_16x16x32_bf16 v[68:71], v[144:147], v[196:199], v[68:71]
	v_mfma_f32_16x16x32_bf16 v[64:67], v[152:155], v[196:199], v[64:67]
	v_mfma_f32_16x16x32_bf16 v[116:119], v[148:151], v[164:167], v[116:119]
	v_mfma_f32_16x16x32_bf16 v[112:115], v[156:159], v[164:167], v[112:115]
	v_mfma_f32_16x16x32_bf16 v[100:103], v[148:151], v[172:175], v[100:103]
	v_mfma_f32_16x16x32_bf16 v[96:99], v[156:159], v[172:175], v[96:99]
	v_mfma_f32_16x16x32_bf16 v[84:87], v[148:151], v[192:195], v[84:87]
	v_mfma_f32_16x16x32_bf16 v[80:83], v[156:159], v[192:195], v[80:83]
	v_mfma_f32_16x16x32_bf16 v[68:71], v[148:151], v[210:213], v[68:71]
	v_mfma_f32_16x16x32_bf16 v[64:67], v[156:159], v[210:213], v[64:67]
	s_setprio 0
	s_barrier
	s_mov_b32 m0, s55
	v_lshl_add_u64 v[214:215], s[34:35], 0, v[178:179]
	ds_read_b128 v[160:163], v205 offset:16384
	ds_read_b128 v[164:167], v205 offset:17408
	ds_read_b128 v[168:171], v205 offset:18432
	ds_read_b128 v[172:175], v205 offset:19456
	ds_read_b128 v[188:191], v205 offset:20480
	ds_read_b128 v[192:195], v205 offset:21504
	ds_read_b128 v[196:199], v205 offset:22528
	ds_read_b128 v[210:213], v205 offset:23552
	global_load_lds_dwordx4 v[214:215], off
	s_add_i32 m0, s55, 0x2000
	s_add_u32 s60, s34, 0x40000
	v_lshl_add_u64 v[216:217], s[34:35], 0, v[182:183]
	s_addc_u32 s61, s35, 0
	s_add_i32 s62, s51, s42
	global_load_lds_dwordx4 v[216:217], off
	v_lshl_add_u64 v[218:219], s[60:61], 0, v[178:179]
	s_mov_b32 m0, s62
	v_lshl_add_u64 v[220:221], s[36:37], 0, v[180:181]
	global_load_lds_dwordx4 v[218:219], off
	v_lshl_add_u64 v[218:219], s[60:61], 0, v[182:183]
	s_add_i32 m0, s62, 0x2000
	s_nop 0
	global_load_lds_dwordx4 v[218:219], off
	v_lshl_add_u64 v[218:219], s[36:37], 0, v[176:177]
	s_mov_b32 m0, s29
	s_nop 0
	global_load_lds_dwordx4 v[218:219], off
	s_mov_b32 m0, s43
	s_nop 0
	global_load_lds_dwordx4 v[220:221], off
	s_waitcnt vmcnt(10)
	s_waitcnt lgkmcnt(0)
	v_add_f32_e32 v20, v20, v240
	v_add_f32_e32 v21, v21, v241
	v_add_f32_e32 v22, v22, v242
	v_add_f32_e32 v23, v23, v243
	global_load_dwordx4 v[240:243], v229, s[68:69] offset:16
	s_setprio 1
	s_waitcnt lgkmcnt(0)
	v_mfma_f32_16x16x32_bf16 v[60:63], v[128:131], v[160:163], v[60:63]
	v_mfma_f32_16x16x32_bf16 v[56:59], v[136:139], v[160:163], v[56:59]
	v_mfma_f32_16x16x32_bf16 v[44:47], v[128:131], v[168:171], v[44:47]
	v_mfma_f32_16x16x32_bf16 v[40:43], v[136:139], v[168:171], v[40:43]
	s_barrier
; #define PG8_STAGE(bufoff, gbase, voff) do { _Pragma("unroll") for (int _i = 0; _i < 2; ++_i) \
;         __builtin_amdgcn_global_load_lds((const unsigned*)((const char*)(gbase) + (voff)[_i]), (LAS unsigned*)(lds + (bufoff) + ldsw + _i * 8192), 16, 0, 0); } while (0)
; #define PG8_LDA(dst, b, h) do { _Pragma("unroll") for (int m = 0; m < 4; ++m) _Pragma("unroll") for (int k = 0; k < 2; ++k) dst[m][k] = *(const LAS bf16x8*)(lds + PG8_SA(b, h) + aoff + m * 2048 + k * 1024); } while (0)
; #define PG8_LDB(dst, b, h) do { _Pragma("unroll") for (int n = 0; n < 2; ++n) _Pragma("unroll") for (int k = 0; k < 2; ++k) dst[n][k] = *(const LAS bf16x8*)(lds + PG8_SB(b, h) + boff + n * 2048 + k * 1024); } while (0)
; #define PG8_WAIT_V(n) asm volatile("s_waitcnt vmcnt(" #n ")" ::: "memory")
; #define PG8_WAIT_L(n) asm volatile("s_waitcnt lgkmcnt(" #n ")" ::: "memory")
; template <class Epi, bool ALIGN_EPI, bool SP2>
; __device__ __forceinline__ void gemm_phase(LAS unsigned char* lds, const int K, const Sched& S, const Epi& E) {
;     ...
;             PG8_WAIT_V(8); PG8_WAIT_L(0); PG8_BAR; PG8_MMA(1, 0, At, B0); PG8_MMA(1, 1, At, B1); PG8_BAR; PG8_SCHED;
;             PG8_LDB(B0, 1, 0); PG8_LDB(B1, 1, 1); PG8_SCHED; PG8_LDA(At, 1, 0); PG8_STAGE(PG8_SA(0, 1), a2 + hstep, voffA);
;             PG8_WAIT_V(8); PG8_WAIT_L(0); PG8_BAR; PG8_MMA(0, 0, At, B0); PG8_MMA(0, 1, At, B1); PG8_BAR; PG8_SCHED;
;             PG8_LDA(At, 1, 1); PG8_STAGE(PG8_SB(1, 0), b3, voffB); PG8_STAGE(PG8_SB(1, 1), b3 + hstep, voffB); PG8_STAGE(PG8_SA(1, 0), a3, voffA);
;             PG8_WAIT_V(8); PG8_WAIT_L(0); PG8_BAR; PG8_MMA(1, 0, At, B0); PG8_MMA(1, 1, At, B1); PG8_BAR; PG8_SCHED;
;     __device__ __forceinline__ void operator()(Acc& acc, const Unit& u, int wr, int wc, int fr, int fq) const {
;     ...
;                     for (int bj = 0; bj < 2; ++bj) { const float* p = basef + (size_t)(row0 + ai * HALF + m * 16) * D + col0 + bj * HALF; rx[m][bj][0] = *(const f32x4*)p; rx[m][bj][1] = *(const f32x4*)(p + 4); }
;                 __builtin_amdgcn_sched_barrier(0);
; #pragma unroll
;                 for (int m = 0; m < 4; ++m) { const int row = row0 + ai * HALF + m * 16; const size_t o = (size_t)row * D + col0; float ss = 0.f;
; #pragma unroll
;                     for (int bj = 0; bj < 2; ++bj) { const f32x4 h0 = rx[m][bj][0] + acc[ai][bj][m][0], h1 = rx[m][bj][1] + acc[ai][bj][m][1];
	v_mfma_f32_16x16x32_bf16 v[28:31], v[128:131], v[188:191], v[28:31]
	v_mfma_f32_16x16x32_bf16 v[24:27], v[136:139], v[188:191], v[24:27]
	v_mfma_f32_16x16x32_bf16 v[12:15], v[128:131], v[196:199], v[12:15]
	v_mfma_f32_16x16x32_bf16 v[8:11], v[136:139], v[196:199], v[8:11]
	v_mfma_f32_16x16x32_bf16 v[60:63], v[132:135], v[164:167], v[60:63]
	v_mfma_f32_16x16x32_bf16 v[56:59], v[140:143], v[164:167], v[56:59]
	v_mfma_f32_16x16x32_bf16 v[44:47], v[132:135], v[172:175], v[44:47]
	v_mfma_f32_16x16x32_bf16 v[40:43], v[140:143], v[172:175], v[40:43]
	v_mfma_f32_16x16x32_bf16 v[28:31], v[132:135], v[192:195], v[28:31]
	v_mfma_f32_16x16x32_bf16 v[24:27], v[140:143], v[192:195], v[24:27]
	v_mfma_f32_16x16x32_bf16 v[12:15], v[132:135], v[210:213], v[12:15]
	v_mfma_f32_16x16x32_bf16 v[8:11], v[140:143], v[210:213], v[8:11]
	s_setprio 0
	s_setprio 1
	v_mfma_f32_16x16x32_bf16 v[52:55], v[144:147], v[160:163], v[52:55]
	v_mfma_f32_16x16x32_bf16 v[48:51], v[152:155], v[160:163], v[48:51]
	v_mfma_f32_16x16x32_bf16 v[36:39], v[144:147], v[168:171], v[36:39]
	v_mfma_f32_16x16x32_bf16 v[32:35], v[152:155], v[168:171], v[32:35]
	v_mfma_f32_16x16x32_bf16 v[20:23], v[144:147], v[188:191], v[20:23]
	v_mfma_f32_16x16x32_bf16 v[16:19], v[152:155], v[188:191], v[16:19]
	v_mfma_f32_16x16x32_bf16 v[4:7], v[144:147], v[196:199], v[4:7]
	v_mfma_f32_16x16x32_bf16 v[0:3], v[152:155], v[196:199], v[0:3]
	v_mfma_f32_16x16x32_bf16 v[52:55], v[148:151], v[164:167], v[52:55]
	v_mfma_f32_16x16x32_bf16 v[48:51], v[156:159], v[164:167], v[48:51]
	v_mfma_f32_16x16x32_bf16 v[36:39], v[148:151], v[172:175], v[36:39]
	v_mfma_f32_16x16x32_bf16 v[32:35], v[156:159], v[172:175], v[32:35]
	v_mfma_f32_16x16x32_bf16 v[20:23], v[148:151], v[192:195], v[20:23]
	v_mfma_f32_16x16x32_bf16 v[16:19], v[156:159], v[192:195], v[16:19]
	v_mfma_f32_16x16x32_bf16 v[4:7], v[148:151], v[210:213], v[4:7]
	v_mfma_f32_16x16x32_bf16 v[0:3], v[156:159], v[210:213], v[0:3]
	s_setprio 0
	s_barrier
	s_add_i32 s60, 0, 0x18000
	s_add_i32 s61, 0, 0x1c000
	v_add_u32_e32 v140, s60, v202
	v_add_u32_e32 v156, s61, v202
	ds_read_b128 v[128:131], v140
	ds_read_b128 v[132:135], v140 offset:1024
	ds_read_b128 v[136:139], v140 offset:2048
	ds_read_b128 v[140:143], v140 offset:3072
	ds_read_b128 v[144:147], v156
	ds_read_b128 v[148:151], v156 offset:1024
	ds_read_b128 v[152:155], v156 offset:2048
	ds_read_b128 v[156:159], v156 offset:3072
	s_add_u32 s36, s36, 0x40000
	s_addc_u32 s37, s37, 0
	s_mov_b32 m0, s44
	v_lshl_add_u64 v[222:223], s[36:37], 0, v[176:177]
	ds_read_b128 v[160:163], v205 offset:32768
	ds_read_b128 v[164:167], v205 offset:33792
	ds_read_b128 v[168:171], v205 offset:34816
	ds_read_b128 v[172:175], v205 offset:35840
	ds_read_b128 v[188:191], v205 offset:36864
	ds_read_b128 v[192:195], v205 offset:37888
	ds_read_b128 v[196:199], v205 offset:38912
	ds_read_b128 v[210:213], v205 offset:39936
	global_load_lds_dwordx4 v[222:223], off
	v_lshl_add_u64 v[222:223], s[36:37], 0, v[180:181]
	s_mov_b32 m0, s45
	s_nop 0
	global_load_lds_dwordx4 v[222:223], off
	s_waitcnt vmcnt(10)
	s_waitcnt lgkmcnt(0)
	v_add_f32_e32 v16, v16, v232
	v_add_f32_e32 v17, v17, v233
	v_add_f32_e32 v18, v18, v234
	v_add_f32_e32 v19, v19, v235
	global_load_dwordx4 v[232:235], v229, s[68:69] offset:512
	s_setprio 1
	s_waitcnt lgkmcnt(0)
	v_mfma_f32_16x16x32_bf16 v[124:127], v[128:131], v[160:163], v[124:127]
	v_mfma_f32_16x16x32_bf16 v[120:123], v[136:139], v[160:163], v[120:123]
	v_mfma_f32_16x16x32_bf16 v[108:111], v[128:131], v[168:171], v[108:111]
	v_mfma_f32_16x16x32_bf16 v[104:107], v[136:139], v[168:171], v[104:107]
	s_barrier
	v_mfma_f32_16x16x32_bf16 v[92:95], v[128:131], v[188:191], v[92:95]
	v_mfma_f32_16x16x32_bf16 v[88:91], v[136:139], v[188:191], v[88:91]
	v_mfma_f32_16x16x32_bf16 v[76:79], v[128:131], v[196:199], v[76:79]
	v_mfma_f32_16x16x32_bf16 v[72:75], v[136:139], v[196:199], v[72:75]
	v_mfma_f32_16x16x32_bf16 v[124:127], v[132:135], v[164:167], v[124:127]
	v_mfma_f32_16x16x32_bf16 v[120:123], v[140:143], v[164:167], v[120:123]
	v_mfma_f32_16x16x32_bf16 v[108:111], v[132:135], v[172:175], v[108:111]
	v_mfma_f32_16x16x32_bf16 v[104:107], v[140:143], v[172:175], v[104:107]
	v_mfma_f32_16x16x32_bf16 v[92:95], v[132:135], v[192:195], v[92:95]
	v_mfma_f32_16x16x32_bf16 v[88:91], v[140:143], v[192:195], v[88:91]
	v_mfma_f32_16x16x32_bf16 v[76:79], v[132:135], v[210:213], v[76:79]
	v_mfma_f32_16x16x32_bf16 v[72:75], v[140:143], v[210:213], v[72:75]
	s_setprio 0
	s_setprio 1
	v_mfma_f32_16x16x32_bf16 v[116:119], v[144:147], v[160:163], v[116:119]
	v_mfma_f32_16x16x32_bf16 v[112:115], v[152:155], v[160:163], v[112:115]
	v_mfma_f32_16x16x32_bf16 v[100:103], v[144:147], v[168:171], v[100:103]
	v_mfma_f32_16x16x32_bf16 v[96:99], v[152:155], v[168:171], v[96:99]
	v_mfma_f32_16x16x32_bf16 v[84:87], v[144:147], v[188:191], v[84:87]
	v_mfma_f32_16x16x32_bf16 v[80:83], v[152:155], v[188:191], v[80:83]
	v_mfma_f32_16x16x32_bf16 v[68:71], v[144:147], v[196:199], v[68:71]
	v_mfma_f32_16x16x32_bf16 v[64:67], v[152:155], v[196:199], v[64:67]
	v_mfma_f32_16x16x32_bf16 v[116:119], v[148:151], v[164:167], v[116:119]
	v_mfma_f32_16x16x32_bf16 v[112:115], v[156:159], v[164:167], v[112:115]
	v_mfma_f32_16x16x32_bf16 v[100:103], v[148:151], v[172:175], v[100:103]
	v_mfma_f32_16x16x32_bf16 v[96:99], v[156:159], v[172:175], v[96:99]
	v_mfma_f32_16x16x32_bf16 v[84:87], v[148:151], v[192:195], v[84:87]
	v_mfma_f32_16x16x32_bf16 v[80:83], v[156:159], v[192:195], v[80:83]
	v_mfma_f32_16x16x32_bf16 v[68:71], v[148:151], v[210:213], v[68:71]
	v_mfma_f32_16x16x32_bf16 v[64:67], v[156:159], v[210:213], v[64:67]
	s_setprio 0
	s_barrier
; #define PG8_STAGE(bufoff, gbase, voff) do { _Pragma("unroll") for (int _i = 0; _i < 2; ++_i) \
;         __builtin_amdgcn_global_load_lds((const unsigned*)((const char*)(gbase) + (voff)[_i]), (LAS unsigned*)(lds + (bufoff) + ldsw + _i * 8192), 16, 0, 0); } while (0)
; #define PG8_LDA(dst, b, h) do { _Pragma("unroll") for (int m = 0; m < 4; ++m) _Pragma("unroll") for (int k = 0; k < 2; ++k) dst[m][k] = *(const LAS bf16x8*)(lds + PG8_SA(b, h) + aoff + m * 2048 + k * 1024); } while (0)
; #define PG8_MMA(ai, bj, At, Bt) do { __builtin_amdgcn_s_setprio(1); _Pragma("unroll") for (int m = 0; m < 4; ++m) _Pragma("unroll") for (int n = 0; n < 2; ++n) _Pragma("unroll") for (int k = 0; k < 2; ++k) \
;         acc[ai][bj][m][n] = __builtin_amdgcn_mfma_f32_16x16x32_bf16(Bt[n][k], At[m][k], acc[ai][bj][m][n], 0, 0, 0); __builtin_amdgcn_s_setprio(0); } while (0)
; #define PG8_WAIT_V(n) asm volatile("s_waitcnt vmcnt(" #n ")" ::: "memory")
; #define PG8_WAIT_L(n) asm volatile("s_waitcnt lgkmcnt(" #n ")" ::: "memory")
; #define PG8_BAR __builtin_amdgcn_s_barrier()
; #define PG8_SCHED __builtin_amdgcn_sched_barrier(0)
; template <class Epi, bool ALIGN_EPI, bool SP2>
; __device__ __forceinline__ void gemm_phase(LAS unsigned char* lds, const int K, const Sched& S, const Epi& E) {
;     ...
;             PG8_LDA(At, 1, 1); PG8_STAGE(PG8_SB(1, 0), b3, voffB); PG8_STAGE(PG8_SB(1, 1), b3 + hstep, voffB); PG8_STAGE(PG8_SA(1, 0), a3, voffA);
;             PG8_WAIT_V(8); PG8_WAIT_L(0); PG8_BAR; PG8_MMA(1, 0, At, B0); PG8_MMA(1, 1, At, B1); PG8_BAR; PG8_SCHED;
;     __device__ __forceinline__ void operator()(Acc& acc, const Unit& u, int wr, int wc, int fr, int fq) const {
;     ...
;                     for (int bj = 0; bj < 2; ++bj) { const float* p = basef + (size_t)(row0 + ai * HALF + m * 16) * D + col0 + bj * HALF; rx[m][bj][0] = *(const f32x4*)p; rx[m][bj][1] = *(const f32x4*)(p + 4); }
;                 __builtin_amdgcn_sched_barrier(0);
; #pragma unroll
;                 for (int m = 0; m < 4; ++m) { const int row = row0 + ai * HALF + m * 16; const size_t o = (size_t)row * D + col0; float ss = 0.f;
; #pragma unroll
;                     for (int bj = 0; bj < 2; ++bj) { const f32x4 h0 = rx[m][bj][0] + acc[ai][bj][m][0], h1 = rx[m][bj][1] + acc[ai][bj][m][1];
	s_add_i32 s36, s60, s42
	v_lshl_add_u64 v[214:215], v[214:215], 0, s[14:15]
	s_mov_b32 m0, s36
	ds_read_b128 v[160:163], v205 offset:49152
	ds_read_b128 v[164:167], v205 offset:50176
	ds_read_b128 v[168:171], v205 offset:51200
	ds_read_b128 v[172:175], v205 offset:52224
	ds_read_b128 v[188:191], v205 offset:53248
	ds_read_b128 v[192:195], v205 offset:54272
	ds_read_b128 v[196:199], v205 offset:55296
	ds_read_b128 v[210:213], v205 offset:56320
	global_load_lds_dwordx4 v[214:215], off
	s_add_i32 m0, s36, 0x2000
	s_add_u32 s34, s34, 0x40080
	v_lshl_add_u64 v[214:215], v[216:217], 0, s[14:15]
	s_addc_u32 s35, s35, 0
	s_add_i32 s36, s61, s42
	global_load_lds_dwordx4 v[214:215], off
	v_lshl_add_u64 v[214:215], s[34:35], 0, v[178:179]
	s_mov_b32 m0, s36
	s_nop 0
	global_load_lds_dwordx4 v[214:215], off
	v_lshl_add_u64 v[214:215], s[34:35], 0, v[182:183]
	s_add_i32 m0, s36, 0x2000
	s_nop 0
	global_load_lds_dwordx4 v[214:215], off
	v_lshl_add_u64 v[214:215], v[218:219], 0, s[14:15]
	s_mov_b32 m0, s49
	s_nop 0
	global_load_lds_dwordx4 v[214:215], off
	v_lshl_add_u64 v[214:215], v[220:221], 0, s[14:15]
	s_mov_b32 m0, s50
	s_nop 0
	global_load_lds_dwordx4 v[214:215], off
	s_waitcnt vmcnt(10)
	s_waitcnt lgkmcnt(0)
	v_add_f32_e32 v12, v12, v236
	v_add_f32_e32 v13, v13, v237
	v_add_f32_e32 v14, v14, v238
	v_add_f32_e32 v15, v15, v239
	global_load_dwordx4 v[236:239], v229, s[68:69] offset:528
	s_setprio 1
	s_waitcnt lgkmcnt(0)
	v_mfma_f32_16x16x32_bf16 v[60:63], v[128:131], v[160:163], v[60:63]
	v_mfma_f32_16x16x32_bf16 v[56:59], v[136:139], v[160:163], v[56:59]
	v_mfma_f32_16x16x32_bf16 v[44:47], v[128:131], v[168:171], v[44:47]
	v_mfma_f32_16x16x32_bf16 v[40:43], v[136:139], v[168:171], v[40:43]
	s_barrier
	v_mfma_f32_16x16x32_bf16 v[28:31], v[128:131], v[188:191], v[28:31]
	v_mfma_f32_16x16x32_bf16 v[24:27], v[136:139], v[188:191], v[24:27]
	v_mfma_f32_16x16x32_bf16 v[12:15], v[128:131], v[196:199], v[12:15]
	v_mfma_f32_16x16x32_bf16 v[8:11], v[136:139], v[196:199], v[8:11]
	v_mfma_f32_16x16x32_bf16 v[60:63], v[132:135], v[164:167], v[60:63]
	v_mfma_f32_16x16x32_bf16 v[56:59], v[140:143], v[164:167], v[56:59]
	v_mfma_f32_16x16x32_bf16 v[44:47], v[132:135], v[172:175], v[44:47]
	v_mfma_f32_16x16x32_bf16 v[40:43], v[140:143], v[172:175], v[40:43]
	v_mfma_f32_16x16x32_bf16 v[28:31], v[132:135], v[192:195], v[28:31]
	v_mfma_f32_16x16x32_bf16 v[24:27], v[140:143], v[192:195], v[24:27]
	v_mfma_f32_16x16x32_bf16 v[12:15], v[132:135], v[210:213], v[12:15]
	v_mfma_f32_16x16x32_bf16 v[8:11], v[140:143], v[210:213], v[8:11]
	s_setprio 0
	s_setprio 1
	v_mfma_f32_16x16x32_bf16 v[52:55], v[144:147], v[160:163], v[52:55]
	v_mfma_f32_16x16x32_bf16 v[48:51], v[152:155], v[160:163], v[48:51]
	v_mfma_f32_16x16x32_bf16 v[36:39], v[144:147], v[168:171], v[36:39]
	v_mfma_f32_16x16x32_bf16 v[32:35], v[152:155], v[168:171], v[32:35]
	v_mfma_f32_16x16x32_bf16 v[20:23], v[144:147], v[188:191], v[20:23]
	v_mfma_f32_16x16x32_bf16 v[16:19], v[152:155], v[188:191], v[16:19]
	v_mfma_f32_16x16x32_bf16 v[4:7], v[144:147], v[196:199], v[4:7]
	v_mfma_f32_16x16x32_bf16 v[0:3], v[152:155], v[196:199], v[0:3]
	v_mfma_f32_16x16x32_bf16 v[52:55], v[148:151], v[164:167], v[52:55]
	v_mfma_f32_16x16x32_bf16 v[48:51], v[156:159], v[164:167], v[48:51]
	v_mfma_f32_16x16x32_bf16 v[36:39], v[148:151], v[172:175], v[36:39]
	v_mfma_f32_16x16x32_bf16 v[32:35], v[156:159], v[172:175], v[32:35]
	v_mfma_f32_16x16x32_bf16 v[20:23], v[148:151], v[192:195], v[20:23]
	v_mfma_f32_16x16x32_bf16 v[16:19], v[156:159], v[192:195], v[16:19]
	v_mfma_f32_16x16x32_bf16 v[4:7], v[148:151], v[210:213], v[4:7]
	v_mfma_f32_16x16x32_bf16 v[0:3], v[156:159], v[210:213], v[0:3]
	s_setprio 0
	s_barrier
	s_add_i32 s59, s59, 2
	s_add_u32 s30, s30, 0x100
	s_addc_u32 s31, s31, 0
	s_add_u32 s57, s57, 0x100
	s_addc_u32 s58, s58, 0
	s_and_b64 vcc, exec, s[16:17]
	s_cbranch_vccz .LBB0_698
	s_barrier
; __device__ __forceinline__ u32x4 pack8(const f32x4& a, const f32x4& b) { u32x4 w; w.x = cvt_pk_bf16(a[0], a[1]); w.y = cvt_pk_bf16(a[2], a[3]); w.z = cvt_pk_bf16(b[0], b[1]); w.w = cvt_pk_bf16(b[2], b[3]); return w; }
;     __device__ __forceinline__ void operator()(Acc& acc, const Unit& u, int wr, int wc, int fr, int fq) const {
;     ...
; #pragma unroll
;             for (int ai = 0; ai < 2; ++ai) {
;                 f32x4 rx[4][2][2];
; #pragma unroll
;                 for (int m = 0; m < 4; ++m)
; #pragma unroll
;                     for (int bj = 0; bj < 2; ++bj) { const float* p = basef + (size_t)(row0 + ai * HALF + m * 16) * D + col0 + bj * HALF; rx[m][bj][0] = *(const f32x4*)p; rx[m][bj][1] = *(const f32x4*)(p + 4); }
;                 __builtin_amdgcn_sched_barrier(0);
; #pragma unroll
;                 for (int m = 0; m < 4; ++m) { const int row = row0 + ai * HALF + m * 16; const size_t o = (size_t)row * D + col0; float ss = 0.f;
; #pragma unroll
;                     for (int bj = 0; bj < 2; ++bj) { const f32x4 h0 = rx[m][bj][0] + acc[ai][bj][m][0], h1 = rx[m][bj][1] + acc[ai][bj][m][1];
;                         *(u32x4*)(hb + o + bj * HALF) = pack8(h0, h1);
;                         ss += (h0[0] * h0[0] + h0[1] * h0[1]) + (h0[2] * h0[2] + h0[3] * h0[3]) + (h1[0] * h1[0] + h1[1] * h1[1]) + (h1[2] * h1[2] + h1[3] * h1[3]); }
;                     ss += __shfl_xor(ss, 16); ss += __shfl_xor(ss, 32);
;                     if (fq == 0) atomicAdd(sumsq + row, ss); }
.LBB0_698:
	s_lshl_b32 s7, s28, 8
	s_lshl_b32 s6, s6, 8
	v_mov_b32_e32 v128, v200
	v_mov_b32_e32 v207, v201
	s_add_i32 s7, s7, s47
	s_or_b32 s6, s6, s48
	s_nop 0
	v_add_u32_e32 v190, s7, v128
	v_lshl_add_u32 v188, v207, 3, s6
	v_ashrrev_i32_e32 v189, 31, v188
	v_ashrrev_i32_e32 v191, 31, v190
	v_lshl_add_u64 v[192:193], v[188:189], 2, s[64:65]
	v_lshlrev_b64 v[128:129], 12, v[190:191]
	v_add_u32_e32 v198, 16, v190
	v_lshl_add_u64 v[128:129], v[192:193], 0, v[128:129]
	v_ashrrev_i32_e32 v199, 31, v198
	v_mov_b64_e32 v[210:211], 0
	v_mov_b64_e32 v[212:213], 0
	v_mov_b64_e32 v[214:215], 0
	v_mov_b64_e32 v[216:217], 0
	v_mov_b64_e32 v[218:219], 0
	v_mov_b64_e32 v[220:221], 0
	v_mov_b64_e32 v[222:223], 0
	v_mov_b64_e32 v[224:225], 0
	v_lshlrev_b64 v[128:129], 12, v[198:199]
	v_add_u32_e32 v196, 32, v190
	v_lshl_add_u64 v[128:129], v[192:193], 0, v[128:129]
	v_ashrrev_i32_e32 v197, 31, v196
	v_mov_b64_e32 v[168:169], 0
	v_mov_b64_e32 v[170:171], 0
	v_mov_b64_e32 v[172:173], 0
	v_mov_b64_e32 v[174:175], 0
	v_mov_b64_e32 v[160:161], 0
	v_mov_b64_e32 v[162:163], 0
	v_mov_b64_e32 v[164:165], 0
	v_mov_b64_e32 v[166:167], 0
	v_lshlrev_b64 v[128:129], 12, v[196:197]
	v_add_u32_e32 v194, 48, v190
	v_lshl_add_u64 v[128:129], v[192:193], 0, v[128:129]
	v_ashrrev_i32_e32 v195, 31, v194
	v_mov_b64_e32 v[152:153], 0
	v_mov_b64_e32 v[154:155], 0
	v_mov_b64_e32 v[156:157], 0
	v_mov_b64_e32 v[158:159], 0
	v_mov_b64_e32 v[144:145], 0
	v_mov_b64_e32 v[146:147], 0
	v_mov_b64_e32 v[148:149], 0
	v_mov_b64_e32 v[150:151], 0
	v_lshlrev_b64 v[128:129], 12, v[194:195]
	v_lshl_add_u64 v[132:133], v[192:193], 0, v[128:129]
	v_mov_b64_e32 v[136:137], 0
	v_mov_b64_e32 v[138:139], 0
	v_mov_b64_e32 v[140:141], 0
	v_mov_b64_e32 v[142:143], 0
	v_mov_b64_e32 v[128:129], 0
	v_mov_b64_e32 v[130:131], 0
	s_nop 0
	v_mov_b64_e32 v[132:133], 0
	v_mov_b64_e32 v[134:135], 0
	v_cmp_eq_u32_e32 vcc, 0, v207
	v_pk_add_f32 v[126:127], v[126:127], v[216:217]
	v_pk_add_f32 v[214:215], v[124:125], v[214:215]
	v_pk_add_f32 v[118:119], v[118:119], v[224:225]
	v_pk_add_f32 v[116:117], v[116:117], v[222:223]
	v_pk_add_f32 v[212:213], v[122:123], v[212:213]
	v_pk_add_f32 v[120:121], v[120:121], v[210:211]
	v_cvt_pk_bf16_f32 v122, v214, v215
	v_cvt_pk_bf16_f32 v123, v126, v127
	v_mul_f32_e32 v207, v215, v215
	v_mul_f32_e32 v127, v127, v127
	v_pk_add_f32 v[210:211], v[112:113], v[218:219]
	v_mul_f32_e32 v112, v117, v117
	v_mul_f32_e32 v113, v119, v119
	v_cvt_pk_bf16_f32 v124, v120, v121
	v_fmac_f32_e32 v207, v214, v214
	v_fmac_f32_e32 v127, v126, v126
	v_mul_f32_e32 v121, v121, v121
	v_fmac_f32_e32 v112, v116, v116
	v_fmac_f32_e32 v113, v118, v118
	v_add_f32_e32 v126, v207, v127
	v_fmac_f32_e32 v121, v120, v120
	v_add_f32_e32 v112, v112, v113
	v_mul_f32_e32 v113, v211, v211
	v_add_f32_e32 v120, v126, v121
	v_pk_add_f32 v[126:127], v[114:115], v[220:221]
	v_fmac_f32_e32 v113, v210, v210
	v_mul_f32_e32 v121, v213, v213
	v_add_f32_e32 v112, v112, v113
	v_mul_f32_e32 v113, v127, v127
	v_fmac_f32_e32 v121, v212, v212
	v_fmac_f32_e32 v113, v126, v126
	v_add_f32_e32 v120, v121, v120
	v_add_f32_e32 v112, v113, v112
	v_and_b32_e32 v113, 64, v206
	v_add_f32_e32 v115, v120, v112
	v_xor_b32_e32 v112, 16, v206
	v_add_u32_e32 v121, 64, v113
	v_cmp_lt_i32_e64 s[6:7], v112, v121
	v_lshlrev_b64 v[226:227], 11, v[190:191]
	v_cvt_pk_bf16_f32 v125, v212, v213
	s_nop 0
	v_cndmask_b32_e64 v112, v206, v112, s[6:7]
	v_lshlrev_b32_e32 v120, 2, v112
	ds_bpermute_b32 v207, v120, v115
	v_lshl_add_u64 v[112:113], s[12:13], 0, v[226:227]
	v_lshl_add_u64 v[212:213], v[188:189], 1, v[112:113]
	v_xor_b32_e32 v113, 32, v206
	v_cmp_lt_i32_e64 s[6:7], v113, v121
	s_waitcnt lgkmcnt(0)
	v_add_f32_e32 v112, v115, v207
	global_store_dwordx4 v[212:213], v[122:125], off
	v_cndmask_b32_e64 v113, v206, v113, s[6:7]
	v_lshlrev_b32_e32 v121, 2, v113
	ds_bpermute_b32 v113, v121, v112
	v_cvt_pk_bf16_f32 v114, v116, v117
	v_cvt_pk_bf16_f32 v115, v118, v119
	v_cvt_pk_bf16_f32 v116, v210, v211
	v_cvt_pk_bf16_f32 v117, v126, v127
	global_store_dwordx4 v[212:213], v[114:117], off offset:256
	s_and_saveexec_b64 s[6:7], vcc
	s_cbranch_execz .LBB0_700
	v_lshl_add_u64 v[114:115], v[190:191], 2, s[0:1]
	s_waitcnt lgkmcnt(0)
	v_add_f32_e32 v112, v112, v113
	global_atomic_add_f32 v[114:115], v112, off

; __device__ __forceinline__ u32x4 pack8(const f32x4& a, const f32x4& b) { u32x4 w; w.x = cvt_pk_bf16(a[0], a[1]); w.y = cvt_pk_bf16(a[2], a[3]); w.z = cvt_pk_bf16(b[0], b[1]); w.w = cvt_pk_bf16(b[2], b[3]); return w; }
;     __device__ __forceinline__ void operator()(Acc& acc, const Unit& u, int wr, int wc, int fr, int fq) const {
;     ...
; #pragma unroll
;             for (int ai = 0; ai < 2; ++ai) {
;                 f32x4 rx[4][2][2];
; #pragma unroll
;                 for (int m = 0; m < 4; ++m)
; #pragma unroll
;                     for (int bj = 0; bj < 2; ++bj) { const float* p = basef + (size_t)(row0 + ai * HALF + m * 16) * D + col0 + bj * HALF; rx[m][bj][0] = *(const f32x4*)p; rx[m][bj][1] = *(const f32x4*)(p + 4); }
;                 __builtin_amdgcn_sched_barrier(0);
; #pragma unroll
;                 for (int m = 0; m < 4; ++m) { const int row = row0 + ai * HALF + m * 16; const size_t o = (size_t)row * D + col0; float ss = 0.f;
; #pragma unroll
;                     for (int bj = 0; bj < 2; ++bj) { const f32x4 h0 = rx[m][bj][0] + acc[ai][bj][m][0], h1 = rx[m][bj][1] + acc[ai][bj][m][1];
;                         *(u32x4*)(hb + o + bj * HALF) = pack8(h0, h1);
;                         ss += (h0[0] * h0[0] + h0[1] * h0[1]) + (h0[2] * h0[2] + h0[3] * h0[3]) + (h1[0] * h1[0] + h1[1] * h1[1]) + (h1[2] * h1[2] + h1[3] * h1[3]); }
;                     ss += __shfl_xor(ss, 16); ss += __shfl_xor(ss, 32);
;                     if (fq == 0) atomicAdd(sumsq + row, ss); }
.LBB0_706:
	s_or_b64 exec, exec, s[6:7]
	v_add_u32_e32 v118, 0x80, v190
	v_ashrrev_i32_e32 v119, 31, v118
	s_waitcnt lgkmcnt(0)
	v_lshlrev_b64 v[64:65], 12, v[118:119]
	v_add_u32_e32 v116, 0x90, v190
	v_lshl_add_u64 v[64:65], v[192:193], 0, v[64:65]
	v_ashrrev_i32_e32 v117, 31, v116
	s_waitcnt vmcnt(8)
	v_add_f32_e32 v8, v8, v240
	v_add_f32_e32 v9, v9, v241
	v_add_f32_e32 v10, v10, v242
	v_add_f32_e32 v11, v11, v243
	v_add_f32_e32 v4, v4, v232
	v_add_f32_e32 v5, v5, v233
	v_add_f32_e32 v6, v6, v234
	v_add_f32_e32 v7, v7, v235
	v_add_f32_e32 v0, v0, v236
	v_add_f32_e32 v1, v1, v237
	v_add_f32_e32 v2, v2, v238
	v_add_f32_e32 v3, v3, v239
	v_mov_b64_e32 v[122:123], 0
	v_mov_b64_e32 v[124:125], 0
	v_mov_b64_e32 v[126:127], 0
	v_mov_b64_e32 v[128:129], 0
	v_mov_b64_e32 v[130:131], 0
	v_mov_b64_e32 v[132:133], 0
	v_mov_b64_e32 v[134:135], 0
	v_mov_b64_e32 v[136:137], 0
	v_lshlrev_b64 v[64:65], 12, v[116:117]
	v_add_u32_e32 v114, 0xa0, v190
	v_lshl_add_u64 v[64:65], v[192:193], 0, v[64:65]
	v_ashrrev_i32_e32 v115, 31, v114
	v_mov_b64_e32 v[104:105], 0
	v_mov_b64_e32 v[106:107], 0
	v_mov_b64_e32 v[108:109], 0
	v_mov_b64_e32 v[110:111], 0
	v_mov_b64_e32 v[96:97], 0
	v_mov_b64_e32 v[98:99], 0
	v_mov_b64_e32 v[100:101], 0
	v_mov_b64_e32 v[102:103], 0
	v_lshlrev_b64 v[64:65], 12, v[114:115]
	v_add_u32_e32 v112, 0xb0, v190
	v_lshl_add_u64 v[64:65], v[192:193], 0, v[64:65]
	v_ashrrev_i32_e32 v113, 31, v112
	v_mov_b64_e32 v[88:89], 0
	v_mov_b64_e32 v[90:91], 0
	v_mov_b64_e32 v[92:93], 0
	v_mov_b64_e32 v[94:95], 0
	v_mov_b64_e32 v[80:81], 0
	v_mov_b64_e32 v[82:83], 0
	v_mov_b64_e32 v[84:85], 0
	v_mov_b64_e32 v[86:87], 0
	v_lshlrev_b64 v[64:65], 12, v[112:113]
	v_lshl_add_u64 v[68:69], v[192:193], 0, v[64:65]
	v_mov_b64_e32 v[72:73], 0
	v_mov_b64_e32 v[74:75], 0
	v_mov_b64_e32 v[76:77], 0
	v_mov_b64_e32 v[78:79], 0
	v_mov_b64_e32 v[64:65], 0
	v_mov_b64_e32 v[66:67], 0
	s_nop 0
	v_mov_b64_e32 v[68:69], 0
	v_mov_b64_e32 v[70:71], 0
	s_waitcnt vmcnt(14)
	v_pk_add_f32 v[60:61], v[60:61], v[126:127]
	v_pk_add_f32 v[62:63], v[62:63], v[128:129]
	v_pk_add_f32 v[122:123], v[56:57], v[122:123]
	v_cvt_pk_bf16_f32 v56, v60, v61
	v_mul_f32_e32 v61, v61, v61
	v_fmac_f32_e32 v61, v60, v60
	v_mul_f32_e32 v60, v63, v63
	v_fmac_f32_e32 v60, v62, v62
	v_add_f32_e32 v60, v61, v60
	v_mul_f32_e32 v61, v123, v123
	s_waitcnt vmcnt(12)
	v_pk_add_f32 v[54:55], v[54:55], v[136:137]
	v_pk_add_f32 v[52:53], v[52:53], v[134:135]
	v_pk_add_f32 v[124:125], v[58:59], v[124:125]
	v_cvt_pk_bf16_f32 v57, v62, v63
	v_fmac_f32_e32 v61, v122, v122
	v_pk_add_f32 v[62:63], v[48:49], v[130:131]
	v_mul_f32_e32 v48, v53, v53
	v_mul_f32_e32 v49, v55, v55
	v_add_f32_e32 v60, v60, v61
	v_mul_f32_e32 v61, v125, v125
	v_fmac_f32_e32 v48, v52, v52
	v_fmac_f32_e32 v49, v54, v54
	v_fmac_f32_e32 v61, v124, v124
	v_add_f32_e32 v48, v48, v49
	v_mul_f32_e32 v49, v63, v63
	v_cvt_pk_bf16_f32 v58, v122, v123
	v_add_f32_e32 v122, v61, v60
	v_pk_add_f32 v[60:61], v[50:51], v[132:133]
	v_fmac_f32_e32 v49, v62, v62
	v_add_f32_e32 v48, v48, v49
	v_mul_f32_e32 v49, v61, v61
	v_fmac_f32_e32 v49, v60, v60
	v_add_f32_e32 v48, v49, v48
	v_add_f32_e32 v51, v122, v48
	v_cvt_pk_bf16_f32 v59, v124, v125
	ds_bpermute_b32 v124, v120, v51
	v_lshlrev_b64 v[138:139], 11, v[118:119]
	v_lshl_add_u64 v[48:49], s[12:13], 0, v[138:139]
	v_lshl_add_u64 v[122:123], v[188:189], 1, v[48:49]
	global_store_dwordx4 v[122:123], v[56:59], off
	s_waitcnt lgkmcnt(0)
	v_add_f32_e32 v48, v51, v124
	ds_bpermute_b32 v49, v121, v48
	v_cvt_pk_bf16_f32 v50, v52, v53
	v_cvt_pk_bf16_f32 v51, v54, v55
	v_cvt_pk_bf16_f32 v52, v62, v63
	v_cvt_pk_bf16_f32 v53, v60, v61
	global_store_dwordx4 v[122:123], v[50:53], off offset:256
	s_and_saveexec_b64 s[6:7], vcc
	s_cbranch_execz .LBB0_708
	v_lshl_add_u64 v[50:51], v[118:119], 2, s[0:1]
	s_waitcnt lgkmcnt(0)
	v_add_f32_e32 v48, v48, v49
	global_atomic_add_f32 v[50:51], v48, off
